# v16 + GEMM K-loop back-edge rotation: counter updates and next-iteration scalar preamble before the closing barrier (exit path has its own barrier copy)
# baseline (speedup 1.0000x reference)
.LBB0_393:
	s_ashr_i32 s19, s18, 31
	s_lshl_b64 s[0:1], s[18:19], 20
	s_add_u32 s20, s42, s0
	s_addc_u32 s21, s43, s1
	s_and_b64 s[0:1], s[4:5], exec
	s_cselect_b32 s7, s21, s25
	s_cselect_b32 s19, s20, s24
	s_ashr_i32 s17, s16, 31
	s_lshl_b64 s[0:1], s[16:17], 20
	s_add_u32 s22, s30, s0
	s_addc_u32 s23, s31, s1
	s_and_b64 s[0:1], s[4:5], exec
	s_cselect_b32 s17, s23, s27
	s_cselect_b32 s49, s22, s26
	s_add_u32 s24, s24, 0x80080
	s_addc_u32 s25, s25, 0
	s_add_u32 s58, s26, 0x100
	v_mov_b32_e32 v2, 0
	s_addc_u32 s59, s27, 0
	s_mov_b32 s60, -2
	v_mov_b32_e32 v3, v2
	s_waitcnt lgkmcnt(0)
	v_mov_b32_e32 v4, v2
	v_mov_b32_e32 v5, v2
	v_mov_b32_e32 v6, v2
	v_mov_b32_e32 v7, v2
	v_mov_b32_e32 v8, v2
	v_mov_b32_e32 v9, v2
	v_mov_b32_e32 v18, v2
	v_mov_b32_e32 v19, v2
	v_mov_b32_e32 v20, v2
	v_mov_b32_e32 v21, v2
	v_mov_b32_e32 v22, v2
	v_mov_b32_e32 v23, v2
	v_mov_b32_e32 v24, v2
	v_mov_b32_e32 v25, v2
	s_waitcnt vmcnt(0)
	v_mov_b32_e32 v34, v2
	v_mov_b32_e32 v35, v2
	v_mov_b32_e32 v36, v2
	v_mov_b32_e32 v37, v2
	v_mov_b32_e32 v38, v2
	v_mov_b32_e32 v39, v2
	v_mov_b32_e32 v40, v2
	v_mov_b32_e32 v41, v2
	v_mov_b32_e32 v50, v2
	v_mov_b32_e32 v51, v2
	v_mov_b32_e32 v52, v2
	v_mov_b32_e32 v53, v2
	v_mov_b32_e32 v54, v2
	v_mov_b32_e32 v55, v2
	v_mov_b32_e32 v56, v2
	v_mov_b32_e32 v57, v2
	v_mov_b32_e32 v10, v2
	v_mov_b32_e32 v11, v2
	v_mov_b32_e32 v12, v2
	v_mov_b32_e32 v13, v2
	v_mov_b32_e32 v14, v2
	v_mov_b32_e32 v15, v2
	v_mov_b32_e32 v16, v2
	v_mov_b32_e32 v17, v2
	v_mov_b32_e32 v26, v2
	v_mov_b32_e32 v27, v2
	v_mov_b32_e32 v28, v2
	v_mov_b32_e32 v29, v2
	v_mov_b32_e32 v30, v2
	v_mov_b32_e32 v31, v2
	v_mov_b32_e32 v32, v2
	v_mov_b32_e32 v33, v2
	v_mov_b32_e32 v42, v2
	v_mov_b32_e32 v43, v2
	v_mov_b32_e32 v44, v2
	v_mov_b32_e32 v45, v2
	v_mov_b32_e32 v46, v2
	v_mov_b32_e32 v47, v2
	v_mov_b32_e32 v48, v2
	v_mov_b32_e32 v49, v2
	v_mov_b32_e32 v58, v2
	v_mov_b32_e32 v59, v2
	v_mov_b32_e32 v60, v2
	v_mov_b32_e32 v61, v2
	v_mov_b32_e32 v62, v2
	v_mov_b32_e32 v63, v2
	v_mov_b32_e32 v64, v2
	v_mov_b32_e32 v65, v2
	v_mov_b32_e32 v66, v2
	v_mov_b32_e32 v67, v2
	v_mov_b32_e32 v68, v2
	v_mov_b32_e32 v69, v2
	v_mov_b32_e32 v70, v2
	v_mov_b32_e32 v71, v2
	v_mov_b32_e32 v72, v2
	v_mov_b32_e32 v73, v2
	v_mov_b32_e32 v82, v2
	v_mov_b32_e32 v83, v2
	v_mov_b32_e32 v84, v2
	v_mov_b32_e32 v85, v2
	v_mov_b32_e32 v86, v2
	v_mov_b32_e32 v87, v2
	v_mov_b32_e32 v88, v2
	v_mov_b32_e32 v89, v2
	v_mov_b32_e32 v98, v2
	v_mov_b32_e32 v99, v2
	v_mov_b32_e32 v100, v2
	v_mov_b32_e32 v101, v2
	v_mov_b32_e32 v102, v2
	v_mov_b32_e32 v103, v2
	v_mov_b32_e32 v104, v2
	v_mov_b32_e32 v105, v2
	v_mov_b32_e32 v114, v2
	v_mov_b32_e32 v115, v2
	v_mov_b32_e32 v116, v2
	v_mov_b32_e32 v117, v2
	v_mov_b32_e32 v118, v2
	v_mov_b32_e32 v119, v2
	v_mov_b32_e32 v120, v2
	v_mov_b32_e32 v121, v2
	v_mov_b32_e32 v74, v2
	v_mov_b32_e32 v75, v2
	v_mov_b32_e32 v76, v2
	v_mov_b32_e32 v77, v2
	v_mov_b32_e32 v78, v2
	v_mov_b32_e32 v79, v2
	v_mov_b32_e32 v80, v2
	v_mov_b32_e32 v81, v2
	v_mov_b32_e32 v90, v2
	v_mov_b32_e32 v91, v2
	v_mov_b32_e32 v92, v2
	v_mov_b32_e32 v93, v2
	v_mov_b32_e32 v94, v2
	v_mov_b32_e32 v95, v2
	v_mov_b32_e32 v96, v2
	v_mov_b32_e32 v97, v2
	v_mov_b32_e32 v106, v2
	v_mov_b32_e32 v107, v2
	v_mov_b32_e32 v108, v2
	v_mov_b32_e32 v109, v2
	v_mov_b32_e32 v110, v2
	v_mov_b32_e32 v111, v2
	v_mov_b32_e32 v112, v2
	v_mov_b32_e32 v113, v2
	v_mov_b32_e32 v122, v2
	v_mov_b32_e32 v123, v2
	v_mov_b32_e32 v124, v2
	v_mov_b32_e32 v125, v2
	v_mov_b32_e32 v126, v2
	v_mov_b32_e32 v127, v2
	v_mov_b32_e32 v128, v2
	v_mov_b32_e32 v129, v2
	s_add_u32 s0, s24, 0xfff80080
	s_addc_u32 s1, s25, -1
	s_add_i32 s33, 0, 0x10000
	s_cmp_eq_u32 s60, 28
	s_cselect_b32 s29, s7, s1
	s_cselect_b32 s28, s19, s0
	s_cselect_b32 s27, s17, s59
	s_cselect_b32 s26, s49, s58
	s_add_i32 s55, 0, 0x14000
	v_add_u32_e32 v158, s33, v151
	v_add_u32_e32 v174, s55, v151
.LBB0_394:
	ds_read_b128 v[142:145], v158
	ds_read_b128 v[146:149], v158 offset:1024
	ds_read_b128 v[154:157], v158 offset:2048
	ds_read_b128 v[158:161], v158 offset:3072
	ds_read_b128 v[162:165], v174
	ds_read_b128 v[166:169], v174 offset:1024
	ds_read_b128 v[170:173], v174 offset:2048
	ds_read_b128 v[174:177], v174 offset:3072
	v_lshl_add_u64 v[204:205], s[24:25], 0, v[138:139]
	s_add_i32 m0, s9, 0xc000
	ds_read_b128 v[178:181], v153
	ds_read_b128 v[182:185], v153 offset:1024
	ds_read_b128 v[186:189], v153 offset:2048
	ds_read_b128 v[190:193], v153 offset:3072
	ds_read_b128 v[194:197], v153 offset:4096
	ds_read_b128 v[198:201], v153 offset:5120
	ds_read_b128 v[208:211], v153 offset:6144
	ds_read_b128 v[212:215], v153 offset:7168
	global_load_lds_dwordx4 v[204:205], off
	v_lshl_add_u64 v[204:205], s[24:25], 0, v[140:141]
	s_add_i32 m0, s9, 0xe000
	s_nop 0
	global_load_lds_dwordx4 v[204:205], off
	s_waitcnt vmcnt(8)
	s_waitcnt lgkmcnt(0)
	s_barrier
	s_setprio 1
	s_waitcnt lgkmcnt(0)
	v_mfma_f32_16x16x32_bf16 v[126:129], v[142:145], v[178:181], v[126:129]
	v_mfma_f32_16x16x32_bf16 v[122:125], v[154:157], v[178:181], v[122:125]
	v_mfma_f32_16x16x32_bf16 v[110:113], v[142:145], v[186:189], v[110:113]
	v_mfma_f32_16x16x32_bf16 v[106:109], v[154:157], v[186:189], v[106:109]
	v_mfma_f32_16x16x32_bf16 v[94:97], v[142:145], v[194:197], v[94:97]
	v_mfma_f32_16x16x32_bf16 v[90:93], v[154:157], v[194:197], v[90:93]
	v_mfma_f32_16x16x32_bf16 v[78:81], v[142:145], v[208:211], v[78:81]
	v_mfma_f32_16x16x32_bf16 v[74:77], v[154:157], v[208:211], v[74:77]
	v_mfma_f32_16x16x32_bf16 v[126:129], v[146:149], v[182:185], v[126:129]
	v_mfma_f32_16x16x32_bf16 v[122:125], v[158:161], v[182:185], v[122:125]
	v_mfma_f32_16x16x32_bf16 v[110:113], v[146:149], v[190:193], v[110:113]
	v_mfma_f32_16x16x32_bf16 v[106:109], v[158:161], v[190:193], v[106:109]
	v_mfma_f32_16x16x32_bf16 v[94:97], v[146:149], v[198:201], v[94:97]
	v_mfma_f32_16x16x32_bf16 v[90:93], v[158:161], v[198:201], v[90:93]
	v_mfma_f32_16x16x32_bf16 v[78:81], v[146:149], v[212:215], v[78:81]
	v_mfma_f32_16x16x32_bf16 v[74:77], v[158:161], v[212:215], v[74:77]
	s_setprio 0
	s_setprio 1
	v_mfma_f32_16x16x32_bf16 v[118:121], v[162:165], v[178:181], v[118:121]
	v_mfma_f32_16x16x32_bf16 v[114:117], v[170:173], v[178:181], v[114:117]
	v_mfma_f32_16x16x32_bf16 v[102:105], v[162:165], v[186:189], v[102:105]
	v_mfma_f32_16x16x32_bf16 v[98:101], v[170:173], v[186:189], v[98:101]
	v_mfma_f32_16x16x32_bf16 v[86:89], v[162:165], v[194:197], v[86:89]
	v_mfma_f32_16x16x32_bf16 v[82:85], v[170:173], v[194:197], v[82:85]
	v_mfma_f32_16x16x32_bf16 v[70:73], v[162:165], v[208:211], v[70:73]
	v_mfma_f32_16x16x32_bf16 v[66:69], v[170:173], v[208:211], v[66:69]
	v_mfma_f32_16x16x32_bf16 v[118:121], v[166:169], v[182:185], v[118:121]
	v_mfma_f32_16x16x32_bf16 v[114:117], v[174:177], v[182:185], v[114:117]
	v_mfma_f32_16x16x32_bf16 v[102:105], v[166:169], v[190:193], v[102:105]
	v_mfma_f32_16x16x32_bf16 v[98:101], v[174:177], v[190:193], v[98:101]
	v_mfma_f32_16x16x32_bf16 v[86:89], v[166:169], v[198:201], v[86:89]
	v_mfma_f32_16x16x32_bf16 v[82:85], v[174:177], v[198:201], v[82:85]
	v_mfma_f32_16x16x32_bf16 v[70:73], v[166:169], v[212:215], v[70:73]
	v_mfma_f32_16x16x32_bf16 v[66:69], v[174:177], v[212:215], v[66:69]
	s_setprio 0
	s_barrier
	s_add_i32 s0, s33, s34
	v_lshl_add_u64 v[204:205], s[26:27], 0, v[132:133]
	s_mov_b32 m0, s0
	ds_read_b128 v[178:181], v153 offset:16384
	ds_read_b128 v[182:185], v153 offset:17408
	ds_read_b128 v[186:189], v153 offset:18432
	ds_read_b128 v[190:193], v153 offset:19456
	ds_read_b128 v[194:197], v153 offset:20480
	ds_read_b128 v[198:201], v153 offset:21504
	ds_read_b128 v[208:211], v153 offset:22528
	ds_read_b128 v[212:215], v153 offset:23552
	global_load_lds_dwordx4 v[204:205], off
	s_add_i32 m0, s0, 0x2000
	s_add_u32 s0, s26, 0x80000
	v_lshl_add_u64 v[216:217], s[26:27], 0, v[136:137]
	s_addc_u32 s1, s27, 0
	s_add_i32 s33, s55, s34
	global_load_lds_dwordx4 v[216:217], off
	v_lshl_add_u64 v[218:219], s[0:1], 0, v[132:133]
	s_mov_b32 m0, s33
	v_lshl_add_u64 v[220:221], s[28:29], 0, v[134:135]
	global_load_lds_dwordx4 v[218:219], off
	v_lshl_add_u64 v[218:219], s[0:1], 0, v[136:137]
	s_add_i32 m0, s33, 0x2000
	s_nop 0
	global_load_lds_dwordx4 v[218:219], off
	v_lshl_add_u64 v[218:219], s[28:29], 0, v[130:131]
	s_mov_b32 m0, s9
	s_nop 0
	global_load_lds_dwordx4 v[218:219], off
	s_mov_b32 m0, s35
	s_nop 0
	global_load_lds_dwordx4 v[220:221], off
	s_waitcnt vmcnt(8)
	s_waitcnt lgkmcnt(0)
	s_barrier
	s_setprio 1
	s_waitcnt lgkmcnt(0)
	v_mfma_f32_16x16x32_bf16 v[62:65], v[142:145], v[178:181], v[62:65]
	v_mfma_f32_16x16x32_bf16 v[58:61], v[154:157], v[178:181], v[58:61]
	v_mfma_f32_16x16x32_bf16 v[46:49], v[142:145], v[186:189], v[46:49]
	v_mfma_f32_16x16x32_bf16 v[42:45], v[154:157], v[186:189], v[42:45]
	v_mfma_f32_16x16x32_bf16 v[30:33], v[142:145], v[194:197], v[30:33]
	v_mfma_f32_16x16x32_bf16 v[26:29], v[154:157], v[194:197], v[26:29]
	v_mfma_f32_16x16x32_bf16 v[14:17], v[142:145], v[208:211], v[14:17]
	v_mfma_f32_16x16x32_bf16 v[10:13], v[154:157], v[208:211], v[10:13]
	v_mfma_f32_16x16x32_bf16 v[62:65], v[146:149], v[182:185], v[62:65]
	v_mfma_f32_16x16x32_bf16 v[58:61], v[158:161], v[182:185], v[58:61]
	v_mfma_f32_16x16x32_bf16 v[46:49], v[146:149], v[190:193], v[46:49]
	v_mfma_f32_16x16x32_bf16 v[42:45], v[158:161], v[190:193], v[42:45]
	v_mfma_f32_16x16x32_bf16 v[30:33], v[146:149], v[198:201], v[30:33]
	v_mfma_f32_16x16x32_bf16 v[26:29], v[158:161], v[198:201], v[26:29]
	v_mfma_f32_16x16x32_bf16 v[14:17], v[146:149], v[212:215], v[14:17]
	v_mfma_f32_16x16x32_bf16 v[10:13], v[158:161], v[212:215], v[10:13]
	s_setprio 0
	s_setprio 1
	v_mfma_f32_16x16x32_bf16 v[54:57], v[162:165], v[178:181], v[54:57]
	v_mfma_f32_16x16x32_bf16 v[50:53], v[170:173], v[178:181], v[50:53]
	v_mfma_f32_16x16x32_bf16 v[38:41], v[162:165], v[186:189], v[38:41]
	v_mfma_f32_16x16x32_bf16 v[34:37], v[170:173], v[186:189], v[34:37]
	v_mfma_f32_16x16x32_bf16 v[22:25], v[162:165], v[194:197], v[22:25]
	v_mfma_f32_16x16x32_bf16 v[18:21], v[170:173], v[194:197], v[18:21]
	v_mfma_f32_16x16x32_bf16 v[6:9], v[162:165], v[208:211], v[6:9]
	v_mfma_f32_16x16x32_bf16 v[2:5], v[170:173], v[208:211], v[2:5]
	v_mfma_f32_16x16x32_bf16 v[54:57], v[166:169], v[182:185], v[54:57]
	v_mfma_f32_16x16x32_bf16 v[50:53], v[174:177], v[182:185], v[50:53]
	v_mfma_f32_16x16x32_bf16 v[38:41], v[166:169], v[190:193], v[38:41]
	v_mfma_f32_16x16x32_bf16 v[34:37], v[174:177], v[190:193], v[34:37]
	v_mfma_f32_16x16x32_bf16 v[22:25], v[166:169], v[198:201], v[22:25]
	v_mfma_f32_16x16x32_bf16 v[18:21], v[174:177], v[198:201], v[18:21]
	v_mfma_f32_16x16x32_bf16 v[6:9], v[166:169], v[212:215], v[6:9]
	v_mfma_f32_16x16x32_bf16 v[2:5], v[174:177], v[212:215], v[2:5]
	s_setprio 0
	s_barrier
	s_add_i32 s33, 0, 0x18000
	s_add_i32 s55, 0, 0x1c000
	v_add_u32_e32 v158, s33, v151
	v_add_u32_e32 v174, s55, v151
	ds_read_b128 v[142:145], v158
	ds_read_b128 v[146:149], v158 offset:1024
	ds_read_b128 v[154:157], v158 offset:2048
	ds_read_b128 v[158:161], v158 offset:3072
	ds_read_b128 v[162:165], v174
	ds_read_b128 v[166:169], v174 offset:1024
	ds_read_b128 v[170:173], v174 offset:2048
	ds_read_b128 v[174:177], v174 offset:3072
	s_add_u32 s0, s28, 0x80000
	s_addc_u32 s1, s29, 0
	s_mov_b32 m0, s36
	v_lshl_add_u64 v[222:223], s[0:1], 0, v[130:131]
	ds_read_b128 v[178:181], v153 offset:32768
	ds_read_b128 v[182:185], v153 offset:33792
	ds_read_b128 v[186:189], v153 offset:34816
	ds_read_b128 v[190:193], v153 offset:35840
	ds_read_b128 v[194:197], v153 offset:36864
	ds_read_b128 v[198:201], v153 offset:37888
	ds_read_b128 v[208:211], v153 offset:38912
	ds_read_b128 v[212:215], v153 offset:39936
	global_load_lds_dwordx4 v[222:223], off
	v_lshl_add_u64 v[222:223], s[0:1], 0, v[134:135]
	s_mov_b32 m0, s37
	s_nop 0
	global_load_lds_dwordx4 v[222:223], off
	s_waitcnt vmcnt(8)
	s_waitcnt lgkmcnt(0)
	s_barrier
	s_setprio 1
	s_waitcnt lgkmcnt(0)
	v_mfma_f32_16x16x32_bf16 v[126:129], v[142:145], v[178:181], v[126:129]
	v_mfma_f32_16x16x32_bf16 v[122:125], v[154:157], v[178:181], v[122:125]
	v_mfma_f32_16x16x32_bf16 v[110:113], v[142:145], v[186:189], v[110:113]
	v_mfma_f32_16x16x32_bf16 v[106:109], v[154:157], v[186:189], v[106:109]
	v_mfma_f32_16x16x32_bf16 v[94:97], v[142:145], v[194:197], v[94:97]
	v_mfma_f32_16x16x32_bf16 v[90:93], v[154:157], v[194:197], v[90:93]
	v_mfma_f32_16x16x32_bf16 v[78:81], v[142:145], v[208:211], v[78:81]
	v_mfma_f32_16x16x32_bf16 v[74:77], v[154:157], v[208:211], v[74:77]
	v_mfma_f32_16x16x32_bf16 v[126:129], v[146:149], v[182:185], v[126:129]
	v_mfma_f32_16x16x32_bf16 v[122:125], v[158:161], v[182:185], v[122:125]
	v_mfma_f32_16x16x32_bf16 v[110:113], v[146:149], v[190:193], v[110:113]
	v_mfma_f32_16x16x32_bf16 v[106:109], v[158:161], v[190:193], v[106:109]
	v_mfma_f32_16x16x32_bf16 v[94:97], v[146:149], v[198:201], v[94:97]
	v_mfma_f32_16x16x32_bf16 v[90:93], v[158:161], v[198:201], v[90:93]
	v_mfma_f32_16x16x32_bf16 v[78:81], v[146:149], v[212:215], v[78:81]
	v_mfma_f32_16x16x32_bf16 v[74:77], v[158:161], v[212:215], v[74:77]
	s_setprio 0
	s_setprio 1
	v_mfma_f32_16x16x32_bf16 v[118:121], v[162:165], v[178:181], v[118:121]
	v_mfma_f32_16x16x32_bf16 v[114:117], v[170:173], v[178:181], v[114:117]
	v_mfma_f32_16x16x32_bf16 v[102:105], v[162:165], v[186:189], v[102:105]
	v_mfma_f32_16x16x32_bf16 v[98:101], v[170:173], v[186:189], v[98:101]
	v_mfma_f32_16x16x32_bf16 v[86:89], v[162:165], v[194:197], v[86:89]
	v_mfma_f32_16x16x32_bf16 v[82:85], v[170:173], v[194:197], v[82:85]
	v_mfma_f32_16x16x32_bf16 v[70:73], v[162:165], v[208:211], v[70:73]
	v_mfma_f32_16x16x32_bf16 v[66:69], v[170:173], v[208:211], v[66:69]
	v_mfma_f32_16x16x32_bf16 v[118:121], v[166:169], v[182:185], v[118:121]
	v_mfma_f32_16x16x32_bf16 v[114:117], v[174:177], v[182:185], v[114:117]
	v_mfma_f32_16x16x32_bf16 v[102:105], v[166:169], v[190:193], v[102:105]
	v_mfma_f32_16x16x32_bf16 v[98:101], v[174:177], v[190:193], v[98:101]
	v_mfma_f32_16x16x32_bf16 v[86:89], v[166:169], v[198:201], v[86:89]
	v_mfma_f32_16x16x32_bf16 v[82:85], v[174:177], v[198:201], v[82:85]
	v_mfma_f32_16x16x32_bf16 v[70:73], v[166:169], v[212:215], v[70:73]
	v_mfma_f32_16x16x32_bf16 v[66:69], v[174:177], v[212:215], v[66:69]
	s_setprio 0
	s_barrier
	s_add_i32 s0, s33, s34
	v_lshl_add_u64 v[204:205], v[204:205], 0, s[80:81]
	s_mov_b32 m0, s0
	ds_read_b128 v[178:181], v153 offset:49152
	ds_read_b128 v[182:185], v153 offset:50176
	ds_read_b128 v[186:189], v153 offset:51200
	ds_read_b128 v[190:193], v153 offset:52224
	ds_read_b128 v[194:197], v153 offset:53248
	ds_read_b128 v[198:201], v153 offset:54272
	ds_read_b128 v[208:211], v153 offset:55296
	ds_read_b128 v[212:215], v153 offset:56320
	global_load_lds_dwordx4 v[204:205], off
	s_add_i32 m0, s0, 0x2000
	s_add_u32 s0, s26, 0x80080
	v_lshl_add_u64 v[204:205], v[216:217], 0, s[80:81]
	s_addc_u32 s1, s27, 0
	s_add_i32 s26, s55, s34
	global_load_lds_dwordx4 v[204:205], off
	v_lshl_add_u64 v[204:205], s[0:1], 0, v[132:133]
	s_mov_b32 m0, s26
	s_nop 0
	global_load_lds_dwordx4 v[204:205], off
	v_lshl_add_u64 v[204:205], s[0:1], 0, v[136:137]
	s_add_i32 m0, s26, 0x2000
	s_nop 0
	global_load_lds_dwordx4 v[204:205], off
	v_lshl_add_u64 v[204:205], v[218:219], 0, s[80:81]
	s_mov_b32 m0, s39
	s_nop 0
	global_load_lds_dwordx4 v[204:205], off
	v_lshl_add_u64 v[204:205], v[220:221], 0, s[80:81]
	s_mov_b32 m0, s40
	s_nop 0
	global_load_lds_dwordx4 v[204:205], off
	s_waitcnt vmcnt(8)
	s_waitcnt lgkmcnt(0)
	s_barrier
	s_setprio 1
	s_waitcnt lgkmcnt(0)
	v_mfma_f32_16x16x32_bf16 v[62:65], v[142:145], v[178:181], v[62:65]
	v_mfma_f32_16x16x32_bf16 v[58:61], v[154:157], v[178:181], v[58:61]
	v_mfma_f32_16x16x32_bf16 v[46:49], v[142:145], v[186:189], v[46:49]
	v_mfma_f32_16x16x32_bf16 v[42:45], v[154:157], v[186:189], v[42:45]
	v_mfma_f32_16x16x32_bf16 v[30:33], v[142:145], v[194:197], v[30:33]
	v_mfma_f32_16x16x32_bf16 v[26:29], v[154:157], v[194:197], v[26:29]
	v_mfma_f32_16x16x32_bf16 v[14:17], v[142:145], v[208:211], v[14:17]
	v_mfma_f32_16x16x32_bf16 v[10:13], v[154:157], v[208:211], v[10:13]
	v_mfma_f32_16x16x32_bf16 v[62:65], v[146:149], v[182:185], v[62:65]
	v_mfma_f32_16x16x32_bf16 v[58:61], v[158:161], v[182:185], v[58:61]
	v_mfma_f32_16x16x32_bf16 v[46:49], v[146:149], v[190:193], v[46:49]
	v_mfma_f32_16x16x32_bf16 v[42:45], v[158:161], v[190:193], v[42:45]
	v_mfma_f32_16x16x32_bf16 v[30:33], v[146:149], v[198:201], v[30:33]
	v_mfma_f32_16x16x32_bf16 v[26:29], v[158:161], v[198:201], v[26:29]
	v_mfma_f32_16x16x32_bf16 v[14:17], v[146:149], v[212:215], v[14:17]
	v_mfma_f32_16x16x32_bf16 v[10:13], v[158:161], v[212:215], v[10:13]
	s_setprio 0
	s_setprio 1
	v_mfma_f32_16x16x32_bf16 v[54:57], v[162:165], v[178:181], v[54:57]
	v_mfma_f32_16x16x32_bf16 v[50:53], v[170:173], v[178:181], v[50:53]
	v_mfma_f32_16x16x32_bf16 v[38:41], v[162:165], v[186:189], v[38:41]
	v_mfma_f32_16x16x32_bf16 v[34:37], v[170:173], v[186:189], v[34:37]
	v_mfma_f32_16x16x32_bf16 v[22:25], v[162:165], v[194:197], v[22:25]
	v_mfma_f32_16x16x32_bf16 v[18:21], v[170:173], v[194:197], v[18:21]
	v_mfma_f32_16x16x32_bf16 v[6:9], v[162:165], v[208:211], v[6:9]
	v_mfma_f32_16x16x32_bf16 v[2:5], v[170:173], v[208:211], v[2:5]
	v_mfma_f32_16x16x32_bf16 v[54:57], v[166:169], v[182:185], v[54:57]
	v_mfma_f32_16x16x32_bf16 v[50:53], v[174:177], v[182:185], v[50:53]
	v_mfma_f32_16x16x32_bf16 v[38:41], v[166:169], v[190:193], v[38:41]
	v_mfma_f32_16x16x32_bf16 v[34:37], v[174:177], v[190:193], v[34:37]
	v_mfma_f32_16x16x32_bf16 v[22:25], v[166:169], v[198:201], v[22:25]
	v_mfma_f32_16x16x32_bf16 v[18:21], v[174:177], v[198:201], v[18:21]
	v_mfma_f32_16x16x32_bf16 v[6:9], v[166:169], v[212:215], v[6:9]
	v_mfma_f32_16x16x32_bf16 v[2:5], v[174:177], v[212:215], v[2:5]
	s_setprio 0
	s_add_i32 s60, s60, 2
	s_add_u32 s24, s24, 0x100
	s_addc_u32 s25, s25, 0
	s_add_u32 s58, s58, 0x100
	s_addc_u32 s59, s59, 0
	s_cmp_gt_u32 s60, 29
	s_cbranch_scc1 .Lrot_exit_0
	s_add_u32 s0, s24, 0xfff80080
	s_addc_u32 s1, s25, -1
	s_add_i32 s33, 0, 0x10000
	s_cmp_eq_u32 s60, 28
	s_cselect_b32 s29, s7, s1
	s_cselect_b32 s28, s19, s0
	s_cselect_b32 s27, s17, s59
	s_cselect_b32 s26, s49, s58
	s_add_i32 s55, 0, 0x14000
	v_add_u32_e32 v158, s33, v151
	v_add_u32_e32 v174, s55, v151
	s_barrier
	s_branch .LBB0_394
.Lrot_exit_0:
	s_barrier
	s_and_b64 vcc, exec, s[14:15]
	s_cbranch_vccz .LBB0_397
	s_barrier

.LBB0_691:
	s_ashr_i32 s11, s10, 31
	s_lshl_b64 s[0:1], s[10:11], 21
	s_add_u32 s14, s78, s0
	s_addc_u32 s15, s79, s1
	s_and_b64 s[0:1], s[2:3], exec
	s_cselect_b32 s11, s15, s19
	s_cselect_b32 s49, s14, s18
	s_ashr_i32 s9, s8, 31
	s_lshl_b64 s[0:1], s[8:9], 21
	s_add_u32 s16, s24, s0
	s_addc_u32 s17, s25, s1
	s_and_b64 s[0:1], s[2:3], exec
	s_cselect_b32 s9, s17, s21
	s_cselect_b32 s58, s16, s20
	s_add_u32 s18, s18, 0x100080
	s_addc_u32 s19, s19, 0
	s_add_u32 s59, s20, 0x100
	v_mov_b32_e32 v2, 0
	s_addc_u32 s60, s21, 0
	s_mov_b32 s61, -2
	v_mov_b32_e32 v3, v2
	v_mov_b32_e32 v4, v2
	v_mov_b32_e32 v5, v2
	v_mov_b32_e32 v6, v2
	v_mov_b32_e32 v7, v2
	v_mov_b32_e32 v8, v2
	v_mov_b32_e32 v9, v2
	v_mov_b32_e32 v18, v2
	v_mov_b32_e32 v19, v2
	v_mov_b32_e32 v20, v2
	v_mov_b32_e32 v21, v2
	v_mov_b32_e32 v22, v2
	v_mov_b32_e32 v23, v2
	v_mov_b32_e32 v24, v2
	v_mov_b32_e32 v25, v2
	v_mov_b32_e32 v34, v2
	v_mov_b32_e32 v35, v2
	v_mov_b32_e32 v36, v2
	v_mov_b32_e32 v37, v2
	v_mov_b32_e32 v38, v2
	v_mov_b32_e32 v39, v2
	v_mov_b32_e32 v40, v2
	v_mov_b32_e32 v41, v2
	v_mov_b32_e32 v50, v2
	v_mov_b32_e32 v51, v2
	v_mov_b32_e32 v52, v2
	v_mov_b32_e32 v53, v2
	v_mov_b32_e32 v54, v2
	v_mov_b32_e32 v55, v2
	v_mov_b32_e32 v56, v2
	v_mov_b32_e32 v57, v2
	v_mov_b32_e32 v10, v2
	v_mov_b32_e32 v11, v2
	v_mov_b32_e32 v12, v2
	v_mov_b32_e32 v13, v2
	v_mov_b32_e32 v14, v2
	v_mov_b32_e32 v15, v2
	v_mov_b32_e32 v16, v2
	v_mov_b32_e32 v17, v2
	v_mov_b32_e32 v26, v2
	v_mov_b32_e32 v27, v2
	v_mov_b32_e32 v28, v2
	v_mov_b32_e32 v29, v2
	v_mov_b32_e32 v30, v2
	v_mov_b32_e32 v31, v2
	v_mov_b32_e32 v32, v2
	v_mov_b32_e32 v33, v2
	v_mov_b32_e32 v42, v2
	v_mov_b32_e32 v43, v2
	v_mov_b32_e32 v44, v2
	v_mov_b32_e32 v45, v2
	v_mov_b32_e32 v46, v2
	v_mov_b32_e32 v47, v2
	v_mov_b32_e32 v48, v2
	v_mov_b32_e32 v49, v2
	v_mov_b32_e32 v58, v2
	v_mov_b32_e32 v59, v2
	v_mov_b32_e32 v60, v2
	v_mov_b32_e32 v61, v2
	v_mov_b32_e32 v62, v2
	v_mov_b32_e32 v63, v2
	v_mov_b32_e32 v64, v2
	v_mov_b32_e32 v65, v2
	v_mov_b32_e32 v66, v2
	v_mov_b32_e32 v67, v2
	v_mov_b32_e32 v68, v2
	v_mov_b32_e32 v69, v2
	v_mov_b32_e32 v70, v2
	v_mov_b32_e32 v71, v2
	v_mov_b32_e32 v72, v2
	v_mov_b32_e32 v73, v2
	v_mov_b32_e32 v90, v2
	v_mov_b32_e32 v91, v2
	v_mov_b32_e32 v92, v2
	v_mov_b32_e32 v93, v2
	v_mov_b32_e32 v102, v2
	v_mov_b32_e32 v103, v2
	v_mov_b32_e32 v104, v2
	v_mov_b32_e32 v105, v2
	v_mov_b32_e32 v122, v2
	v_mov_b32_e32 v123, v2
	v_mov_b32_e32 v124, v2
	v_mov_b32_e32 v125, v2
	v_mov_b32_e32 v130, v2
	v_mov_b32_e32 v131, v2
	v_mov_b32_e32 v132, v2
	v_mov_b32_e32 v133, v2
	v_mov_b32_e32 v150, v2
	v_mov_b32_e32 v151, v2
	v_mov_b32_e32 v152, v2
	v_mov_b32_e32 v153, v2
	v_mov_b32_e32 v154, v2
	v_mov_b32_e32 v155, v2
	v_mov_b32_e32 v156, v2
	v_mov_b32_e32 v157, v2
	v_mov_b32_e32 v74, v2
	v_mov_b32_e32 v75, v2
	v_mov_b32_e32 v76, v2
	v_mov_b32_e32 v77, v2
	v_mov_b32_e32 v82, v2
	v_mov_b32_e32 v83, v2
	v_mov_b32_e32 v84, v2
	v_mov_b32_e32 v85, v2
	v_mov_b32_e32 v114, v2
	v_mov_b32_e32 v115, v2
	v_mov_b32_e32 v116, v2
	v_mov_b32_e32 v117, v2
	v_mov_b32_e32 v118, v2
	v_mov_b32_e32 v119, v2
	v_mov_b32_e32 v120, v2
	v_mov_b32_e32 v121, v2
	v_mov_b32_e32 v138, v2
	v_mov_b32_e32 v139, v2
	v_mov_b32_e32 v140, v2
	v_mov_b32_e32 v141, v2
	v_mov_b32_e32 v142, v2
	v_mov_b32_e32 v143, v2
	v_mov_b32_e32 v144, v2
	v_mov_b32_e32 v145, v2
	v_mov_b32_e32 v162, v2
	v_mov_b32_e32 v163, v2
	v_mov_b32_e32 v164, v2
	v_mov_b32_e32 v165, v2
	v_mov_b32_e32 v170, v2
	v_mov_b32_e32 v171, v2
	v_mov_b32_e32 v172, v2
	v_mov_b32_e32 v173, v2
	s_add_u32 s0, s18, 0xfff00080
	s_addc_u32 s1, s19, -1
	s_add_i32 s33, 0, 0x10000
	s_cmp_eq_u32 s61, 60
	s_cselect_b32 s23, s11, s1
	s_cselect_b32 s22, s49, s0
	s_cselect_b32 s21, s9, s60
	s_cselect_b32 s20, s58, s59
	s_add_i32 s55, 0, 0x14000
	v_add_u32_e32 v98, s33, v205
	v_add_u32_e32 v134, s55, v205
.LBB0_692:
	ds_read_b128 v[78:81], v98
	ds_read_b128 v[86:89], v98 offset:1024
	ds_read_b128 v[94:97], v98 offset:2048
	ds_read_b128 v[98:101], v98 offset:3072
	ds_read_b128 v[106:109], v134
	ds_read_b128 v[110:113], v134 offset:1024
	ds_read_b128 v[126:129], v134 offset:2048
	ds_read_b128 v[134:137], v134 offset:3072
	v_lshl_add_u64 v[194:195], s[18:19], 0, v[214:215]
	s_add_i32 m0, s27, 0xc000
	ds_read_b128 v[146:149], v239
	ds_read_b128 v[158:161], v239 offset:1024
	ds_read_b128 v[166:169], v239 offset:2048
	ds_read_b128 v[174:177], v239 offset:3072
	ds_read_b128 v[178:181], v239 offset:4096
	ds_read_b128 v[182:185], v239 offset:5120
	ds_read_b128 v[186:189], v239 offset:6144
	ds_read_b128 v[190:193], v239 offset:7168
	global_load_lds_dwordx4 v[194:195], off
	v_lshl_add_u64 v[194:195], s[18:19], 0, v[216:217]
	s_add_i32 m0, s27, 0xe000
	s_nop 0
	global_load_lds_dwordx4 v[194:195], off
	s_waitcnt vmcnt(8)
	s_waitcnt lgkmcnt(0)
	s_barrier
	s_setprio 1
	s_waitcnt lgkmcnt(0)
	v_mfma_f32_16x16x32_bf16 v[170:173], v[78:81], v[146:149], v[170:173]
	v_mfma_f32_16x16x32_bf16 v[162:165], v[94:97], v[146:149], v[162:165]
	v_mfma_f32_16x16x32_bf16 v[142:145], v[78:81], v[166:169], v[142:145]
	v_mfma_f32_16x16x32_bf16 v[138:141], v[94:97], v[166:169], v[138:141]
	v_mfma_f32_16x16x32_bf16 v[118:121], v[78:81], v[178:181], v[118:121]
	v_mfma_f32_16x16x32_bf16 v[114:117], v[94:97], v[178:181], v[114:117]
	v_mfma_f32_16x16x32_bf16 v[82:85], v[78:81], v[186:189], v[82:85]
	v_mfma_f32_16x16x32_bf16 v[74:77], v[94:97], v[186:189], v[74:77]
	v_mfma_f32_16x16x32_bf16 v[170:173], v[86:89], v[158:161], v[170:173]
	v_mfma_f32_16x16x32_bf16 v[162:165], v[98:101], v[158:161], v[162:165]
	v_mfma_f32_16x16x32_bf16 v[142:145], v[86:89], v[174:177], v[142:145]
	v_mfma_f32_16x16x32_bf16 v[138:141], v[98:101], v[174:177], v[138:141]
	v_mfma_f32_16x16x32_bf16 v[118:121], v[86:89], v[182:185], v[118:121]
	v_mfma_f32_16x16x32_bf16 v[114:117], v[98:101], v[182:185], v[114:117]
	v_mfma_f32_16x16x32_bf16 v[82:85], v[86:89], v[190:193], v[82:85]
	v_mfma_f32_16x16x32_bf16 v[74:77], v[98:101], v[190:193], v[74:77]
	s_setprio 0
	s_setprio 1
	v_mfma_f32_16x16x32_bf16 v[154:157], v[106:109], v[146:149], v[154:157]
	v_mfma_f32_16x16x32_bf16 v[130:133], v[106:109], v[166:169], v[130:133]
	v_mfma_f32_16x16x32_bf16 v[122:125], v[126:129], v[166:169], v[122:125]
	v_mfma_f32_16x16x32_bf16 v[102:105], v[106:109], v[178:181], v[102:105]
	v_mfma_f32_16x16x32_bf16 v[90:93], v[126:129], v[178:181], v[90:93]
	v_mfma_f32_16x16x32_bf16 v[70:73], v[106:109], v[186:189], v[70:73]
	v_mfma_f32_16x16x32_bf16 v[66:69], v[126:129], v[186:189], v[66:69]
	v_mfma_f32_16x16x32_bf16 v[154:157], v[110:113], v[158:161], v[154:157]
	v_mfma_f32_16x16x32_bf16 v[146:149], v[126:129], v[146:149], v[150:153]
	v_mfma_f32_16x16x32_bf16 v[130:133], v[110:113], v[174:177], v[130:133]
	v_mfma_f32_16x16x32_bf16 v[122:125], v[134:137], v[174:177], v[122:125]
	v_mfma_f32_16x16x32_bf16 v[102:105], v[110:113], v[182:185], v[102:105]
	v_mfma_f32_16x16x32_bf16 v[90:93], v[134:137], v[182:185], v[90:93]
	v_mfma_f32_16x16x32_bf16 v[70:73], v[110:113], v[190:193], v[70:73]
	v_mfma_f32_16x16x32_bf16 v[66:69], v[134:137], v[190:193], v[66:69]
	v_mfma_f32_16x16x32_bf16 v[146:149], v[134:137], v[158:161], v[146:149]
	s_setprio 0
	s_barrier
	s_add_i32 s0, s33, s26
	v_lshl_add_u64 v[194:195], s[20:21], 0, v[202:203]
	s_mov_b32 m0, s0
	ds_read_b128 v[150:153], v239 offset:16384
	ds_read_b128 v[158:161], v239 offset:17408
	ds_read_b128 v[166:169], v239 offset:18432
	ds_read_b128 v[174:177], v239 offset:19456
	ds_read_b128 v[178:181], v239 offset:20480
	ds_read_b128 v[182:185], v239 offset:21504
	ds_read_b128 v[186:189], v239 offset:22528
	ds_read_b128 v[190:193], v239 offset:23552
	global_load_lds_dwordx4 v[194:195], off
	s_add_i32 m0, s0, 0x2000
	s_add_u32 s0, s20, 0x100000
	v_lshl_add_u64 v[196:197], s[20:21], 0, v[208:209]
	s_addc_u32 s1, s21, 0
	s_add_i32 s33, s55, s26
	global_load_lds_dwordx4 v[196:197], off
	v_lshl_add_u64 v[198:199], s[0:1], 0, v[202:203]
	s_mov_b32 m0, s33
	v_lshl_add_u64 v[200:201], s[22:23], 0, v[210:211]
	global_load_lds_dwordx4 v[198:199], off
	v_lshl_add_u64 v[198:199], s[0:1], 0, v[208:209]
	s_add_i32 m0, s33, 0x2000
	s_nop 0
	global_load_lds_dwordx4 v[198:199], off
	v_lshl_add_u64 v[198:199], s[22:23], 0, v[212:213]
	s_mov_b32 m0, s27
	s_nop 0
	global_load_lds_dwordx4 v[198:199], off
	s_mov_b32 m0, s28
	s_nop 0
	global_load_lds_dwordx4 v[200:201], off
	s_waitcnt vmcnt(8)
	s_waitcnt lgkmcnt(0)
	s_barrier
	s_setprio 1
	s_waitcnt lgkmcnt(0)
	v_mfma_f32_16x16x32_bf16 v[62:65], v[78:81], v[150:153], v[62:65]
	v_mfma_f32_16x16x32_bf16 v[58:61], v[94:97], v[150:153], v[58:61]
	v_mfma_f32_16x16x32_bf16 v[46:49], v[78:81], v[166:169], v[46:49]
	v_mfma_f32_16x16x32_bf16 v[42:45], v[94:97], v[166:169], v[42:45]
	v_mfma_f32_16x16x32_bf16 v[30:33], v[78:81], v[178:181], v[30:33]
	v_mfma_f32_16x16x32_bf16 v[26:29], v[94:97], v[178:181], v[26:29]
	v_mfma_f32_16x16x32_bf16 v[14:17], v[78:81], v[186:189], v[14:17]
	v_mfma_f32_16x16x32_bf16 v[10:13], v[94:97], v[186:189], v[10:13]
	v_mfma_f32_16x16x32_bf16 v[62:65], v[86:89], v[158:161], v[62:65]
	v_mfma_f32_16x16x32_bf16 v[58:61], v[98:101], v[158:161], v[58:61]
	v_mfma_f32_16x16x32_bf16 v[46:49], v[86:89], v[174:177], v[46:49]
	v_mfma_f32_16x16x32_bf16 v[42:45], v[98:101], v[174:177], v[42:45]
	v_mfma_f32_16x16x32_bf16 v[30:33], v[86:89], v[182:185], v[30:33]
	v_mfma_f32_16x16x32_bf16 v[26:29], v[98:101], v[182:185], v[26:29]
	v_mfma_f32_16x16x32_bf16 v[14:17], v[86:89], v[190:193], v[14:17]
	v_mfma_f32_16x16x32_bf16 v[10:13], v[98:101], v[190:193], v[10:13]
	s_setprio 0
	s_setprio 1
	v_mfma_f32_16x16x32_bf16 v[54:57], v[106:109], v[150:153], v[54:57]
	v_mfma_f32_16x16x32_bf16 v[50:53], v[126:129], v[150:153], v[50:53]
	v_mfma_f32_16x16x32_bf16 v[38:41], v[106:109], v[166:169], v[38:41]
	v_mfma_f32_16x16x32_bf16 v[34:37], v[126:129], v[166:169], v[34:37]
	v_mfma_f32_16x16x32_bf16 v[22:25], v[106:109], v[178:181], v[22:25]
	v_mfma_f32_16x16x32_bf16 v[18:21], v[126:129], v[178:181], v[18:21]
	v_mfma_f32_16x16x32_bf16 v[6:9], v[106:109], v[186:189], v[6:9]
	v_mfma_f32_16x16x32_bf16 v[2:5], v[126:129], v[186:189], v[2:5]
	v_mfma_f32_16x16x32_bf16 v[54:57], v[110:113], v[158:161], v[54:57]
	v_mfma_f32_16x16x32_bf16 v[50:53], v[134:137], v[158:161], v[50:53]
	v_mfma_f32_16x16x32_bf16 v[38:41], v[110:113], v[174:177], v[38:41]
	v_mfma_f32_16x16x32_bf16 v[34:37], v[134:137], v[174:177], v[34:37]
	v_mfma_f32_16x16x32_bf16 v[22:25], v[110:113], v[182:185], v[22:25]
	v_mfma_f32_16x16x32_bf16 v[18:21], v[134:137], v[182:185], v[18:21]
	v_mfma_f32_16x16x32_bf16 v[6:9], v[110:113], v[190:193], v[6:9]
	v_mfma_f32_16x16x32_bf16 v[2:5], v[134:137], v[190:193], v[2:5]
	s_setprio 0
	s_barrier
	s_add_i32 s33, 0, 0x18000
	s_add_i32 s55, 0, 0x1c000
	v_add_u32_e32 v98, s33, v205
	v_add_u32_e32 v134, s55, v205
	ds_read_b128 v[78:81], v98
	ds_read_b128 v[86:89], v98 offset:1024
	ds_read_b128 v[94:97], v98 offset:2048
	ds_read_b128 v[98:101], v98 offset:3072
	ds_read_b128 v[106:109], v134
	ds_read_b128 v[110:113], v134 offset:1024
	ds_read_b128 v[126:129], v134 offset:2048
	ds_read_b128 v[134:137], v134 offset:3072
	s_add_u32 s0, s22, 0x100000
	s_addc_u32 s1, s23, 0
	s_mov_b32 m0, s29
	v_lshl_add_u64 v[206:207], s[0:1], 0, v[212:213]
	ds_read_b128 v[150:153], v239 offset:32768
	ds_read_b128 v[158:161], v239 offset:33792
	ds_read_b128 v[166:169], v239 offset:34816
	ds_read_b128 v[174:177], v239 offset:35840
	ds_read_b128 v[178:181], v239 offset:36864
	ds_read_b128 v[182:185], v239 offset:37888
	ds_read_b128 v[186:189], v239 offset:38912
	ds_read_b128 v[190:193], v239 offset:39936
	global_load_lds_dwordx4 v[206:207], off
	v_lshl_add_u64 v[206:207], s[0:1], 0, v[210:211]
	s_mov_b32 m0, s30
	s_nop 0
	global_load_lds_dwordx4 v[206:207], off
	s_waitcnt vmcnt(8)
	s_waitcnt lgkmcnt(0)
	s_barrier
	s_setprio 1
	s_waitcnt lgkmcnt(0)
	v_mfma_f32_16x16x32_bf16 v[170:173], v[78:81], v[150:153], v[170:173]
	v_mfma_f32_16x16x32_bf16 v[162:165], v[94:97], v[150:153], v[162:165]
	v_mfma_f32_16x16x32_bf16 v[142:145], v[78:81], v[166:169], v[142:145]
	v_mfma_f32_16x16x32_bf16 v[138:141], v[94:97], v[166:169], v[138:141]
	v_mfma_f32_16x16x32_bf16 v[118:121], v[78:81], v[178:181], v[118:121]
	v_mfma_f32_16x16x32_bf16 v[114:117], v[94:97], v[178:181], v[114:117]
	v_mfma_f32_16x16x32_bf16 v[82:85], v[78:81], v[186:189], v[82:85]
	v_mfma_f32_16x16x32_bf16 v[74:77], v[94:97], v[186:189], v[74:77]
	v_mfma_f32_16x16x32_bf16 v[170:173], v[86:89], v[158:161], v[170:173]
	v_mfma_f32_16x16x32_bf16 v[162:165], v[98:101], v[158:161], v[162:165]
	v_mfma_f32_16x16x32_bf16 v[142:145], v[86:89], v[174:177], v[142:145]
	v_mfma_f32_16x16x32_bf16 v[138:141], v[98:101], v[174:177], v[138:141]
	v_mfma_f32_16x16x32_bf16 v[118:121], v[86:89], v[182:185], v[118:121]
	v_mfma_f32_16x16x32_bf16 v[114:117], v[98:101], v[182:185], v[114:117]
	v_mfma_f32_16x16x32_bf16 v[82:85], v[86:89], v[190:193], v[82:85]
	v_mfma_f32_16x16x32_bf16 v[74:77], v[98:101], v[190:193], v[74:77]
	s_setprio 0
	s_setprio 1
	v_mfma_f32_16x16x32_bf16 v[154:157], v[106:109], v[150:153], v[154:157]
	v_mfma_f32_16x16x32_bf16 v[146:149], v[126:129], v[150:153], v[146:149]
	v_mfma_f32_16x16x32_bf16 v[130:133], v[106:109], v[166:169], v[130:133]
	v_mfma_f32_16x16x32_bf16 v[122:125], v[126:129], v[166:169], v[122:125]
	v_mfma_f32_16x16x32_bf16 v[102:105], v[106:109], v[178:181], v[102:105]
	v_mfma_f32_16x16x32_bf16 v[90:93], v[126:129], v[178:181], v[90:93]
	v_mfma_f32_16x16x32_bf16 v[70:73], v[106:109], v[186:189], v[70:73]
	v_mfma_f32_16x16x32_bf16 v[66:69], v[126:129], v[186:189], v[66:69]
	v_mfma_f32_16x16x32_bf16 v[154:157], v[110:113], v[158:161], v[154:157]
	v_mfma_f32_16x16x32_bf16 v[150:153], v[134:137], v[158:161], v[146:149]
	v_mfma_f32_16x16x32_bf16 v[130:133], v[110:113], v[174:177], v[130:133]
	v_mfma_f32_16x16x32_bf16 v[122:125], v[134:137], v[174:177], v[122:125]
	v_mfma_f32_16x16x32_bf16 v[102:105], v[110:113], v[182:185], v[102:105]
	v_mfma_f32_16x16x32_bf16 v[90:93], v[134:137], v[182:185], v[90:93]
	v_mfma_f32_16x16x32_bf16 v[70:73], v[110:113], v[190:193], v[70:73]
	v_mfma_f32_16x16x32_bf16 v[66:69], v[134:137], v[190:193], v[66:69]
	s_setprio 0
	s_barrier
	s_add_i32 s0, s33, s26
	v_lshl_add_u64 v[194:195], v[194:195], 0, s[80:81]
	s_mov_b32 m0, s0
	ds_read_b128 v[146:149], v239 offset:49152
	ds_read_b128 v[158:161], v239 offset:50176
	ds_read_b128 v[166:169], v239 offset:51200
	ds_read_b128 v[174:177], v239 offset:52224
	ds_read_b128 v[178:181], v239 offset:53248
	ds_read_b128 v[182:185], v239 offset:54272
	ds_read_b128 v[186:189], v239 offset:55296
	ds_read_b128 v[190:193], v239 offset:56320
	global_load_lds_dwordx4 v[194:195], off
	s_add_i32 m0, s0, 0x2000
	s_add_u32 s0, s20, 0x100080
	v_lshl_add_u64 v[194:195], v[196:197], 0, s[80:81]
	s_addc_u32 s1, s21, 0
	s_add_i32 s20, s55, s26
	global_load_lds_dwordx4 v[194:195], off
	v_lshl_add_u64 v[194:195], s[0:1], 0, v[202:203]
	s_mov_b32 m0, s20
	s_nop 0
	global_load_lds_dwordx4 v[194:195], off
	v_lshl_add_u64 v[194:195], s[0:1], 0, v[208:209]
	s_add_i32 m0, s20, 0x2000
	s_nop 0
	global_load_lds_dwordx4 v[194:195], off
	v_lshl_add_u64 v[194:195], v[198:199], 0, s[80:81]
	s_mov_b32 m0, s35
	s_nop 0
	global_load_lds_dwordx4 v[194:195], off
	v_lshl_add_u64 v[194:195], v[200:201], 0, s[80:81]
	s_mov_b32 m0, s36
	s_nop 0
	global_load_lds_dwordx4 v[194:195], off
	s_waitcnt vmcnt(8)
	s_waitcnt lgkmcnt(0)
	s_barrier
	s_setprio 1
	s_waitcnt lgkmcnt(0)
	v_mfma_f32_16x16x32_bf16 v[62:65], v[78:81], v[146:149], v[62:65]
	v_mfma_f32_16x16x32_bf16 v[58:61], v[94:97], v[146:149], v[58:61]
	v_mfma_f32_16x16x32_bf16 v[46:49], v[78:81], v[166:169], v[46:49]
	v_mfma_f32_16x16x32_bf16 v[42:45], v[94:97], v[166:169], v[42:45]
	v_mfma_f32_16x16x32_bf16 v[30:33], v[78:81], v[178:181], v[30:33]
	v_mfma_f32_16x16x32_bf16 v[26:29], v[94:97], v[178:181], v[26:29]
	v_mfma_f32_16x16x32_bf16 v[14:17], v[78:81], v[186:189], v[14:17]
	v_mfma_f32_16x16x32_bf16 v[10:13], v[94:97], v[186:189], v[10:13]
	v_mfma_f32_16x16x32_bf16 v[62:65], v[86:89], v[158:161], v[62:65]
	v_mfma_f32_16x16x32_bf16 v[58:61], v[98:101], v[158:161], v[58:61]
	v_mfma_f32_16x16x32_bf16 v[46:49], v[86:89], v[174:177], v[46:49]
	v_mfma_f32_16x16x32_bf16 v[42:45], v[98:101], v[174:177], v[42:45]
	v_mfma_f32_16x16x32_bf16 v[30:33], v[86:89], v[182:185], v[30:33]
	v_mfma_f32_16x16x32_bf16 v[26:29], v[98:101], v[182:185], v[26:29]
	v_mfma_f32_16x16x32_bf16 v[14:17], v[86:89], v[190:193], v[14:17]
	v_mfma_f32_16x16x32_bf16 v[10:13], v[98:101], v[190:193], v[10:13]
	s_setprio 0
	s_setprio 1
	v_mfma_f32_16x16x32_bf16 v[54:57], v[106:109], v[146:149], v[54:57]
	v_mfma_f32_16x16x32_bf16 v[50:53], v[126:129], v[146:149], v[50:53]
	v_mfma_f32_16x16x32_bf16 v[38:41], v[106:109], v[166:169], v[38:41]
	v_mfma_f32_16x16x32_bf16 v[34:37], v[126:129], v[166:169], v[34:37]
	v_mfma_f32_16x16x32_bf16 v[22:25], v[106:109], v[178:181], v[22:25]
	v_mfma_f32_16x16x32_bf16 v[18:21], v[126:129], v[178:181], v[18:21]
	v_mfma_f32_16x16x32_bf16 v[6:9], v[106:109], v[186:189], v[6:9]
	v_mfma_f32_16x16x32_bf16 v[2:5], v[126:129], v[186:189], v[2:5]
	v_mfma_f32_16x16x32_bf16 v[54:57], v[110:113], v[158:161], v[54:57]
	v_mfma_f32_16x16x32_bf16 v[50:53], v[134:137], v[158:161], v[50:53]
	v_mfma_f32_16x16x32_bf16 v[38:41], v[110:113], v[174:177], v[38:41]
	v_mfma_f32_16x16x32_bf16 v[34:37], v[134:137], v[174:177], v[34:37]
	v_mfma_f32_16x16x32_bf16 v[22:25], v[110:113], v[182:185], v[22:25]
	v_mfma_f32_16x16x32_bf16 v[18:21], v[134:137], v[182:185], v[18:21]
	v_mfma_f32_16x16x32_bf16 v[6:9], v[110:113], v[190:193], v[6:9]
	v_mfma_f32_16x16x32_bf16 v[2:5], v[134:137], v[190:193], v[2:5]
	s_setprio 0
	s_add_i32 s61, s61, 2
	s_add_u32 s18, s18, 0x100
	s_addc_u32 s19, s19, 0
	s_add_u32 s59, s59, 0x100
	s_addc_u32 s60, s60, 0
	s_cmp_gt_u32 s61, 61
	s_cbranch_scc1 .Lrot_exit_1
	s_add_u32 s0, s18, 0xfff00080
	s_addc_u32 s1, s19, -1
	s_add_i32 s33, 0, 0x10000
	s_cmp_eq_u32 s61, 60
	s_cselect_b32 s23, s11, s1
	s_cselect_b32 s22, s49, s0
	s_cselect_b32 s21, s9, s60
	s_cselect_b32 s20, s58, s59
	s_add_i32 s55, 0, 0x14000
	v_add_u32_e32 v98, s33, v205
	v_add_u32_e32 v134, s55, v205
	s_barrier
	s_branch .LBB0_692
.Lrot_exit_1:
	s_barrier
	s_and_b64 vcc, exec, s[6:7]
	s_cbranch_vccz .LBB0_695
	s_barrier

.LBB0_711:
	s_add_u32 s18, s18, 0x100080
	s_addc_u32 s19, s19, 0
	s_add_u32 s9, s20, 0x100
	v_mov_b32_e32 v2, 0
	s_addc_u32 s11, s21, 0
	s_mov_b32 s49, -2
	v_mov_b32_e32 v3, v2
	v_mov_b32_e32 v4, v2
	v_mov_b32_e32 v5, v2
	v_mov_b32_e32 v6, v2
	v_mov_b32_e32 v7, v2
	v_mov_b32_e32 v8, v2
	v_mov_b32_e32 v9, v2
	v_mov_b32_e32 v10, v2
	v_mov_b32_e32 v11, v2
	v_mov_b32_e32 v12, v2
	v_mov_b32_e32 v13, v2
	v_mov_b32_e32 v14, v2
	v_mov_b32_e32 v15, v2
	v_mov_b32_e32 v16, v2
	v_mov_b32_e32 v17, v2
	v_mov_b32_e32 v26, v2
	v_mov_b32_e32 v27, v2
	v_mov_b32_e32 v28, v2
	v_mov_b32_e32 v29, v2
	v_mov_b32_e32 v30, v2
	v_mov_b32_e32 v31, v2
	v_mov_b32_e32 v32, v2
	v_mov_b32_e32 v33, v2
	v_mov_b32_e32 v42, v2
	v_mov_b32_e32 v43, v2
	v_mov_b32_e32 v44, v2
	v_mov_b32_e32 v45, v2
	v_mov_b32_e32 v46, v2
	v_mov_b32_e32 v47, v2
	v_mov_b32_e32 v48, v2
	v_mov_b32_e32 v49, v2
	v_mov_b32_e32 v18, v2
	v_mov_b32_e32 v19, v2
	v_mov_b32_e32 v20, v2
	v_mov_b32_e32 v21, v2
	v_mov_b32_e32 v22, v2
	v_mov_b32_e32 v23, v2
	v_mov_b32_e32 v24, v2
	v_mov_b32_e32 v25, v2
	v_mov_b32_e32 v34, v2
	v_mov_b32_e32 v35, v2
	v_mov_b32_e32 v36, v2
	v_mov_b32_e32 v37, v2
	v_mov_b32_e32 v38, v2
	v_mov_b32_e32 v39, v2
	v_mov_b32_e32 v40, v2
	v_mov_b32_e32 v41, v2
	v_mov_b32_e32 v50, v2
	v_mov_b32_e32 v51, v2
	v_mov_b32_e32 v52, v2
	v_mov_b32_e32 v53, v2
	v_mov_b32_e32 v54, v2
	v_mov_b32_e32 v55, v2
	v_mov_b32_e32 v56, v2
	v_mov_b32_e32 v57, v2
	v_mov_b32_e32 v58, v2
	v_mov_b32_e32 v59, v2
	v_mov_b32_e32 v60, v2
	v_mov_b32_e32 v61, v2
	v_mov_b32_e32 v62, v2
	v_mov_b32_e32 v63, v2
	v_mov_b32_e32 v64, v2
	v_mov_b32_e32 v65, v2
	v_mov_b32_e32 v66, v2
	v_mov_b32_e32 v67, v2
	v_mov_b32_e32 v68, v2
	v_mov_b32_e32 v69, v2
	v_mov_b32_e32 v70, v2
	v_mov_b32_e32 v71, v2
	v_mov_b32_e32 v72, v2
	v_mov_b32_e32 v73, v2
	v_mov_b32_e32 v74, v2
	v_mov_b32_e32 v75, v2
	v_mov_b32_e32 v76, v2
	v_mov_b32_e32 v77, v2
	v_mov_b32_e32 v78, v2
	v_mov_b32_e32 v79, v2
	v_mov_b32_e32 v80, v2
	v_mov_b32_e32 v81, v2
	v_mov_b32_e32 v86, v2
	v_mov_b32_e32 v87, v2
	v_mov_b32_e32 v88, v2
	v_mov_b32_e32 v89, v2
	v_mov_b32_e32 v94, v2
	v_mov_b32_e32 v95, v2
	v_mov_b32_e32 v96, v2
	v_mov_b32_e32 v97, v2
	v_mov_b32_e32 v102, v2
	v_mov_b32_e32 v103, v2
	v_mov_b32_e32 v104, v2
	v_mov_b32_e32 v105, v2
	v_mov_b32_e32 v110, v2
	v_mov_b32_e32 v111, v2
	v_mov_b32_e32 v112, v2
	v_mov_b32_e32 v113, v2
	v_mov_b32_e32 v82, v2
	v_mov_b32_e32 v83, v2
	v_mov_b32_e32 v84, v2
	v_mov_b32_e32 v85, v2
	v_mov_b32_e32 v90, v2
	v_mov_b32_e32 v91, v2
	v_mov_b32_e32 v92, v2
	v_mov_b32_e32 v93, v2
	v_mov_b32_e32 v98, v2
	v_mov_b32_e32 v99, v2
	v_mov_b32_e32 v100, v2
	v_mov_b32_e32 v101, v2
	v_mov_b32_e32 v106, v2
	v_mov_b32_e32 v107, v2
	v_mov_b32_e32 v108, v2
	v_mov_b32_e32 v109, v2
	v_mov_b32_e32 v114, v2
	v_mov_b32_e32 v115, v2
	v_mov_b32_e32 v116, v2
	v_mov_b32_e32 v117, v2
	v_mov_b32_e32 v118, v2
	v_mov_b32_e32 v119, v2
	v_mov_b32_e32 v120, v2
	v_mov_b32_e32 v121, v2
	v_mov_b32_e32 v122, v2
	v_mov_b32_e32 v123, v2
	v_mov_b32_e32 v124, v2
	v_mov_b32_e32 v125, v2
	v_mov_b32_e32 v126, v2
	v_mov_b32_e32 v127, v2
	v_mov_b32_e32 v128, v2
	v_mov_b32_e32 v129, v2
	s_add_u32 s0, s18, 0xfff00080
	s_addc_u32 s1, s19, -1
	s_add_i32 s33, 0, 0x10000
	s_cmp_eq_u32 s49, 4
	s_cselect_b32 s23, s15, s1
	s_cselect_b32 s22, s14, s0
	s_cselect_b32 s21, s17, s11
	s_cselect_b32 s20, s16, s9
	s_add_i32 s55, 0, 0x14000
	v_add_u32_e32 v152, s33, v136
	v_add_u32_e32 v168, s55, v136
.LBB0_712:
	ds_read_b128 v[140:143], v152
	ds_read_b128 v[144:147], v152 offset:1024
	ds_read_b128 v[148:151], v152 offset:2048
	ds_read_b128 v[152:155], v152 offset:3072
	ds_read_b128 v[156:159], v168
	ds_read_b128 v[160:163], v168 offset:1024
	ds_read_b128 v[164:167], v168 offset:2048
	ds_read_b128 v[168:171], v168 offset:3072
	v_lshl_add_u64 v[200:201], s[18:19], 0, v[132:133]
	s_add_i32 m0, s27, 0xc000
	ds_read_b128 v[172:175], v139
	ds_read_b128 v[176:179], v139 offset:1024
	ds_read_b128 v[180:183], v139 offset:2048
	ds_read_b128 v[184:187], v139 offset:3072
	ds_read_b128 v[188:191], v139 offset:4096
	ds_read_b128 v[192:195], v139 offset:5120
	ds_read_b128 v[196:199], v139 offset:6144
	ds_read_b128 v[208:211], v139 offset:7168
	global_load_lds_dwordx4 v[200:201], off
	v_lshl_add_u64 v[200:201], s[18:19], 0, v[134:135]
	s_add_i32 m0, s27, 0xe000
	s_nop 0
	global_load_lds_dwordx4 v[200:201], off
	s_waitcnt vmcnt(8)
	s_waitcnt lgkmcnt(0)
	s_barrier
	s_setprio 1
	s_waitcnt lgkmcnt(0)
	v_mfma_f32_16x16x32_bf16 v[126:129], v[140:143], v[172:175], v[126:129]
	v_mfma_f32_16x16x32_bf16 v[122:125], v[148:151], v[172:175], v[122:125]
	v_mfma_f32_16x16x32_bf16 v[118:121], v[140:143], v[180:183], v[118:121]
	v_mfma_f32_16x16x32_bf16 v[114:117], v[148:151], v[180:183], v[114:117]
	v_mfma_f32_16x16x32_bf16 v[106:109], v[140:143], v[188:191], v[106:109]
	v_mfma_f32_16x16x32_bf16 v[98:101], v[148:151], v[188:191], v[98:101]
	v_mfma_f32_16x16x32_bf16 v[90:93], v[140:143], v[196:199], v[90:93]
	v_mfma_f32_16x16x32_bf16 v[82:85], v[148:151], v[196:199], v[82:85]
	v_mfma_f32_16x16x32_bf16 v[126:129], v[144:147], v[176:179], v[126:129]
	v_mfma_f32_16x16x32_bf16 v[122:125], v[152:155], v[176:179], v[122:125]
	v_mfma_f32_16x16x32_bf16 v[118:121], v[144:147], v[184:187], v[118:121]
	v_mfma_f32_16x16x32_bf16 v[114:117], v[152:155], v[184:187], v[114:117]
	v_mfma_f32_16x16x32_bf16 v[106:109], v[144:147], v[192:195], v[106:109]
	v_mfma_f32_16x16x32_bf16 v[98:101], v[152:155], v[192:195], v[98:101]
	v_mfma_f32_16x16x32_bf16 v[90:93], v[144:147], v[208:211], v[90:93]
	v_mfma_f32_16x16x32_bf16 v[82:85], v[152:155], v[208:211], v[82:85]
	s_setprio 0
	s_setprio 1
	v_mfma_f32_16x16x32_bf16 v[110:113], v[156:159], v[172:175], v[110:113]
	v_mfma_f32_16x16x32_bf16 v[102:105], v[164:167], v[172:175], v[102:105]
	v_mfma_f32_16x16x32_bf16 v[94:97], v[156:159], v[180:183], v[94:97]
	v_mfma_f32_16x16x32_bf16 v[86:89], v[164:167], v[180:183], v[86:89]
	v_mfma_f32_16x16x32_bf16 v[78:81], v[156:159], v[188:191], v[78:81]
	v_mfma_f32_16x16x32_bf16 v[74:77], v[164:167], v[188:191], v[74:77]
	v_mfma_f32_16x16x32_bf16 v[70:73], v[156:159], v[196:199], v[70:73]
	v_mfma_f32_16x16x32_bf16 v[66:69], v[164:167], v[196:199], v[66:69]
	v_mfma_f32_16x16x32_bf16 v[110:113], v[160:163], v[176:179], v[110:113]
	v_mfma_f32_16x16x32_bf16 v[102:105], v[168:171], v[176:179], v[102:105]
	v_mfma_f32_16x16x32_bf16 v[94:97], v[160:163], v[184:187], v[94:97]
	v_mfma_f32_16x16x32_bf16 v[86:89], v[168:171], v[184:187], v[86:89]
	v_mfma_f32_16x16x32_bf16 v[78:81], v[160:163], v[192:195], v[78:81]
	v_mfma_f32_16x16x32_bf16 v[74:77], v[168:171], v[192:195], v[74:77]
	v_mfma_f32_16x16x32_bf16 v[70:73], v[160:163], v[208:211], v[70:73]
	v_mfma_f32_16x16x32_bf16 v[66:69], v[168:171], v[208:211], v[66:69]
	s_setprio 0
	s_barrier
	s_add_i32 s0, s33, s26
	v_lshl_add_u64 v[200:201], s[20:21], 0, v[202:203]
	s_mov_b32 m0, s0
	ds_read_b128 v[172:175], v139 offset:16384
	ds_read_b128 v[176:179], v139 offset:17408
	ds_read_b128 v[180:183], v139 offset:18432
	ds_read_b128 v[184:187], v139 offset:19456
	ds_read_b128 v[188:191], v139 offset:20480
	ds_read_b128 v[192:195], v139 offset:21504
	ds_read_b128 v[196:199], v139 offset:22528
	ds_read_b128 v[208:211], v139 offset:23552
	global_load_lds_dwordx4 v[200:201], off
	s_add_i32 m0, s0, 0x2000
	s_add_u32 s0, s20, 0x100000
	v_lshl_add_u64 v[204:205], s[20:21], 0, v[130:131]
	s_addc_u32 s1, s21, 0
	s_add_i32 s33, s55, s26
	global_load_lds_dwordx4 v[204:205], off
	v_lshl_add_u64 v[206:207], s[0:1], 0, v[202:203]
	s_mov_b32 m0, s33
	v_lshl_add_u64 v[212:213], s[22:23], 0, v[130:131]
	global_load_lds_dwordx4 v[206:207], off
	v_lshl_add_u64 v[206:207], s[0:1], 0, v[130:131]
	s_add_i32 m0, s33, 0x2000
	s_nop 0
	global_load_lds_dwordx4 v[206:207], off
	v_lshl_add_u64 v[206:207], s[22:23], 0, v[202:203]
	s_mov_b32 m0, s27
	s_nop 0
	global_load_lds_dwordx4 v[206:207], off
	s_mov_b32 m0, s28
	s_nop 0
	global_load_lds_dwordx4 v[212:213], off
	s_waitcnt vmcnt(8)
	s_waitcnt lgkmcnt(0)
	s_barrier
	s_setprio 1
	s_waitcnt lgkmcnt(0)
	v_mfma_f32_16x16x32_bf16 v[62:65], v[140:143], v[172:175], v[62:65]
	v_mfma_f32_16x16x32_bf16 v[58:61], v[148:151], v[172:175], v[58:61]
	v_mfma_f32_16x16x32_bf16 v[54:57], v[140:143], v[180:183], v[54:57]
	v_mfma_f32_16x16x32_bf16 v[50:53], v[148:151], v[180:183], v[50:53]
	v_mfma_f32_16x16x32_bf16 v[38:41], v[140:143], v[188:191], v[38:41]
	v_mfma_f32_16x16x32_bf16 v[34:37], v[148:151], v[188:191], v[34:37]
	v_mfma_f32_16x16x32_bf16 v[22:25], v[140:143], v[196:199], v[22:25]
	v_mfma_f32_16x16x32_bf16 v[18:21], v[148:151], v[196:199], v[18:21]
	v_mfma_f32_16x16x32_bf16 v[62:65], v[144:147], v[176:179], v[62:65]
	v_mfma_f32_16x16x32_bf16 v[58:61], v[152:155], v[176:179], v[58:61]
	v_mfma_f32_16x16x32_bf16 v[54:57], v[144:147], v[184:187], v[54:57]
	v_mfma_f32_16x16x32_bf16 v[50:53], v[152:155], v[184:187], v[50:53]
	v_mfma_f32_16x16x32_bf16 v[38:41], v[144:147], v[192:195], v[38:41]
	v_mfma_f32_16x16x32_bf16 v[34:37], v[152:155], v[192:195], v[34:37]
	v_mfma_f32_16x16x32_bf16 v[22:25], v[144:147], v[208:211], v[22:25]
	v_mfma_f32_16x16x32_bf16 v[18:21], v[152:155], v[208:211], v[18:21]
	s_setprio 0
	s_setprio 1
	v_mfma_f32_16x16x32_bf16 v[46:49], v[156:159], v[172:175], v[46:49]
	v_mfma_f32_16x16x32_bf16 v[42:45], v[164:167], v[172:175], v[42:45]
	v_mfma_f32_16x16x32_bf16 v[30:33], v[156:159], v[180:183], v[30:33]
	v_mfma_f32_16x16x32_bf16 v[26:29], v[164:167], v[180:183], v[26:29]
	v_mfma_f32_16x16x32_bf16 v[14:17], v[156:159], v[188:191], v[14:17]
	v_mfma_f32_16x16x32_bf16 v[10:13], v[164:167], v[188:191], v[10:13]
	v_mfma_f32_16x16x32_bf16 v[6:9], v[156:159], v[196:199], v[6:9]
	v_mfma_f32_16x16x32_bf16 v[2:5], v[164:167], v[196:199], v[2:5]
	v_mfma_f32_16x16x32_bf16 v[46:49], v[160:163], v[176:179], v[46:49]
	v_mfma_f32_16x16x32_bf16 v[42:45], v[168:171], v[176:179], v[42:45]
	v_mfma_f32_16x16x32_bf16 v[30:33], v[160:163], v[184:187], v[30:33]
	v_mfma_f32_16x16x32_bf16 v[26:29], v[168:171], v[184:187], v[26:29]
	v_mfma_f32_16x16x32_bf16 v[14:17], v[160:163], v[192:195], v[14:17]
	v_mfma_f32_16x16x32_bf16 v[10:13], v[168:171], v[192:195], v[10:13]
	v_mfma_f32_16x16x32_bf16 v[6:9], v[160:163], v[208:211], v[6:9]
	v_mfma_f32_16x16x32_bf16 v[2:5], v[168:171], v[208:211], v[2:5]
	s_setprio 0
	s_barrier
	s_add_i32 s33, 0, 0x18000
	s_add_i32 s55, 0, 0x1c000
	v_add_u32_e32 v152, s33, v136
	v_add_u32_e32 v168, s55, v136
	ds_read_b128 v[140:143], v152
	ds_read_b128 v[144:147], v152 offset:1024
	ds_read_b128 v[148:151], v152 offset:2048
	ds_read_b128 v[152:155], v152 offset:3072
	ds_read_b128 v[156:159], v168
	ds_read_b128 v[160:163], v168 offset:1024
	ds_read_b128 v[164:167], v168 offset:2048
	ds_read_b128 v[168:171], v168 offset:3072
	s_add_u32 s0, s22, 0x100000
	s_addc_u32 s1, s23, 0
	s_mov_b32 m0, s29
	v_lshl_add_u64 v[214:215], s[0:1], 0, v[202:203]
	ds_read_b128 v[172:175], v139 offset:32768
	ds_read_b128 v[176:179], v139 offset:33792
	ds_read_b128 v[180:183], v139 offset:34816
	ds_read_b128 v[184:187], v139 offset:35840
	ds_read_b128 v[188:191], v139 offset:36864
	ds_read_b128 v[192:195], v139 offset:37888
	ds_read_b128 v[196:199], v139 offset:38912
	ds_read_b128 v[208:211], v139 offset:39936
	global_load_lds_dwordx4 v[214:215], off
	v_lshl_add_u64 v[214:215], s[0:1], 0, v[130:131]
	s_mov_b32 m0, s30
	s_nop 0
	global_load_lds_dwordx4 v[214:215], off
	s_waitcnt vmcnt(8)
	s_waitcnt lgkmcnt(0)
	s_barrier
	s_setprio 1
	s_waitcnt lgkmcnt(0)
	v_mfma_f32_16x16x32_bf16 v[126:129], v[140:143], v[172:175], v[126:129]
	v_mfma_f32_16x16x32_bf16 v[122:125], v[148:151], v[172:175], v[122:125]
	v_mfma_f32_16x16x32_bf16 v[118:121], v[140:143], v[180:183], v[118:121]
	v_mfma_f32_16x16x32_bf16 v[114:117], v[148:151], v[180:183], v[114:117]
	v_mfma_f32_16x16x32_bf16 v[106:109], v[140:143], v[188:191], v[106:109]
	v_mfma_f32_16x16x32_bf16 v[98:101], v[148:151], v[188:191], v[98:101]
	v_mfma_f32_16x16x32_bf16 v[90:93], v[140:143], v[196:199], v[90:93]
	v_mfma_f32_16x16x32_bf16 v[82:85], v[148:151], v[196:199], v[82:85]
	v_mfma_f32_16x16x32_bf16 v[126:129], v[144:147], v[176:179], v[126:129]
	v_mfma_f32_16x16x32_bf16 v[122:125], v[152:155], v[176:179], v[122:125]
	v_mfma_f32_16x16x32_bf16 v[118:121], v[144:147], v[184:187], v[118:121]
	v_mfma_f32_16x16x32_bf16 v[114:117], v[152:155], v[184:187], v[114:117]
	v_mfma_f32_16x16x32_bf16 v[106:109], v[144:147], v[192:195], v[106:109]
	v_mfma_f32_16x16x32_bf16 v[98:101], v[152:155], v[192:195], v[98:101]
	v_mfma_f32_16x16x32_bf16 v[90:93], v[144:147], v[208:211], v[90:93]
	v_mfma_f32_16x16x32_bf16 v[82:85], v[152:155], v[208:211], v[82:85]
	s_setprio 0
	s_setprio 1
	v_mfma_f32_16x16x32_bf16 v[110:113], v[156:159], v[172:175], v[110:113]
	v_mfma_f32_16x16x32_bf16 v[102:105], v[164:167], v[172:175], v[102:105]
	v_mfma_f32_16x16x32_bf16 v[94:97], v[156:159], v[180:183], v[94:97]
	v_mfma_f32_16x16x32_bf16 v[86:89], v[164:167], v[180:183], v[86:89]
	v_mfma_f32_16x16x32_bf16 v[78:81], v[156:159], v[188:191], v[78:81]
	v_mfma_f32_16x16x32_bf16 v[74:77], v[164:167], v[188:191], v[74:77]
	v_mfma_f32_16x16x32_bf16 v[70:73], v[156:159], v[196:199], v[70:73]
	v_mfma_f32_16x16x32_bf16 v[66:69], v[164:167], v[196:199], v[66:69]
	v_mfma_f32_16x16x32_bf16 v[110:113], v[160:163], v[176:179], v[110:113]
	v_mfma_f32_16x16x32_bf16 v[102:105], v[168:171], v[176:179], v[102:105]
	v_mfma_f32_16x16x32_bf16 v[94:97], v[160:163], v[184:187], v[94:97]
	v_mfma_f32_16x16x32_bf16 v[86:89], v[168:171], v[184:187], v[86:89]
	v_mfma_f32_16x16x32_bf16 v[78:81], v[160:163], v[192:195], v[78:81]
	v_mfma_f32_16x16x32_bf16 v[74:77], v[168:171], v[192:195], v[74:77]
	v_mfma_f32_16x16x32_bf16 v[70:73], v[160:163], v[208:211], v[70:73]
	v_mfma_f32_16x16x32_bf16 v[66:69], v[168:171], v[208:211], v[66:69]
	s_setprio 0
	s_barrier
	s_add_i32 s0, s33, s26
	v_lshl_add_u64 v[200:201], v[200:201], 0, s[80:81]
	s_mov_b32 m0, s0
	ds_read_b128 v[172:175], v139 offset:49152
	ds_read_b128 v[176:179], v139 offset:50176
	ds_read_b128 v[180:183], v139 offset:51200
	ds_read_b128 v[184:187], v139 offset:52224
	ds_read_b128 v[188:191], v139 offset:53248
	ds_read_b128 v[192:195], v139 offset:54272
	ds_read_b128 v[196:199], v139 offset:55296
	ds_read_b128 v[208:211], v139 offset:56320
	global_load_lds_dwordx4 v[200:201], off
	s_add_i32 m0, s0, 0x2000
	s_add_u32 s0, s20, 0x100080
	v_lshl_add_u64 v[200:201], v[204:205], 0, s[80:81]
	s_addc_u32 s1, s21, 0
	s_add_i32 s20, s55, s26
	global_load_lds_dwordx4 v[200:201], off
	v_lshl_add_u64 v[200:201], s[0:1], 0, v[202:203]
	s_mov_b32 m0, s20
	s_nop 0
	global_load_lds_dwordx4 v[200:201], off
	v_lshl_add_u64 v[200:201], s[0:1], 0, v[130:131]
	s_add_i32 m0, s20, 0x2000
	s_nop 0
	global_load_lds_dwordx4 v[200:201], off
	v_lshl_add_u64 v[200:201], v[206:207], 0, s[80:81]
	s_mov_b32 m0, s31
	s_nop 0
	global_load_lds_dwordx4 v[200:201], off
	v_lshl_add_u64 v[200:201], v[212:213], 0, s[80:81]
	s_mov_b32 m0, s34
	s_nop 0
	global_load_lds_dwordx4 v[200:201], off
	s_waitcnt vmcnt(8)
	s_waitcnt lgkmcnt(0)
	s_barrier
	s_setprio 1
	s_waitcnt lgkmcnt(0)
	v_mfma_f32_16x16x32_bf16 v[62:65], v[140:143], v[172:175], v[62:65]
	v_mfma_f32_16x16x32_bf16 v[58:61], v[148:151], v[172:175], v[58:61]
	v_mfma_f32_16x16x32_bf16 v[54:57], v[140:143], v[180:183], v[54:57]
	v_mfma_f32_16x16x32_bf16 v[50:53], v[148:151], v[180:183], v[50:53]
	v_mfma_f32_16x16x32_bf16 v[38:41], v[140:143], v[188:191], v[38:41]
	v_mfma_f32_16x16x32_bf16 v[34:37], v[148:151], v[188:191], v[34:37]
	v_mfma_f32_16x16x32_bf16 v[22:25], v[140:143], v[196:199], v[22:25]
	v_mfma_f32_16x16x32_bf16 v[18:21], v[148:151], v[196:199], v[18:21]
	v_mfma_f32_16x16x32_bf16 v[62:65], v[144:147], v[176:179], v[62:65]
	v_mfma_f32_16x16x32_bf16 v[58:61], v[152:155], v[176:179], v[58:61]
	v_mfma_f32_16x16x32_bf16 v[54:57], v[144:147], v[184:187], v[54:57]
	v_mfma_f32_16x16x32_bf16 v[50:53], v[152:155], v[184:187], v[50:53]
	v_mfma_f32_16x16x32_bf16 v[38:41], v[144:147], v[192:195], v[38:41]
	v_mfma_f32_16x16x32_bf16 v[34:37], v[152:155], v[192:195], v[34:37]
	v_mfma_f32_16x16x32_bf16 v[22:25], v[144:147], v[208:211], v[22:25]
	v_mfma_f32_16x16x32_bf16 v[18:21], v[152:155], v[208:211], v[18:21]
	s_setprio 0
	s_setprio 1
	v_mfma_f32_16x16x32_bf16 v[46:49], v[156:159], v[172:175], v[46:49]
	v_mfma_f32_16x16x32_bf16 v[42:45], v[164:167], v[172:175], v[42:45]
	v_mfma_f32_16x16x32_bf16 v[30:33], v[156:159], v[180:183], v[30:33]
	v_mfma_f32_16x16x32_bf16 v[26:29], v[164:167], v[180:183], v[26:29]
	v_mfma_f32_16x16x32_bf16 v[14:17], v[156:159], v[188:191], v[14:17]
	v_mfma_f32_16x16x32_bf16 v[10:13], v[164:167], v[188:191], v[10:13]
	v_mfma_f32_16x16x32_bf16 v[6:9], v[156:159], v[196:199], v[6:9]
	v_mfma_f32_16x16x32_bf16 v[2:5], v[164:167], v[196:199], v[2:5]
	v_mfma_f32_16x16x32_bf16 v[46:49], v[160:163], v[176:179], v[46:49]
	v_mfma_f32_16x16x32_bf16 v[42:45], v[168:171], v[176:179], v[42:45]
	v_mfma_f32_16x16x32_bf16 v[30:33], v[160:163], v[184:187], v[30:33]
	v_mfma_f32_16x16x32_bf16 v[26:29], v[168:171], v[184:187], v[26:29]
	v_mfma_f32_16x16x32_bf16 v[14:17], v[160:163], v[192:195], v[14:17]
	v_mfma_f32_16x16x32_bf16 v[10:13], v[168:171], v[192:195], v[10:13]
	v_mfma_f32_16x16x32_bf16 v[6:9], v[160:163], v[208:211], v[6:9]
	v_mfma_f32_16x16x32_bf16 v[2:5], v[168:171], v[208:211], v[2:5]
	s_setprio 0
	s_add_i32 s49, s49, 2
	s_add_u32 s18, s18, 0x100
	s_addc_u32 s19, s19, 0
	s_add_u32 s9, s9, 0x100
	s_addc_u32 s11, s11, 0
	s_cmp_gt_u32 s49, 5
	s_cbranch_scc1 .Lrot_exit_2
	s_add_u32 s0, s18, 0xfff00080
	s_addc_u32 s1, s19, -1
	s_add_i32 s33, 0, 0x10000
	s_cmp_eq_u32 s49, 4
	s_cselect_b32 s23, s15, s1
	s_cselect_b32 s22, s14, s0
	s_cselect_b32 s21, s17, s11
	s_cselect_b32 s20, s16, s9
	s_add_i32 s55, 0, 0x14000
	v_add_u32_e32 v152, s33, v136
	v_add_u32_e32 v168, s55, v136
	s_barrier
	s_branch .LBB0_712

.LBB0_836:
	s_ashr_i32 s11, s10, 31
	s_lshl_b64 s[0:1], s[10:11], 20
	s_add_u32 s14, s42, s0
	s_addc_u32 s15, s43, s1
	s_and_b64 s[0:1], s[2:3], exec
	s_cselect_b32 s11, s15, s19
	s_cselect_b32 s38, s14, s18
	s_ashr_i32 s9, s8, 31
	s_lshl_b64 s[0:1], s[8:9], 20
	s_add_u32 s16, s24, s0
	s_addc_u32 s17, s25, s1
	s_and_b64 s[0:1], s[2:3], exec
	s_cselect_b32 s9, s17, s21
	s_cselect_b32 s39, s16, s20
	s_add_u32 s18, s18, 0x80080
	s_addc_u32 s19, s19, 0
	s_add_u32 s49, s20, 0x100
	v_mov_b32_e32 v2, 0
	s_addc_u32 s58, s21, 0
	s_mov_b32 s59, -2
	v_mov_b32_e32 v3, v2
	v_mov_b32_e32 v4, v2
	v_mov_b32_e32 v5, v2
	v_mov_b32_e32 v10, v2
	v_mov_b32_e32 v11, v2
	v_mov_b32_e32 v12, v2
	v_mov_b32_e32 v13, v2
	v_mov_b32_e32 v18, v2
	v_mov_b32_e32 v19, v2
	v_mov_b32_e32 v20, v2
	v_mov_b32_e32 v21, v2
	v_mov_b32_e32 v26, v2
	v_mov_b32_e32 v27, v2
	v_mov_b32_e32 v28, v2
	v_mov_b32_e32 v29, v2
	v_mov_b32_e32 v34, v2
	v_mov_b32_e32 v35, v2
	v_mov_b32_e32 v36, v2
	v_mov_b32_e32 v37, v2
	v_mov_b32_e32 v42, v2
	v_mov_b32_e32 v43, v2
	v_mov_b32_e32 v44, v2
	v_mov_b32_e32 v45, v2
	v_mov_b32_e32 v50, v2
	v_mov_b32_e32 v51, v2
	v_mov_b32_e32 v52, v2
	v_mov_b32_e32 v53, v2
	v_mov_b32_e32 v58, v2
	v_mov_b32_e32 v59, v2
	v_mov_b32_e32 v60, v2
	v_mov_b32_e32 v61, v2
	v_mov_b32_e32 v6, v2
	v_mov_b32_e32 v7, v2
	v_mov_b32_e32 v8, v2
	v_mov_b32_e32 v9, v2
	v_mov_b32_e32 v14, v2
	v_mov_b32_e32 v15, v2
	v_mov_b32_e32 v16, v2
	v_mov_b32_e32 v17, v2
	v_mov_b32_e32 v22, v2
	v_mov_b32_e32 v23, v2
	v_mov_b32_e32 v24, v2
	v_mov_b32_e32 v25, v2
	v_mov_b32_e32 v30, v2
	v_mov_b32_e32 v31, v2
	v_mov_b32_e32 v32, v2
	v_mov_b32_e32 v33, v2
	v_mov_b32_e32 v38, v2
	v_mov_b32_e32 v39, v2
	v_mov_b32_e32 v40, v2
	v_mov_b32_e32 v41, v2
	v_mov_b32_e32 v46, v2
	v_mov_b32_e32 v47, v2
	v_mov_b32_e32 v48, v2
	v_mov_b32_e32 v49, v2
	v_mov_b32_e32 v54, v2
	v_mov_b32_e32 v55, v2
	v_mov_b32_e32 v56, v2
	v_mov_b32_e32 v57, v2
	v_mov_b32_e32 v62, v2
	v_mov_b32_e32 v63, v2
	v_mov_b32_e32 v64, v2
	v_mov_b32_e32 v65, v2
	v_mov_b32_e32 v66, v2
	v_mov_b32_e32 v67, v2
	v_mov_b32_e32 v68, v2
	v_mov_b32_e32 v69, v2
	v_mov_b32_e32 v74, v2
	v_mov_b32_e32 v75, v2
	v_mov_b32_e32 v76, v2
	v_mov_b32_e32 v77, v2
	v_mov_b32_e32 v82, v2
	v_mov_b32_e32 v83, v2
	v_mov_b32_e32 v84, v2
	v_mov_b32_e32 v85, v2
	v_mov_b32_e32 v90, v2
	v_mov_b32_e32 v91, v2
	v_mov_b32_e32 v92, v2
	v_mov_b32_e32 v93, v2
	v_mov_b32_e32 v98, v2
	v_mov_b32_e32 v99, v2
	v_mov_b32_e32 v100, v2
	v_mov_b32_e32 v101, v2
	v_mov_b32_e32 v106, v2
	v_mov_b32_e32 v107, v2
	v_mov_b32_e32 v108, v2
	v_mov_b32_e32 v109, v2
	v_mov_b32_e32 v114, v2
	v_mov_b32_e32 v115, v2
	v_mov_b32_e32 v116, v2
	v_mov_b32_e32 v117, v2
	v_mov_b32_e32 v122, v2
	v_mov_b32_e32 v123, v2
	v_mov_b32_e32 v124, v2
	v_mov_b32_e32 v125, v2
	v_mov_b32_e32 v70, v2
	v_mov_b32_e32 v71, v2
	v_mov_b32_e32 v72, v2
	v_mov_b32_e32 v73, v2
	v_mov_b32_e32 v78, v2
	v_mov_b32_e32 v79, v2
	v_mov_b32_e32 v80, v2
	v_mov_b32_e32 v81, v2
	v_mov_b32_e32 v86, v2
	v_mov_b32_e32 v87, v2
	v_mov_b32_e32 v88, v2
	v_mov_b32_e32 v89, v2
	v_mov_b32_e32 v94, v2
	v_mov_b32_e32 v95, v2
	v_mov_b32_e32 v96, v2
	v_mov_b32_e32 v97, v2
	v_mov_b32_e32 v102, v2
	v_mov_b32_e32 v103, v2
	v_mov_b32_e32 v104, v2
	v_mov_b32_e32 v105, v2
	v_mov_b32_e32 v110, v2
	v_mov_b32_e32 v111, v2
	v_mov_b32_e32 v112, v2
	v_mov_b32_e32 v113, v2
	v_mov_b32_e32 v118, v2
	v_mov_b32_e32 v119, v2
	v_mov_b32_e32 v120, v2
	v_mov_b32_e32 v121, v2
	v_mov_b32_e32 v126, v2
	v_mov_b32_e32 v127, v2
	v_mov_b32_e32 v128, v2
	v_mov_b32_e32 v129, v2
	s_add_u32 s0, s18, 0xfff80080
	s_addc_u32 s1, s19, -1
	s_add_i32 s33, 0, 0x10000
	s_cmp_eq_u32 s59, 28
	s_cselect_b32 s23, s11, s1
	s_cselect_b32 s22, s38, s0
	v_add_u32_e32 v140, s33, v143
	s_cselect_b32 s21, s9, s58
	s_cselect_b32 s20, s39, s49
	s_add_i32 s55, 0, 0x14000
.LBB0_837:
	ds_read_b128 v[146:149], v140
	ds_read_b128 v[150:153], v140 offset:1024
	ds_read_b128 v[154:157], v140 offset:2048
	ds_read_b128 v[158:161], v140 offset:3072
	v_add_u32_e32 v140, s55, v143
	ds_read_b128 v[162:165], v140
	ds_read_b128 v[166:169], v140 offset:1024
	ds_read_b128 v[170:173], v140 offset:2048
	ds_read_b128 v[174:177], v140 offset:3072
	v_lshl_add_u64 v[140:141], s[18:19], 0, v[136:137]
	s_add_i32 m0, s27, 0xc000
	ds_read_b128 v[178:181], v145
	ds_read_b128 v[182:185], v145 offset:1024
	ds_read_b128 v[186:189], v145 offset:2048
	ds_read_b128 v[190:193], v145 offset:3072
	ds_read_b128 v[194:197], v145 offset:4096
	ds_read_b128 v[198:201], v145 offset:5120
	ds_read_b128 v[208:211], v145 offset:6144
	ds_read_b128 v[212:215], v145 offset:7168
	global_load_lds_dwordx4 v[140:141], off
	v_lshl_add_u64 v[140:141], s[18:19], 0, v[138:139]
	s_add_i32 m0, s27, 0xe000
	s_nop 0
	global_load_lds_dwordx4 v[140:141], off
	s_waitcnt vmcnt(8)
	s_waitcnt lgkmcnt(0)
	s_barrier
	s_setprio 1
	s_waitcnt lgkmcnt(0)
	v_mfma_f32_16x16x32_bf16 v[126:129], v[146:149], v[178:181], v[126:129]
	v_mfma_f32_16x16x32_bf16 v[118:121], v[154:157], v[178:181], v[118:121]
	v_mfma_f32_16x16x32_bf16 v[110:113], v[146:149], v[186:189], v[110:113]
	v_mfma_f32_16x16x32_bf16 v[102:105], v[154:157], v[186:189], v[102:105]
	v_mfma_f32_16x16x32_bf16 v[94:97], v[146:149], v[194:197], v[94:97]
	v_mfma_f32_16x16x32_bf16 v[86:89], v[154:157], v[194:197], v[86:89]
	v_mfma_f32_16x16x32_bf16 v[78:81], v[146:149], v[208:211], v[78:81]
	v_mfma_f32_16x16x32_bf16 v[70:73], v[154:157], v[208:211], v[70:73]
	v_mfma_f32_16x16x32_bf16 v[126:129], v[150:153], v[182:185], v[126:129]
	v_mfma_f32_16x16x32_bf16 v[118:121], v[158:161], v[182:185], v[118:121]
	v_mfma_f32_16x16x32_bf16 v[110:113], v[150:153], v[190:193], v[110:113]
	v_mfma_f32_16x16x32_bf16 v[102:105], v[158:161], v[190:193], v[102:105]
	v_mfma_f32_16x16x32_bf16 v[94:97], v[150:153], v[198:201], v[94:97]
	v_mfma_f32_16x16x32_bf16 v[86:89], v[158:161], v[198:201], v[86:89]
	v_mfma_f32_16x16x32_bf16 v[78:81], v[150:153], v[212:215], v[78:81]
	v_mfma_f32_16x16x32_bf16 v[70:73], v[158:161], v[212:215], v[70:73]
	s_setprio 0
	s_setprio 1
	v_mfma_f32_16x16x32_bf16 v[122:125], v[162:165], v[178:181], v[122:125]
	v_mfma_f32_16x16x32_bf16 v[114:117], v[170:173], v[178:181], v[114:117]
	v_mfma_f32_16x16x32_bf16 v[106:109], v[162:165], v[186:189], v[106:109]
	v_mfma_f32_16x16x32_bf16 v[98:101], v[170:173], v[186:189], v[98:101]
	v_mfma_f32_16x16x32_bf16 v[90:93], v[162:165], v[194:197], v[90:93]
	v_mfma_f32_16x16x32_bf16 v[82:85], v[170:173], v[194:197], v[82:85]
	v_mfma_f32_16x16x32_bf16 v[74:77], v[162:165], v[208:211], v[74:77]
	v_mfma_f32_16x16x32_bf16 v[66:69], v[170:173], v[208:211], v[66:69]
	v_mfma_f32_16x16x32_bf16 v[122:125], v[166:169], v[182:185], v[122:125]
	v_mfma_f32_16x16x32_bf16 v[114:117], v[174:177], v[182:185], v[114:117]
	v_mfma_f32_16x16x32_bf16 v[106:109], v[166:169], v[190:193], v[106:109]
	v_mfma_f32_16x16x32_bf16 v[98:101], v[174:177], v[190:193], v[98:101]
	v_mfma_f32_16x16x32_bf16 v[90:93], v[166:169], v[198:201], v[90:93]
	v_mfma_f32_16x16x32_bf16 v[82:85], v[174:177], v[198:201], v[82:85]
	v_mfma_f32_16x16x32_bf16 v[74:77], v[166:169], v[212:215], v[74:77]
	v_mfma_f32_16x16x32_bf16 v[66:69], v[174:177], v[212:215], v[66:69]
	s_setprio 0
	s_barrier
	s_add_i32 s0, s33, s26
	v_lshl_add_u64 v[140:141], s[20:21], 0, v[202:203]
	s_mov_b32 m0, s0
	ds_read_b128 v[178:181], v145 offset:16384
	ds_read_b128 v[182:185], v145 offset:17408
	ds_read_b128 v[186:189], v145 offset:18432
	ds_read_b128 v[190:193], v145 offset:19456
	ds_read_b128 v[194:197], v145 offset:20480
	ds_read_b128 v[198:201], v145 offset:21504
	ds_read_b128 v[208:211], v145 offset:22528
	ds_read_b128 v[212:215], v145 offset:23552
	global_load_lds_dwordx4 v[140:141], off
	s_add_i32 m0, s0, 0x2000
	s_add_u32 s0, s20, 0x80000
	v_lshl_add_u64 v[204:205], s[20:21], 0, v[130:131]
	s_addc_u32 s1, s21, 0
	s_add_i32 s33, s55, s26
	global_load_lds_dwordx4 v[204:205], off
	v_lshl_add_u64 v[206:207], s[0:1], 0, v[202:203]
	s_mov_b32 m0, s33
	v_lshl_add_u64 v[216:217], s[22:23], 0, v[132:133]
	global_load_lds_dwordx4 v[206:207], off
	v_lshl_add_u64 v[206:207], s[0:1], 0, v[130:131]
	s_add_i32 m0, s33, 0x2000
	s_nop 0
	global_load_lds_dwordx4 v[206:207], off
	v_lshl_add_u64 v[206:207], s[22:23], 0, v[134:135]
	s_mov_b32 m0, s27
	s_nop 0
	global_load_lds_dwordx4 v[206:207], off
	s_mov_b32 m0, s28
	s_nop 0
	global_load_lds_dwordx4 v[216:217], off
	s_waitcnt vmcnt(8)
	s_waitcnt lgkmcnt(0)
	s_barrier
	s_setprio 1
	s_waitcnt lgkmcnt(0)
	v_mfma_f32_16x16x32_bf16 v[62:65], v[146:149], v[178:181], v[62:65]
	v_mfma_f32_16x16x32_bf16 v[54:57], v[154:157], v[178:181], v[54:57]
	v_mfma_f32_16x16x32_bf16 v[46:49], v[146:149], v[186:189], v[46:49]
	v_mfma_f32_16x16x32_bf16 v[38:41], v[154:157], v[186:189], v[38:41]
	v_mfma_f32_16x16x32_bf16 v[30:33], v[146:149], v[194:197], v[30:33]
	v_mfma_f32_16x16x32_bf16 v[22:25], v[154:157], v[194:197], v[22:25]
	v_mfma_f32_16x16x32_bf16 v[14:17], v[146:149], v[208:211], v[14:17]
	v_mfma_f32_16x16x32_bf16 v[6:9], v[154:157], v[208:211], v[6:9]
	v_mfma_f32_16x16x32_bf16 v[62:65], v[150:153], v[182:185], v[62:65]
	v_mfma_f32_16x16x32_bf16 v[54:57], v[158:161], v[182:185], v[54:57]
	v_mfma_f32_16x16x32_bf16 v[46:49], v[150:153], v[190:193], v[46:49]
	v_mfma_f32_16x16x32_bf16 v[38:41], v[158:161], v[190:193], v[38:41]
	v_mfma_f32_16x16x32_bf16 v[30:33], v[150:153], v[198:201], v[30:33]
	v_mfma_f32_16x16x32_bf16 v[22:25], v[158:161], v[198:201], v[22:25]
	v_mfma_f32_16x16x32_bf16 v[14:17], v[150:153], v[212:215], v[14:17]
	v_mfma_f32_16x16x32_bf16 v[6:9], v[158:161], v[212:215], v[6:9]
	s_setprio 0
	s_setprio 1
	v_mfma_f32_16x16x32_bf16 v[58:61], v[162:165], v[178:181], v[58:61]
	v_mfma_f32_16x16x32_bf16 v[50:53], v[170:173], v[178:181], v[50:53]
	v_mfma_f32_16x16x32_bf16 v[42:45], v[162:165], v[186:189], v[42:45]
	v_mfma_f32_16x16x32_bf16 v[34:37], v[170:173], v[186:189], v[34:37]
	v_mfma_f32_16x16x32_bf16 v[26:29], v[162:165], v[194:197], v[26:29]
	v_mfma_f32_16x16x32_bf16 v[18:21], v[170:173], v[194:197], v[18:21]
	v_mfma_f32_16x16x32_bf16 v[10:13], v[162:165], v[208:211], v[10:13]
	v_mfma_f32_16x16x32_bf16 v[2:5], v[170:173], v[208:211], v[2:5]
	v_mfma_f32_16x16x32_bf16 v[58:61], v[166:169], v[182:185], v[58:61]
	v_mfma_f32_16x16x32_bf16 v[50:53], v[174:177], v[182:185], v[50:53]
	v_mfma_f32_16x16x32_bf16 v[42:45], v[166:169], v[190:193], v[42:45]
	v_mfma_f32_16x16x32_bf16 v[34:37], v[174:177], v[190:193], v[34:37]
	v_mfma_f32_16x16x32_bf16 v[26:29], v[166:169], v[198:201], v[26:29]
	v_mfma_f32_16x16x32_bf16 v[18:21], v[174:177], v[198:201], v[18:21]
	v_mfma_f32_16x16x32_bf16 v[10:13], v[166:169], v[212:215], v[10:13]
	v_mfma_f32_16x16x32_bf16 v[2:5], v[174:177], v[212:215], v[2:5]
	s_setprio 0
	s_barrier
	s_add_i32 s33, 0, 0x18000
	s_add_i32 s55, 0, 0x1c000
	v_add_u32_e32 v158, s33, v143
	v_add_u32_e32 v174, s55, v143
	ds_read_b128 v[146:149], v158
	ds_read_b128 v[150:153], v158 offset:1024
	ds_read_b128 v[154:157], v158 offset:2048
	ds_read_b128 v[158:161], v158 offset:3072
	ds_read_b128 v[162:165], v174
	ds_read_b128 v[166:169], v174 offset:1024
	ds_read_b128 v[170:173], v174 offset:2048
	ds_read_b128 v[174:177], v174 offset:3072
	s_add_u32 s0, s22, 0x80000
	s_addc_u32 s1, s23, 0
	s_mov_b32 m0, s29
	v_lshl_add_u64 v[218:219], s[0:1], 0, v[134:135]
	ds_read_b128 v[178:181], v145 offset:32768
	ds_read_b128 v[182:185], v145 offset:33792
	ds_read_b128 v[186:189], v145 offset:34816
	ds_read_b128 v[190:193], v145 offset:35840
	ds_read_b128 v[194:197], v145 offset:36864
	ds_read_b128 v[198:201], v145 offset:37888
	ds_read_b128 v[208:211], v145 offset:38912
	ds_read_b128 v[212:215], v145 offset:39936
	global_load_lds_dwordx4 v[218:219], off
	v_lshl_add_u64 v[218:219], s[0:1], 0, v[132:133]
	s_mov_b32 m0, s30
	s_nop 0
	global_load_lds_dwordx4 v[218:219], off
	s_waitcnt vmcnt(8)
	s_waitcnt lgkmcnt(0)
	s_barrier
	s_setprio 1
	s_waitcnt lgkmcnt(0)
	v_mfma_f32_16x16x32_bf16 v[126:129], v[146:149], v[178:181], v[126:129]
	v_mfma_f32_16x16x32_bf16 v[118:121], v[154:157], v[178:181], v[118:121]
	v_mfma_f32_16x16x32_bf16 v[110:113], v[146:149], v[186:189], v[110:113]
	v_mfma_f32_16x16x32_bf16 v[102:105], v[154:157], v[186:189], v[102:105]
	v_mfma_f32_16x16x32_bf16 v[94:97], v[146:149], v[194:197], v[94:97]
	v_mfma_f32_16x16x32_bf16 v[86:89], v[154:157], v[194:197], v[86:89]
	v_mfma_f32_16x16x32_bf16 v[78:81], v[146:149], v[208:211], v[78:81]
	v_mfma_f32_16x16x32_bf16 v[70:73], v[154:157], v[208:211], v[70:73]
	v_mfma_f32_16x16x32_bf16 v[126:129], v[150:153], v[182:185], v[126:129]
	v_mfma_f32_16x16x32_bf16 v[118:121], v[158:161], v[182:185], v[118:121]
	v_mfma_f32_16x16x32_bf16 v[110:113], v[150:153], v[190:193], v[110:113]
	v_mfma_f32_16x16x32_bf16 v[102:105], v[158:161], v[190:193], v[102:105]
	v_mfma_f32_16x16x32_bf16 v[94:97], v[150:153], v[198:201], v[94:97]
	v_mfma_f32_16x16x32_bf16 v[86:89], v[158:161], v[198:201], v[86:89]
	v_mfma_f32_16x16x32_bf16 v[78:81], v[150:153], v[212:215], v[78:81]
	v_mfma_f32_16x16x32_bf16 v[70:73], v[158:161], v[212:215], v[70:73]
	s_setprio 0
	s_setprio 1
	v_mfma_f32_16x16x32_bf16 v[122:125], v[162:165], v[178:181], v[122:125]
	v_mfma_f32_16x16x32_bf16 v[114:117], v[170:173], v[178:181], v[114:117]
	v_mfma_f32_16x16x32_bf16 v[106:109], v[162:165], v[186:189], v[106:109]
	v_mfma_f32_16x16x32_bf16 v[98:101], v[170:173], v[186:189], v[98:101]
	v_mfma_f32_16x16x32_bf16 v[90:93], v[162:165], v[194:197], v[90:93]
	v_mfma_f32_16x16x32_bf16 v[82:85], v[170:173], v[194:197], v[82:85]
	v_mfma_f32_16x16x32_bf16 v[74:77], v[162:165], v[208:211], v[74:77]
	v_mfma_f32_16x16x32_bf16 v[66:69], v[170:173], v[208:211], v[66:69]
	v_mfma_f32_16x16x32_bf16 v[122:125], v[166:169], v[182:185], v[122:125]
	v_mfma_f32_16x16x32_bf16 v[114:117], v[174:177], v[182:185], v[114:117]
	v_mfma_f32_16x16x32_bf16 v[106:109], v[166:169], v[190:193], v[106:109]
	v_mfma_f32_16x16x32_bf16 v[98:101], v[174:177], v[190:193], v[98:101]
	v_mfma_f32_16x16x32_bf16 v[90:93], v[166:169], v[198:201], v[90:93]
	v_mfma_f32_16x16x32_bf16 v[82:85], v[174:177], v[198:201], v[82:85]
	v_mfma_f32_16x16x32_bf16 v[74:77], v[166:169], v[212:215], v[74:77]
	v_mfma_f32_16x16x32_bf16 v[66:69], v[174:177], v[212:215], v[66:69]
	s_setprio 0
	s_barrier
	s_add_i32 s0, s33, s26
	v_lshl_add_u64 v[140:141], v[140:141], 0, s[80:81]
	s_mov_b32 m0, s0
	ds_read_b128 v[178:181], v145 offset:49152
	ds_read_b128 v[182:185], v145 offset:50176
	ds_read_b128 v[186:189], v145 offset:51200
	ds_read_b128 v[190:193], v145 offset:52224
	ds_read_b128 v[194:197], v145 offset:53248
	ds_read_b128 v[198:201], v145 offset:54272
	ds_read_b128 v[208:211], v145 offset:55296
	ds_read_b128 v[212:215], v145 offset:56320
	global_load_lds_dwordx4 v[140:141], off
	s_add_i32 m0, s0, 0x2000
	s_add_u32 s0, s20, 0x80080
	v_lshl_add_u64 v[140:141], v[204:205], 0, s[80:81]
	s_addc_u32 s1, s21, 0
	s_add_i32 s20, s55, s26
	global_load_lds_dwordx4 v[140:141], off
	v_lshl_add_u64 v[140:141], s[0:1], 0, v[202:203]
	s_mov_b32 m0, s20
	s_nop 0
	global_load_lds_dwordx4 v[140:141], off
	v_lshl_add_u64 v[140:141], s[0:1], 0, v[130:131]
	s_add_i32 m0, s20, 0x2000
	s_nop 0
	global_load_lds_dwordx4 v[140:141], off
	v_lshl_add_u64 v[140:141], v[206:207], 0, s[80:81]
	s_mov_b32 m0, s31
	s_nop 0
	global_load_lds_dwordx4 v[140:141], off
	v_lshl_add_u64 v[140:141], v[216:217], 0, s[80:81]
	s_mov_b32 m0, s34
	s_nop 0
	global_load_lds_dwordx4 v[140:141], off
	s_waitcnt vmcnt(8)
	s_waitcnt lgkmcnt(0)
	s_barrier
	s_setprio 1
	s_waitcnt lgkmcnt(0)
	v_mfma_f32_16x16x32_bf16 v[62:65], v[146:149], v[178:181], v[62:65]
	v_mfma_f32_16x16x32_bf16 v[54:57], v[154:157], v[178:181], v[54:57]
	v_mfma_f32_16x16x32_bf16 v[46:49], v[146:149], v[186:189], v[46:49]
	v_mfma_f32_16x16x32_bf16 v[38:41], v[154:157], v[186:189], v[38:41]
	v_mfma_f32_16x16x32_bf16 v[30:33], v[146:149], v[194:197], v[30:33]
	v_mfma_f32_16x16x32_bf16 v[22:25], v[154:157], v[194:197], v[22:25]
	v_mfma_f32_16x16x32_bf16 v[14:17], v[146:149], v[208:211], v[14:17]
	v_mfma_f32_16x16x32_bf16 v[6:9], v[154:157], v[208:211], v[6:9]
	v_mfma_f32_16x16x32_bf16 v[62:65], v[150:153], v[182:185], v[62:65]
	v_mfma_f32_16x16x32_bf16 v[54:57], v[158:161], v[182:185], v[54:57]
	v_mfma_f32_16x16x32_bf16 v[46:49], v[150:153], v[190:193], v[46:49]
	v_mfma_f32_16x16x32_bf16 v[38:41], v[158:161], v[190:193], v[38:41]
	v_mfma_f32_16x16x32_bf16 v[30:33], v[150:153], v[198:201], v[30:33]
	v_mfma_f32_16x16x32_bf16 v[22:25], v[158:161], v[198:201], v[22:25]
	v_mfma_f32_16x16x32_bf16 v[14:17], v[150:153], v[212:215], v[14:17]
	v_mfma_f32_16x16x32_bf16 v[6:9], v[158:161], v[212:215], v[6:9]
	s_setprio 0
	s_setprio 1
	v_mfma_f32_16x16x32_bf16 v[58:61], v[162:165], v[178:181], v[58:61]
	v_mfma_f32_16x16x32_bf16 v[50:53], v[170:173], v[178:181], v[50:53]
	v_mfma_f32_16x16x32_bf16 v[42:45], v[162:165], v[186:189], v[42:45]
	v_mfma_f32_16x16x32_bf16 v[34:37], v[170:173], v[186:189], v[34:37]
	v_mfma_f32_16x16x32_bf16 v[26:29], v[162:165], v[194:197], v[26:29]
	v_mfma_f32_16x16x32_bf16 v[18:21], v[170:173], v[194:197], v[18:21]
	v_mfma_f32_16x16x32_bf16 v[10:13], v[162:165], v[208:211], v[10:13]
	v_mfma_f32_16x16x32_bf16 v[2:5], v[170:173], v[208:211], v[2:5]
	v_mfma_f32_16x16x32_bf16 v[58:61], v[166:169], v[182:185], v[58:61]
	v_mfma_f32_16x16x32_bf16 v[50:53], v[174:177], v[182:185], v[50:53]
	v_mfma_f32_16x16x32_bf16 v[42:45], v[166:169], v[190:193], v[42:45]
	v_mfma_f32_16x16x32_bf16 v[34:37], v[174:177], v[190:193], v[34:37]
	v_mfma_f32_16x16x32_bf16 v[26:29], v[166:169], v[198:201], v[26:29]
	v_mfma_f32_16x16x32_bf16 v[18:21], v[174:177], v[198:201], v[18:21]
	v_mfma_f32_16x16x32_bf16 v[10:13], v[166:169], v[212:215], v[10:13]
	v_mfma_f32_16x16x32_bf16 v[2:5], v[174:177], v[212:215], v[2:5]
	s_setprio 0
	s_add_i32 s59, s59, 2
	s_add_u32 s18, s18, 0x100
	s_addc_u32 s19, s19, 0
	s_add_u32 s49, s49, 0x100
	s_addc_u32 s58, s58, 0
	s_cmp_gt_u32 s59, 29
	s_cbranch_scc1 .Lrot_exit_3
	s_add_u32 s0, s18, 0xfff80080
	s_addc_u32 s1, s19, -1
	s_add_i32 s33, 0, 0x10000
	s_cmp_eq_u32 s59, 28
	s_cselect_b32 s23, s11, s1
	s_cselect_b32 s22, s38, s0
	v_add_u32_e32 v140, s33, v143
	s_cselect_b32 s21, s9, s58
	s_cselect_b32 s20, s39, s49
	s_add_i32 s55, 0, 0x14000
	s_barrier
	s_branch .LBB0_837

.LBB0_969:
	s_add_u32 s49, s16, 0x100
	v_mov_b32_e32 v2, 0
	s_addc_u32 s58, s17, 0
	s_mov_b32 s59, -2
	v_mov_b32_e32 v3, v2
	v_mov_b32_e32 v4, v2
	v_mov_b32_e32 v5, v2
	v_mov_b32_e32 v6, v2
	v_mov_b32_e32 v7, v2
	v_mov_b32_e32 v8, v2
	v_mov_b32_e32 v9, v2
	v_mov_b32_e32 v18, v2
	v_mov_b32_e32 v19, v2
	v_mov_b32_e32 v20, v2
	v_mov_b32_e32 v21, v2
	v_mov_b32_e32 v22, v2
	v_mov_b32_e32 v23, v2
	v_mov_b32_e32 v24, v2
	v_mov_b32_e32 v25, v2
	v_mov_b32_e32 v34, v2
	v_mov_b32_e32 v35, v2
	v_mov_b32_e32 v36, v2
	v_mov_b32_e32 v37, v2
	v_mov_b32_e32 v38, v2
	v_mov_b32_e32 v39, v2
	v_mov_b32_e32 v40, v2
	v_mov_b32_e32 v41, v2
	v_mov_b32_e32 v50, v2
	v_mov_b32_e32 v51, v2
	v_mov_b32_e32 v52, v2
	v_mov_b32_e32 v53, v2
	v_mov_b32_e32 v54, v2
	v_mov_b32_e32 v55, v2
	v_mov_b32_e32 v56, v2
	v_mov_b32_e32 v57, v2
	v_mov_b32_e32 v10, v2
	v_mov_b32_e32 v11, v2
	v_mov_b32_e32 v12, v2
	v_mov_b32_e32 v13, v2
	v_mov_b32_e32 v14, v2
	v_mov_b32_e32 v15, v2
	v_mov_b32_e32 v16, v2
	v_mov_b32_e32 v17, v2
	v_mov_b32_e32 v26, v2
	v_mov_b32_e32 v27, v2
	v_mov_b32_e32 v28, v2
	v_mov_b32_e32 v29, v2
	v_mov_b32_e32 v30, v2
	v_mov_b32_e32 v31, v2
	v_mov_b32_e32 v32, v2
	v_mov_b32_e32 v33, v2
	v_mov_b32_e32 v42, v2
	v_mov_b32_e32 v43, v2
	v_mov_b32_e32 v44, v2
	v_mov_b32_e32 v45, v2
	v_mov_b32_e32 v46, v2
	v_mov_b32_e32 v47, v2
	v_mov_b32_e32 v48, v2
	v_mov_b32_e32 v49, v2
	v_mov_b32_e32 v58, v2
	v_mov_b32_e32 v59, v2
	v_mov_b32_e32 v60, v2
	v_mov_b32_e32 v61, v2
	v_mov_b32_e32 v62, v2
	v_mov_b32_e32 v63, v2
	v_mov_b32_e32 v64, v2
	v_mov_b32_e32 v65, v2
	v_mov_b32_e32 v66, v2
	v_mov_b32_e32 v67, v2
	v_mov_b32_e32 v68, v2
	v_mov_b32_e32 v69, v2
	v_mov_b32_e32 v70, v2
	v_mov_b32_e32 v71, v2
	v_mov_b32_e32 v72, v2
	v_mov_b32_e32 v73, v2
	v_mov_b32_e32 v90, v2
	v_mov_b32_e32 v91, v2
	v_mov_b32_e32 v92, v2
	v_mov_b32_e32 v93, v2
	v_mov_b32_e32 v102, v2
	v_mov_b32_e32 v103, v2
	v_mov_b32_e32 v104, v2
	v_mov_b32_e32 v105, v2
	v_mov_b32_e32 v122, v2
	v_mov_b32_e32 v123, v2
	v_mov_b32_e32 v124, v2
	v_mov_b32_e32 v125, v2
	v_mov_b32_e32 v130, v2
	v_mov_b32_e32 v131, v2
	v_mov_b32_e32 v132, v2
	v_mov_b32_e32 v133, v2
	v_mov_b32_e32 v150, v2
	v_mov_b32_e32 v151, v2
	v_mov_b32_e32 v152, v2
	v_mov_b32_e32 v153, v2
	v_mov_b32_e32 v154, v2
	v_mov_b32_e32 v155, v2
	v_mov_b32_e32 v156, v2
	v_mov_b32_e32 v157, v2
	v_mov_b32_e32 v74, v2
	v_mov_b32_e32 v75, v2
	v_mov_b32_e32 v76, v2
	v_mov_b32_e32 v77, v2
	v_mov_b32_e32 v86, v2
	v_mov_b32_e32 v87, v2
	v_mov_b32_e32 v88, v2
	v_mov_b32_e32 v89, v2
	v_mov_b32_e32 v114, v2
	v_mov_b32_e32 v115, v2
	v_mov_b32_e32 v116, v2
	v_mov_b32_e32 v117, v2
	v_mov_b32_e32 v118, v2
	v_mov_b32_e32 v119, v2
	v_mov_b32_e32 v120, v2
	v_mov_b32_e32 v121, v2
	v_mov_b32_e32 v138, v2
	v_mov_b32_e32 v139, v2
	v_mov_b32_e32 v140, v2
	v_mov_b32_e32 v141, v2
	v_mov_b32_e32 v142, v2
	v_mov_b32_e32 v143, v2
	v_mov_b32_e32 v144, v2
	v_mov_b32_e32 v145, v2
	v_mov_b32_e32 v162, v2
	v_mov_b32_e32 v163, v2
	v_mov_b32_e32 v164, v2
	v_mov_b32_e32 v165, v2
	v_mov_b32_e32 v170, v2
	v_mov_b32_e32 v171, v2
	v_mov_b32_e32 v172, v2
	v_mov_b32_e32 v173, v2
	s_add_u32 s16, s2, 0x100
	s_addc_u32 s17, s3, 0
	s_add_i32 s0, 0, 0x10000
	s_cmpk_eq_i32 s59, 0x54
	s_cselect_b32 s21, s7, s17
	s_cselect_b32 s20, s6, s16
	s_cselect_b32 s19, s15, s58
	s_cselect_b32 s18, s14, s49
	s_add_i32 s33, 0, 0x14000
	v_add_u32_e32 v98, s0, v205
	v_add_u32_e32 v134, s33, v205
.LBB0_970:
	ds_read_b128 v[78:81], v98
	ds_read_b128 v[82:85], v98 offset:1024
	ds_read_b128 v[94:97], v98 offset:2048
	ds_read_b128 v[98:101], v98 offset:3072
	ds_read_b128 v[106:109], v134
	ds_read_b128 v[110:113], v134 offset:1024
	ds_read_b128 v[126:129], v134 offset:2048
	ds_read_b128 v[134:137], v134 offset:3072
	v_lshl_add_u64 v[194:195], s[2:3], 0, v[214:215]
	s_add_i32 m0, s25, 0xc000
	ds_read_b128 v[146:149], v239
	ds_read_b128 v[158:161], v239 offset:1024
	ds_read_b128 v[166:169], v239 offset:2048
	ds_read_b128 v[174:177], v239 offset:3072
	ds_read_b128 v[178:181], v239 offset:4096
	ds_read_b128 v[182:185], v239 offset:5120
	ds_read_b128 v[186:189], v239 offset:6144
	ds_read_b128 v[190:193], v239 offset:7168
	global_load_lds_dwordx4 v[194:195], off
	v_lshl_add_u64 v[194:195], s[2:3], 0, v[216:217]
	s_add_i32 m0, s25, 0xe000
	s_nop 0
	global_load_lds_dwordx4 v[194:195], off
	s_waitcnt vmcnt(8)
	s_waitcnt lgkmcnt(0)
	s_barrier
	s_setprio 1
	s_waitcnt lgkmcnt(0)
	v_mfma_f32_16x16x32_bf16 v[170:173], v[78:81], v[146:149], v[170:173]
	v_mfma_f32_16x16x32_bf16 v[162:165], v[94:97], v[146:149], v[162:165]
	v_mfma_f32_16x16x32_bf16 v[142:145], v[78:81], v[166:169], v[142:145]
	v_mfma_f32_16x16x32_bf16 v[138:141], v[94:97], v[166:169], v[138:141]
	v_mfma_f32_16x16x32_bf16 v[118:121], v[78:81], v[178:181], v[118:121]
	v_mfma_f32_16x16x32_bf16 v[114:117], v[94:97], v[178:181], v[114:117]
	v_mfma_f32_16x16x32_bf16 v[86:89], v[78:81], v[186:189], v[86:89]
	v_mfma_f32_16x16x32_bf16 v[74:77], v[94:97], v[186:189], v[74:77]
	v_mfma_f32_16x16x32_bf16 v[170:173], v[82:85], v[158:161], v[170:173]
	v_mfma_f32_16x16x32_bf16 v[162:165], v[98:101], v[158:161], v[162:165]
	v_mfma_f32_16x16x32_bf16 v[142:145], v[82:85], v[174:177], v[142:145]
	v_mfma_f32_16x16x32_bf16 v[138:141], v[98:101], v[174:177], v[138:141]
	v_mfma_f32_16x16x32_bf16 v[118:121], v[82:85], v[182:185], v[118:121]
	v_mfma_f32_16x16x32_bf16 v[114:117], v[98:101], v[182:185], v[114:117]
	v_mfma_f32_16x16x32_bf16 v[86:89], v[82:85], v[190:193], v[86:89]
	v_mfma_f32_16x16x32_bf16 v[74:77], v[98:101], v[190:193], v[74:77]
	s_setprio 0
	s_setprio 1
	v_mfma_f32_16x16x32_bf16 v[154:157], v[106:109], v[146:149], v[154:157]
	v_mfma_f32_16x16x32_bf16 v[130:133], v[106:109], v[166:169], v[130:133]
	v_mfma_f32_16x16x32_bf16 v[122:125], v[126:129], v[166:169], v[122:125]
	v_mfma_f32_16x16x32_bf16 v[102:105], v[106:109], v[178:181], v[102:105]
	v_mfma_f32_16x16x32_bf16 v[90:93], v[126:129], v[178:181], v[90:93]
	v_mfma_f32_16x16x32_bf16 v[70:73], v[106:109], v[186:189], v[70:73]
	v_mfma_f32_16x16x32_bf16 v[66:69], v[126:129], v[186:189], v[66:69]
	v_mfma_f32_16x16x32_bf16 v[154:157], v[110:113], v[158:161], v[154:157]
	v_mfma_f32_16x16x32_bf16 v[146:149], v[126:129], v[146:149], v[150:153]
	v_mfma_f32_16x16x32_bf16 v[130:133], v[110:113], v[174:177], v[130:133]
	v_mfma_f32_16x16x32_bf16 v[122:125], v[134:137], v[174:177], v[122:125]
	v_mfma_f32_16x16x32_bf16 v[102:105], v[110:113], v[182:185], v[102:105]
	v_mfma_f32_16x16x32_bf16 v[90:93], v[134:137], v[182:185], v[90:93]
	v_mfma_f32_16x16x32_bf16 v[70:73], v[110:113], v[190:193], v[70:73]
	v_mfma_f32_16x16x32_bf16 v[66:69], v[134:137], v[190:193], v[66:69]
	v_mfma_f32_16x16x32_bf16 v[146:149], v[134:137], v[158:161], v[146:149]
	s_setprio 0
	s_barrier
	s_add_i32 s0, s0, s24
	v_lshl_add_u64 v[194:195], s[18:19], 0, v[202:203]
	s_mov_b32 m0, s0
	ds_read_b128 v[150:153], v239 offset:16384
	ds_read_b128 v[158:161], v239 offset:17408
	ds_read_b128 v[166:169], v239 offset:18432
	ds_read_b128 v[174:177], v239 offset:19456
	ds_read_b128 v[178:181], v239 offset:20480
	ds_read_b128 v[182:185], v239 offset:21504
	ds_read_b128 v[186:189], v239 offset:22528
	ds_read_b128 v[190:193], v239 offset:23552
	global_load_lds_dwordx4 v[194:195], off
	s_add_i32 m0, s0, 0x2000
	s_add_u32 s0, s18, 0x160000
	v_lshl_add_u64 v[196:197], s[18:19], 0, v[208:209]
	s_addc_u32 s1, s19, 0
	s_add_i32 s2, s33, s24
	global_load_lds_dwordx4 v[196:197], off
	v_lshl_add_u64 v[198:199], s[0:1], 0, v[202:203]
	s_mov_b32 m0, s2
	v_lshl_add_u64 v[200:201], s[20:21], 0, v[210:211]
	global_load_lds_dwordx4 v[198:199], off
	v_lshl_add_u64 v[198:199], s[0:1], 0, v[208:209]
	s_add_i32 m0, s2, 0x2000
	s_nop 0
	global_load_lds_dwordx4 v[198:199], off
	v_lshl_add_u64 v[198:199], s[20:21], 0, v[212:213]
	s_mov_b32 m0, s25
	s_nop 0
	global_load_lds_dwordx4 v[198:199], off
	s_mov_b32 m0, s26
	s_nop 0
	global_load_lds_dwordx4 v[200:201], off
	s_waitcnt vmcnt(8)
	s_waitcnt lgkmcnt(0)
	s_barrier
	s_setprio 1
	s_waitcnt lgkmcnt(0)
	v_mfma_f32_16x16x32_bf16 v[62:65], v[78:81], v[150:153], v[62:65]
	v_mfma_f32_16x16x32_bf16 v[58:61], v[94:97], v[150:153], v[58:61]
	v_mfma_f32_16x16x32_bf16 v[46:49], v[78:81], v[166:169], v[46:49]
	v_mfma_f32_16x16x32_bf16 v[42:45], v[94:97], v[166:169], v[42:45]
	v_mfma_f32_16x16x32_bf16 v[30:33], v[78:81], v[178:181], v[30:33]
	v_mfma_f32_16x16x32_bf16 v[26:29], v[94:97], v[178:181], v[26:29]
	v_mfma_f32_16x16x32_bf16 v[14:17], v[78:81], v[186:189], v[14:17]
	v_mfma_f32_16x16x32_bf16 v[10:13], v[94:97], v[186:189], v[10:13]
	v_mfma_f32_16x16x32_bf16 v[62:65], v[82:85], v[158:161], v[62:65]
	v_mfma_f32_16x16x32_bf16 v[58:61], v[98:101], v[158:161], v[58:61]
	v_mfma_f32_16x16x32_bf16 v[46:49], v[82:85], v[174:177], v[46:49]
	v_mfma_f32_16x16x32_bf16 v[42:45], v[98:101], v[174:177], v[42:45]
	v_mfma_f32_16x16x32_bf16 v[30:33], v[82:85], v[182:185], v[30:33]
	v_mfma_f32_16x16x32_bf16 v[26:29], v[98:101], v[182:185], v[26:29]
	v_mfma_f32_16x16x32_bf16 v[14:17], v[82:85], v[190:193], v[14:17]
	v_mfma_f32_16x16x32_bf16 v[10:13], v[98:101], v[190:193], v[10:13]
	s_setprio 0
	s_setprio 1
	v_mfma_f32_16x16x32_bf16 v[54:57], v[106:109], v[150:153], v[54:57]
	v_mfma_f32_16x16x32_bf16 v[50:53], v[126:129], v[150:153], v[50:53]
	v_mfma_f32_16x16x32_bf16 v[38:41], v[106:109], v[166:169], v[38:41]
	v_mfma_f32_16x16x32_bf16 v[34:37], v[126:129], v[166:169], v[34:37]
	v_mfma_f32_16x16x32_bf16 v[22:25], v[106:109], v[178:181], v[22:25]
	v_mfma_f32_16x16x32_bf16 v[18:21], v[126:129], v[178:181], v[18:21]
	v_mfma_f32_16x16x32_bf16 v[6:9], v[106:109], v[186:189], v[6:9]
	v_mfma_f32_16x16x32_bf16 v[2:5], v[126:129], v[186:189], v[2:5]
	v_mfma_f32_16x16x32_bf16 v[54:57], v[110:113], v[158:161], v[54:57]
	v_mfma_f32_16x16x32_bf16 v[50:53], v[134:137], v[158:161], v[50:53]
	v_mfma_f32_16x16x32_bf16 v[38:41], v[110:113], v[174:177], v[38:41]
	v_mfma_f32_16x16x32_bf16 v[34:37], v[134:137], v[174:177], v[34:37]
	v_mfma_f32_16x16x32_bf16 v[22:25], v[110:113], v[182:185], v[22:25]
	v_mfma_f32_16x16x32_bf16 v[18:21], v[134:137], v[182:185], v[18:21]
	v_mfma_f32_16x16x32_bf16 v[6:9], v[110:113], v[190:193], v[6:9]
	v_mfma_f32_16x16x32_bf16 v[2:5], v[134:137], v[190:193], v[2:5]
	s_setprio 0
	s_barrier
	s_add_i32 s2, 0, 0x18000
	s_add_i32 s3, 0, 0x1c000
	v_add_u32_e32 v98, s2, v205
	v_add_u32_e32 v134, s3, v205
	ds_read_b128 v[78:81], v98
	ds_read_b128 v[82:85], v98 offset:1024
	ds_read_b128 v[94:97], v98 offset:2048
	ds_read_b128 v[98:101], v98 offset:3072
	ds_read_b128 v[106:109], v134
	ds_read_b128 v[110:113], v134 offset:1024
	ds_read_b128 v[126:129], v134 offset:2048
	ds_read_b128 v[134:137], v134 offset:3072
	s_add_u32 s0, s20, 0x160000
	s_addc_u32 s1, s21, 0
	s_mov_b32 m0, s27
	v_lshl_add_u64 v[206:207], s[0:1], 0, v[212:213]
	ds_read_b128 v[150:153], v239 offset:32768
	ds_read_b128 v[158:161], v239 offset:33792
	ds_read_b128 v[166:169], v239 offset:34816
	ds_read_b128 v[174:177], v239 offset:35840
	ds_read_b128 v[178:181], v239 offset:36864
	ds_read_b128 v[182:185], v239 offset:37888
	ds_read_b128 v[186:189], v239 offset:38912
	ds_read_b128 v[190:193], v239 offset:39936
	global_load_lds_dwordx4 v[206:207], off
	v_lshl_add_u64 v[206:207], s[0:1], 0, v[210:211]
	s_mov_b32 m0, s28
	s_nop 0
	global_load_lds_dwordx4 v[206:207], off
	s_waitcnt vmcnt(8)
	s_waitcnt lgkmcnt(0)
	s_barrier
	s_setprio 1
	s_waitcnt lgkmcnt(0)
	v_mfma_f32_16x16x32_bf16 v[170:173], v[78:81], v[150:153], v[170:173]
	v_mfma_f32_16x16x32_bf16 v[162:165], v[94:97], v[150:153], v[162:165]
	v_mfma_f32_16x16x32_bf16 v[142:145], v[78:81], v[166:169], v[142:145]
	v_mfma_f32_16x16x32_bf16 v[138:141], v[94:97], v[166:169], v[138:141]
	v_mfma_f32_16x16x32_bf16 v[118:121], v[78:81], v[178:181], v[118:121]
	v_mfma_f32_16x16x32_bf16 v[114:117], v[94:97], v[178:181], v[114:117]
	v_mfma_f32_16x16x32_bf16 v[86:89], v[78:81], v[186:189], v[86:89]
	v_mfma_f32_16x16x32_bf16 v[74:77], v[94:97], v[186:189], v[74:77]
	v_mfma_f32_16x16x32_bf16 v[170:173], v[82:85], v[158:161], v[170:173]
	v_mfma_f32_16x16x32_bf16 v[162:165], v[98:101], v[158:161], v[162:165]
	v_mfma_f32_16x16x32_bf16 v[142:145], v[82:85], v[174:177], v[142:145]
	v_mfma_f32_16x16x32_bf16 v[138:141], v[98:101], v[174:177], v[138:141]
	v_mfma_f32_16x16x32_bf16 v[118:121], v[82:85], v[182:185], v[118:121]
	v_mfma_f32_16x16x32_bf16 v[114:117], v[98:101], v[182:185], v[114:117]
	v_mfma_f32_16x16x32_bf16 v[86:89], v[82:85], v[190:193], v[86:89]
	v_mfma_f32_16x16x32_bf16 v[74:77], v[98:101], v[190:193], v[74:77]
	s_setprio 0
	s_setprio 1
	v_mfma_f32_16x16x32_bf16 v[154:157], v[106:109], v[150:153], v[154:157]
	v_mfma_f32_16x16x32_bf16 v[146:149], v[126:129], v[150:153], v[146:149]
	v_mfma_f32_16x16x32_bf16 v[130:133], v[106:109], v[166:169], v[130:133]
	v_mfma_f32_16x16x32_bf16 v[122:125], v[126:129], v[166:169], v[122:125]
	v_mfma_f32_16x16x32_bf16 v[102:105], v[106:109], v[178:181], v[102:105]
	v_mfma_f32_16x16x32_bf16 v[90:93], v[126:129], v[178:181], v[90:93]
	v_mfma_f32_16x16x32_bf16 v[70:73], v[106:109], v[186:189], v[70:73]
	v_mfma_f32_16x16x32_bf16 v[66:69], v[126:129], v[186:189], v[66:69]
	v_mfma_f32_16x16x32_bf16 v[154:157], v[110:113], v[158:161], v[154:157]
	v_mfma_f32_16x16x32_bf16 v[150:153], v[134:137], v[158:161], v[146:149]
	v_mfma_f32_16x16x32_bf16 v[130:133], v[110:113], v[174:177], v[130:133]
	v_mfma_f32_16x16x32_bf16 v[122:125], v[134:137], v[174:177], v[122:125]
	v_mfma_f32_16x16x32_bf16 v[102:105], v[110:113], v[182:185], v[102:105]
	v_mfma_f32_16x16x32_bf16 v[90:93], v[134:137], v[182:185], v[90:93]
	v_mfma_f32_16x16x32_bf16 v[70:73], v[110:113], v[190:193], v[70:73]
	v_mfma_f32_16x16x32_bf16 v[66:69], v[134:137], v[190:193], v[66:69]
	s_setprio 0
	s_barrier
	s_add_i32 s0, s2, s24
	v_lshl_add_u64 v[194:195], v[194:195], 0, s[80:81]
	s_mov_b32 m0, s0
	ds_read_b128 v[146:149], v239 offset:49152
	ds_read_b128 v[158:161], v239 offset:50176
	ds_read_b128 v[166:169], v239 offset:51200
	ds_read_b128 v[174:177], v239 offset:52224
	ds_read_b128 v[178:181], v239 offset:53248
	ds_read_b128 v[182:185], v239 offset:54272
	ds_read_b128 v[186:189], v239 offset:55296
	ds_read_b128 v[190:193], v239 offset:56320
	global_load_lds_dwordx4 v[194:195], off
	s_add_i32 m0, s0, 0x2000
	s_add_u32 s0, s18, 0x160080
	v_lshl_add_u64 v[194:195], v[196:197], 0, s[80:81]
	s_addc_u32 s1, s19, 0
	s_add_i32 s2, s3, s24
	global_load_lds_dwordx4 v[194:195], off
	v_lshl_add_u64 v[194:195], s[0:1], 0, v[202:203]
	s_mov_b32 m0, s2
	s_nop 0
	global_load_lds_dwordx4 v[194:195], off
	v_lshl_add_u64 v[194:195], s[0:1], 0, v[208:209]
	s_add_i32 m0, s2, 0x2000
	s_nop 0
	global_load_lds_dwordx4 v[194:195], off
	v_lshl_add_u64 v[194:195], v[198:199], 0, s[80:81]
	s_mov_b32 m0, s31
	s_nop 0
	global_load_lds_dwordx4 v[194:195], off
	v_lshl_add_u64 v[194:195], v[200:201], 0, s[80:81]
	s_mov_b32 m0, s34
	s_nop 0
	global_load_lds_dwordx4 v[194:195], off
	s_waitcnt vmcnt(8)
	s_waitcnt lgkmcnt(0)
	s_barrier
	s_setprio 1
	s_waitcnt lgkmcnt(0)
	v_mfma_f32_16x16x32_bf16 v[62:65], v[78:81], v[146:149], v[62:65]
	v_mfma_f32_16x16x32_bf16 v[58:61], v[94:97], v[146:149], v[58:61]
	v_mfma_f32_16x16x32_bf16 v[46:49], v[78:81], v[166:169], v[46:49]
	v_mfma_f32_16x16x32_bf16 v[42:45], v[94:97], v[166:169], v[42:45]
	v_mfma_f32_16x16x32_bf16 v[30:33], v[78:81], v[178:181], v[30:33]
	v_mfma_f32_16x16x32_bf16 v[26:29], v[94:97], v[178:181], v[26:29]
	v_mfma_f32_16x16x32_bf16 v[14:17], v[78:81], v[186:189], v[14:17]
	v_mfma_f32_16x16x32_bf16 v[10:13], v[94:97], v[186:189], v[10:13]
	v_mfma_f32_16x16x32_bf16 v[62:65], v[82:85], v[158:161], v[62:65]
	v_mfma_f32_16x16x32_bf16 v[58:61], v[98:101], v[158:161], v[58:61]
	v_mfma_f32_16x16x32_bf16 v[46:49], v[82:85], v[174:177], v[46:49]
	v_mfma_f32_16x16x32_bf16 v[42:45], v[98:101], v[174:177], v[42:45]
	v_mfma_f32_16x16x32_bf16 v[30:33], v[82:85], v[182:185], v[30:33]
	v_mfma_f32_16x16x32_bf16 v[26:29], v[98:101], v[182:185], v[26:29]
	v_mfma_f32_16x16x32_bf16 v[14:17], v[82:85], v[190:193], v[14:17]
	v_mfma_f32_16x16x32_bf16 v[10:13], v[98:101], v[190:193], v[10:13]
	s_setprio 0
	s_setprio 1
	v_mfma_f32_16x16x32_bf16 v[54:57], v[106:109], v[146:149], v[54:57]
	v_mfma_f32_16x16x32_bf16 v[50:53], v[126:129], v[146:149], v[50:53]
	v_mfma_f32_16x16x32_bf16 v[38:41], v[106:109], v[166:169], v[38:41]
	v_mfma_f32_16x16x32_bf16 v[34:37], v[126:129], v[166:169], v[34:37]
	v_mfma_f32_16x16x32_bf16 v[22:25], v[106:109], v[178:181], v[22:25]
	v_mfma_f32_16x16x32_bf16 v[18:21], v[126:129], v[178:181], v[18:21]
	v_mfma_f32_16x16x32_bf16 v[6:9], v[106:109], v[186:189], v[6:9]
	v_mfma_f32_16x16x32_bf16 v[2:5], v[126:129], v[186:189], v[2:5]
	v_mfma_f32_16x16x32_bf16 v[54:57], v[110:113], v[158:161], v[54:57]
	v_mfma_f32_16x16x32_bf16 v[50:53], v[134:137], v[158:161], v[50:53]
	v_mfma_f32_16x16x32_bf16 v[38:41], v[110:113], v[174:177], v[38:41]
	v_mfma_f32_16x16x32_bf16 v[34:37], v[134:137], v[174:177], v[34:37]
	v_mfma_f32_16x16x32_bf16 v[22:25], v[110:113], v[182:185], v[22:25]
	v_mfma_f32_16x16x32_bf16 v[18:21], v[134:137], v[182:185], v[18:21]
	v_mfma_f32_16x16x32_bf16 v[6:9], v[110:113], v[190:193], v[6:9]
	v_mfma_f32_16x16x32_bf16 v[2:5], v[134:137], v[190:193], v[2:5]
	s_setprio 0
	s_add_i32 s59, s59, 2
	s_add_u32 s49, s49, 0x100
	s_addc_u32 s58, s58, 0
	s_cmpk_gt_u32 s59, 0x55
	s_mov_b64 s[2:3], s[16:17]
	s_cbranch_scc1 .Lrot_exit_4
	s_add_u32 s16, s2, 0x100
	s_addc_u32 s17, s3, 0
	s_add_i32 s0, 0, 0x10000
	s_cmpk_eq_i32 s59, 0x54
	s_cselect_b32 s21, s7, s17
	s_cselect_b32 s20, s6, s16
	s_cselect_b32 s19, s15, s58
	s_cselect_b32 s18, s14, s49
	s_add_i32 s33, 0, 0x14000
	v_add_u32_e32 v98, s0, v205
	v_add_u32_e32 v134, s33, v205
	s_barrier
	s_branch .LBB0_970
.Lrot_exit_4:
	s_barrier
	s_and_b64 vcc, exec, s[10:11]
	s_cbranch_vccz .LBB0_973
	s_barrier

.LBB0_989:
	s_add_u32 s49, s4, 0x100
	v_mov_b32_e32 v2, 0
	s_addc_u32 s58, s5, 0
	s_mov_b32 s59, -2
	v_mov_b32_e32 v3, v2
	v_mov_b32_e32 v4, v2
	v_mov_b32_e32 v5, v2
	v_mov_b32_e32 v6, v2
	v_mov_b32_e32 v7, v2
	v_mov_b32_e32 v8, v2
	v_mov_b32_e32 v9, v2
	v_mov_b32_e32 v10, v2
	v_mov_b32_e32 v11, v2
	v_mov_b32_e32 v12, v2
	v_mov_b32_e32 v13, v2
	v_mov_b32_e32 v14, v2
	v_mov_b32_e32 v15, v2
	v_mov_b32_e32 v16, v2
	v_mov_b32_e32 v17, v2
	v_mov_b32_e32 v26, v2
	v_mov_b32_e32 v27, v2
	v_mov_b32_e32 v28, v2
	v_mov_b32_e32 v29, v2
	v_mov_b32_e32 v30, v2
	v_mov_b32_e32 v31, v2
	v_mov_b32_e32 v32, v2
	v_mov_b32_e32 v33, v2
	v_mov_b32_e32 v42, v2
	v_mov_b32_e32 v43, v2
	v_mov_b32_e32 v44, v2
	v_mov_b32_e32 v45, v2
	v_mov_b32_e32 v46, v2
	v_mov_b32_e32 v47, v2
	v_mov_b32_e32 v48, v2
	v_mov_b32_e32 v49, v2
	v_mov_b32_e32 v18, v2
	v_mov_b32_e32 v19, v2
	v_mov_b32_e32 v20, v2
	v_mov_b32_e32 v21, v2
	v_mov_b32_e32 v22, v2
	v_mov_b32_e32 v23, v2
	v_mov_b32_e32 v24, v2
	v_mov_b32_e32 v25, v2
	v_mov_b32_e32 v34, v2
	v_mov_b32_e32 v35, v2
	v_mov_b32_e32 v36, v2
	v_mov_b32_e32 v37, v2
	v_mov_b32_e32 v38, v2
	v_mov_b32_e32 v39, v2
	v_mov_b32_e32 v40, v2
	v_mov_b32_e32 v41, v2
	v_mov_b32_e32 v50, v2
	v_mov_b32_e32 v51, v2
	v_mov_b32_e32 v52, v2
	v_mov_b32_e32 v53, v2
	v_mov_b32_e32 v54, v2
	v_mov_b32_e32 v55, v2
	v_mov_b32_e32 v56, v2
	v_mov_b32_e32 v57, v2
	v_mov_b32_e32 v58, v2
	v_mov_b32_e32 v59, v2
	v_mov_b32_e32 v60, v2
	v_mov_b32_e32 v61, v2
	v_mov_b32_e32 v62, v2
	v_mov_b32_e32 v63, v2
	v_mov_b32_e32 v64, v2
	v_mov_b32_e32 v65, v2
	v_mov_b32_e32 v66, v2
	v_mov_b32_e32 v67, v2
	v_mov_b32_e32 v68, v2
	v_mov_b32_e32 v69, v2
	v_mov_b32_e32 v70, v2
	v_mov_b32_e32 v71, v2
	v_mov_b32_e32 v72, v2
	v_mov_b32_e32 v73, v2
	v_mov_b32_e32 v74, v2
	v_mov_b32_e32 v75, v2
	v_mov_b32_e32 v76, v2
	v_mov_b32_e32 v77, v2
	v_mov_b32_e32 v78, v2
	v_mov_b32_e32 v79, v2
	v_mov_b32_e32 v80, v2
	v_mov_b32_e32 v81, v2
	v_mov_b32_e32 v86, v2
	v_mov_b32_e32 v87, v2
	v_mov_b32_e32 v88, v2
	v_mov_b32_e32 v89, v2
	v_mov_b32_e32 v94, v2
	v_mov_b32_e32 v95, v2
	v_mov_b32_e32 v96, v2
	v_mov_b32_e32 v97, v2
	v_mov_b32_e32 v102, v2
	v_mov_b32_e32 v103, v2
	v_mov_b32_e32 v104, v2
	v_mov_b32_e32 v105, v2
	v_mov_b32_e32 v110, v2
	v_mov_b32_e32 v111, v2
	v_mov_b32_e32 v112, v2
	v_mov_b32_e32 v113, v2
	v_mov_b32_e32 v82, v2
	v_mov_b32_e32 v83, v2
	v_mov_b32_e32 v84, v2
	v_mov_b32_e32 v85, v2
	v_mov_b32_e32 v90, v2
	v_mov_b32_e32 v91, v2
	v_mov_b32_e32 v92, v2
	v_mov_b32_e32 v93, v2
	v_mov_b32_e32 v98, v2
	v_mov_b32_e32 v99, v2
	v_mov_b32_e32 v100, v2
	v_mov_b32_e32 v101, v2
	v_mov_b32_e32 v106, v2
	v_mov_b32_e32 v107, v2
	v_mov_b32_e32 v108, v2
	v_mov_b32_e32 v109, v2
	v_mov_b32_e32 v114, v2
	v_mov_b32_e32 v115, v2
	v_mov_b32_e32 v116, v2
	v_mov_b32_e32 v117, v2
	v_mov_b32_e32 v118, v2
	v_mov_b32_e32 v119, v2
	v_mov_b32_e32 v120, v2
	v_mov_b32_e32 v121, v2
	v_mov_b32_e32 v122, v2
	v_mov_b32_e32 v123, v2
	v_mov_b32_e32 v124, v2
	v_mov_b32_e32 v125, v2
	v_mov_b32_e32 v126, v2
	v_mov_b32_e32 v127, v2
	v_mov_b32_e32 v128, v2
	v_mov_b32_e32 v129, v2
	s_add_u32 s4, s2, 0x100
	s_addc_u32 s5, s3, 0
	s_add_i32 s0, 0, 0x10000
	s_cmp_eq_u32 s59, 4
	s_cselect_b32 s21, s15, s5
	s_cselect_b32 s20, s14, s4
	s_cselect_b32 s19, s17, s58
	s_cselect_b32 s18, s16, s49
	s_add_i32 s33, 0, 0x14000
	v_add_u32_e32 v152, s0, v136
	v_add_u32_e32 v168, s33, v136
.LBB0_990:
	ds_read_b128 v[140:143], v152
	ds_read_b128 v[144:147], v152 offset:1024
	ds_read_b128 v[148:151], v152 offset:2048
	ds_read_b128 v[152:155], v152 offset:3072
	ds_read_b128 v[156:159], v168
	ds_read_b128 v[160:163], v168 offset:1024
	ds_read_b128 v[164:167], v168 offset:2048
	ds_read_b128 v[168:171], v168 offset:3072
	v_lshl_add_u64 v[200:201], s[2:3], 0, v[132:133]
	s_add_i32 m0, s25, 0xc000
	ds_read_b128 v[172:175], v139
	ds_read_b128 v[176:179], v139 offset:1024
	ds_read_b128 v[180:183], v139 offset:2048
	ds_read_b128 v[184:187], v139 offset:3072
	ds_read_b128 v[188:191], v139 offset:4096
	ds_read_b128 v[192:195], v139 offset:5120
	ds_read_b128 v[196:199], v139 offset:6144
	ds_read_b128 v[208:211], v139 offset:7168
	global_load_lds_dwordx4 v[200:201], off
	v_lshl_add_u64 v[200:201], s[2:3], 0, v[134:135]
	s_add_i32 m0, s25, 0xe000
	s_nop 0
	global_load_lds_dwordx4 v[200:201], off
	s_waitcnt vmcnt(8)
	s_waitcnt lgkmcnt(0)
	s_barrier
	s_setprio 1
	s_waitcnt lgkmcnt(0)
	v_mfma_f32_16x16x32_bf16 v[126:129], v[140:143], v[172:175], v[126:129]
	v_mfma_f32_16x16x32_bf16 v[122:125], v[148:151], v[172:175], v[122:125]
	v_mfma_f32_16x16x32_bf16 v[118:121], v[140:143], v[180:183], v[118:121]
	v_mfma_f32_16x16x32_bf16 v[114:117], v[148:151], v[180:183], v[114:117]
	v_mfma_f32_16x16x32_bf16 v[106:109], v[140:143], v[188:191], v[106:109]
	v_mfma_f32_16x16x32_bf16 v[98:101], v[148:151], v[188:191], v[98:101]
	v_mfma_f32_16x16x32_bf16 v[90:93], v[140:143], v[196:199], v[90:93]
	v_mfma_f32_16x16x32_bf16 v[82:85], v[148:151], v[196:199], v[82:85]
	v_mfma_f32_16x16x32_bf16 v[126:129], v[144:147], v[176:179], v[126:129]
	v_mfma_f32_16x16x32_bf16 v[122:125], v[152:155], v[176:179], v[122:125]
	v_mfma_f32_16x16x32_bf16 v[118:121], v[144:147], v[184:187], v[118:121]
	v_mfma_f32_16x16x32_bf16 v[114:117], v[152:155], v[184:187], v[114:117]
	v_mfma_f32_16x16x32_bf16 v[106:109], v[144:147], v[192:195], v[106:109]
	v_mfma_f32_16x16x32_bf16 v[98:101], v[152:155], v[192:195], v[98:101]
	v_mfma_f32_16x16x32_bf16 v[90:93], v[144:147], v[208:211], v[90:93]
	v_mfma_f32_16x16x32_bf16 v[82:85], v[152:155], v[208:211], v[82:85]
	s_setprio 0
	s_setprio 1
	v_mfma_f32_16x16x32_bf16 v[110:113], v[156:159], v[172:175], v[110:113]
	v_mfma_f32_16x16x32_bf16 v[102:105], v[164:167], v[172:175], v[102:105]
	v_mfma_f32_16x16x32_bf16 v[94:97], v[156:159], v[180:183], v[94:97]
	v_mfma_f32_16x16x32_bf16 v[86:89], v[164:167], v[180:183], v[86:89]
	v_mfma_f32_16x16x32_bf16 v[78:81], v[156:159], v[188:191], v[78:81]
	v_mfma_f32_16x16x32_bf16 v[74:77], v[164:167], v[188:191], v[74:77]
	v_mfma_f32_16x16x32_bf16 v[70:73], v[156:159], v[196:199], v[70:73]
	v_mfma_f32_16x16x32_bf16 v[66:69], v[164:167], v[196:199], v[66:69]
	v_mfma_f32_16x16x32_bf16 v[110:113], v[160:163], v[176:179], v[110:113]
	v_mfma_f32_16x16x32_bf16 v[102:105], v[168:171], v[176:179], v[102:105]
	v_mfma_f32_16x16x32_bf16 v[94:97], v[160:163], v[184:187], v[94:97]
	v_mfma_f32_16x16x32_bf16 v[86:89], v[168:171], v[184:187], v[86:89]
	v_mfma_f32_16x16x32_bf16 v[78:81], v[160:163], v[192:195], v[78:81]
	v_mfma_f32_16x16x32_bf16 v[74:77], v[168:171], v[192:195], v[74:77]
	v_mfma_f32_16x16x32_bf16 v[70:73], v[160:163], v[208:211], v[70:73]
	v_mfma_f32_16x16x32_bf16 v[66:69], v[168:171], v[208:211], v[66:69]
	s_setprio 0
	s_barrier
	s_add_i32 s0, s0, s24
	v_lshl_add_u64 v[200:201], s[18:19], 0, v[202:203]
	s_mov_b32 m0, s0
	ds_read_b128 v[172:175], v139 offset:16384
	ds_read_b128 v[176:179], v139 offset:17408
	ds_read_b128 v[180:183], v139 offset:18432
	ds_read_b128 v[184:187], v139 offset:19456
	ds_read_b128 v[188:191], v139 offset:20480
	ds_read_b128 v[192:195], v139 offset:21504
	ds_read_b128 v[196:199], v139 offset:22528
	ds_read_b128 v[208:211], v139 offset:23552
	global_load_lds_dwordx4 v[200:201], off
	s_add_i32 m0, s0, 0x2000
	s_add_u32 s0, s18, 0x160000
	v_lshl_add_u64 v[204:205], s[18:19], 0, v[130:131]
	s_addc_u32 s1, s19, 0
	s_add_i32 s2, s33, s24
	global_load_lds_dwordx4 v[204:205], off
	v_lshl_add_u64 v[206:207], s[0:1], 0, v[202:203]
	s_mov_b32 m0, s2
	v_lshl_add_u64 v[212:213], s[20:21], 0, v[130:131]
	global_load_lds_dwordx4 v[206:207], off
	v_lshl_add_u64 v[206:207], s[0:1], 0, v[130:131]
	s_add_i32 m0, s2, 0x2000
	s_nop 0
	global_load_lds_dwordx4 v[206:207], off
	v_lshl_add_u64 v[206:207], s[20:21], 0, v[202:203]
	s_mov_b32 m0, s25
	s_nop 0
	global_load_lds_dwordx4 v[206:207], off
	s_mov_b32 m0, s26
	s_nop 0
	global_load_lds_dwordx4 v[212:213], off
	s_waitcnt vmcnt(8)
	s_waitcnt lgkmcnt(0)
	s_barrier
	s_setprio 1
	s_waitcnt lgkmcnt(0)
	v_mfma_f32_16x16x32_bf16 v[62:65], v[140:143], v[172:175], v[62:65]
	v_mfma_f32_16x16x32_bf16 v[58:61], v[148:151], v[172:175], v[58:61]
	v_mfma_f32_16x16x32_bf16 v[54:57], v[140:143], v[180:183], v[54:57]
	v_mfma_f32_16x16x32_bf16 v[50:53], v[148:151], v[180:183], v[50:53]
	v_mfma_f32_16x16x32_bf16 v[38:41], v[140:143], v[188:191], v[38:41]
	v_mfma_f32_16x16x32_bf16 v[34:37], v[148:151], v[188:191], v[34:37]
	v_mfma_f32_16x16x32_bf16 v[22:25], v[140:143], v[196:199], v[22:25]
	v_mfma_f32_16x16x32_bf16 v[18:21], v[148:151], v[196:199], v[18:21]
	v_mfma_f32_16x16x32_bf16 v[62:65], v[144:147], v[176:179], v[62:65]
	v_mfma_f32_16x16x32_bf16 v[58:61], v[152:155], v[176:179], v[58:61]
	v_mfma_f32_16x16x32_bf16 v[54:57], v[144:147], v[184:187], v[54:57]
	v_mfma_f32_16x16x32_bf16 v[50:53], v[152:155], v[184:187], v[50:53]
	v_mfma_f32_16x16x32_bf16 v[38:41], v[144:147], v[192:195], v[38:41]
	v_mfma_f32_16x16x32_bf16 v[34:37], v[152:155], v[192:195], v[34:37]
	v_mfma_f32_16x16x32_bf16 v[22:25], v[144:147], v[208:211], v[22:25]
	v_mfma_f32_16x16x32_bf16 v[18:21], v[152:155], v[208:211], v[18:21]
	s_setprio 0
	s_setprio 1
	v_mfma_f32_16x16x32_bf16 v[46:49], v[156:159], v[172:175], v[46:49]
	v_mfma_f32_16x16x32_bf16 v[42:45], v[164:167], v[172:175], v[42:45]
	v_mfma_f32_16x16x32_bf16 v[30:33], v[156:159], v[180:183], v[30:33]
	v_mfma_f32_16x16x32_bf16 v[26:29], v[164:167], v[180:183], v[26:29]
	v_mfma_f32_16x16x32_bf16 v[14:17], v[156:159], v[188:191], v[14:17]
	v_mfma_f32_16x16x32_bf16 v[10:13], v[164:167], v[188:191], v[10:13]
	v_mfma_f32_16x16x32_bf16 v[6:9], v[156:159], v[196:199], v[6:9]
	v_mfma_f32_16x16x32_bf16 v[2:5], v[164:167], v[196:199], v[2:5]
	v_mfma_f32_16x16x32_bf16 v[46:49], v[160:163], v[176:179], v[46:49]
	v_mfma_f32_16x16x32_bf16 v[42:45], v[168:171], v[176:179], v[42:45]
	v_mfma_f32_16x16x32_bf16 v[30:33], v[160:163], v[184:187], v[30:33]
	v_mfma_f32_16x16x32_bf16 v[26:29], v[168:171], v[184:187], v[26:29]
	v_mfma_f32_16x16x32_bf16 v[14:17], v[160:163], v[192:195], v[14:17]
	v_mfma_f32_16x16x32_bf16 v[10:13], v[168:171], v[192:195], v[10:13]
	v_mfma_f32_16x16x32_bf16 v[6:9], v[160:163], v[208:211], v[6:9]
	v_mfma_f32_16x16x32_bf16 v[2:5], v[168:171], v[208:211], v[2:5]
	s_setprio 0
	s_barrier
	s_add_i32 s2, 0, 0x18000
	s_add_i32 s3, 0, 0x1c000
	v_add_u32_e32 v152, s2, v136
	v_add_u32_e32 v168, s3, v136
	ds_read_b128 v[140:143], v152
	ds_read_b128 v[144:147], v152 offset:1024
	ds_read_b128 v[148:151], v152 offset:2048
	ds_read_b128 v[152:155], v152 offset:3072
	ds_read_b128 v[156:159], v168
	ds_read_b128 v[160:163], v168 offset:1024
	ds_read_b128 v[164:167], v168 offset:2048
	ds_read_b128 v[168:171], v168 offset:3072
	s_add_u32 s0, s20, 0x160000
	s_addc_u32 s1, s21, 0
	s_mov_b32 m0, s27
	v_lshl_add_u64 v[214:215], s[0:1], 0, v[202:203]
	ds_read_b128 v[172:175], v139 offset:32768
	ds_read_b128 v[176:179], v139 offset:33792
	ds_read_b128 v[180:183], v139 offset:34816
	ds_read_b128 v[184:187], v139 offset:35840
	ds_read_b128 v[188:191], v139 offset:36864
	ds_read_b128 v[192:195], v139 offset:37888
	ds_read_b128 v[196:199], v139 offset:38912
	ds_read_b128 v[208:211], v139 offset:39936
	global_load_lds_dwordx4 v[214:215], off
	v_lshl_add_u64 v[214:215], s[0:1], 0, v[130:131]
	s_mov_b32 m0, s28
	s_nop 0
	global_load_lds_dwordx4 v[214:215], off
	s_waitcnt vmcnt(8)
	s_waitcnt lgkmcnt(0)
	s_barrier
	s_setprio 1
	s_waitcnt lgkmcnt(0)
	v_mfma_f32_16x16x32_bf16 v[126:129], v[140:143], v[172:175], v[126:129]
	v_mfma_f32_16x16x32_bf16 v[122:125], v[148:151], v[172:175], v[122:125]
	v_mfma_f32_16x16x32_bf16 v[118:121], v[140:143], v[180:183], v[118:121]
	v_mfma_f32_16x16x32_bf16 v[114:117], v[148:151], v[180:183], v[114:117]
	v_mfma_f32_16x16x32_bf16 v[106:109], v[140:143], v[188:191], v[106:109]
	v_mfma_f32_16x16x32_bf16 v[98:101], v[148:151], v[188:191], v[98:101]
	v_mfma_f32_16x16x32_bf16 v[90:93], v[140:143], v[196:199], v[90:93]
	v_mfma_f32_16x16x32_bf16 v[82:85], v[148:151], v[196:199], v[82:85]
	v_mfma_f32_16x16x32_bf16 v[126:129], v[144:147], v[176:179], v[126:129]
	v_mfma_f32_16x16x32_bf16 v[122:125], v[152:155], v[176:179], v[122:125]
	v_mfma_f32_16x16x32_bf16 v[118:121], v[144:147], v[184:187], v[118:121]
	v_mfma_f32_16x16x32_bf16 v[114:117], v[152:155], v[184:187], v[114:117]
	v_mfma_f32_16x16x32_bf16 v[106:109], v[144:147], v[192:195], v[106:109]
	v_mfma_f32_16x16x32_bf16 v[98:101], v[152:155], v[192:195], v[98:101]
	v_mfma_f32_16x16x32_bf16 v[90:93], v[144:147], v[208:211], v[90:93]
	v_mfma_f32_16x16x32_bf16 v[82:85], v[152:155], v[208:211], v[82:85]
	s_setprio 0
	s_setprio 1
	v_mfma_f32_16x16x32_bf16 v[110:113], v[156:159], v[172:175], v[110:113]
	v_mfma_f32_16x16x32_bf16 v[102:105], v[164:167], v[172:175], v[102:105]
	v_mfma_f32_16x16x32_bf16 v[94:97], v[156:159], v[180:183], v[94:97]
	v_mfma_f32_16x16x32_bf16 v[86:89], v[164:167], v[180:183], v[86:89]
	v_mfma_f32_16x16x32_bf16 v[78:81], v[156:159], v[188:191], v[78:81]
	v_mfma_f32_16x16x32_bf16 v[74:77], v[164:167], v[188:191], v[74:77]
	v_mfma_f32_16x16x32_bf16 v[70:73], v[156:159], v[196:199], v[70:73]
	v_mfma_f32_16x16x32_bf16 v[66:69], v[164:167], v[196:199], v[66:69]
	v_mfma_f32_16x16x32_bf16 v[110:113], v[160:163], v[176:179], v[110:113]
	v_mfma_f32_16x16x32_bf16 v[102:105], v[168:171], v[176:179], v[102:105]
	v_mfma_f32_16x16x32_bf16 v[94:97], v[160:163], v[184:187], v[94:97]
	v_mfma_f32_16x16x32_bf16 v[86:89], v[168:171], v[184:187], v[86:89]
	v_mfma_f32_16x16x32_bf16 v[78:81], v[160:163], v[192:195], v[78:81]
	v_mfma_f32_16x16x32_bf16 v[74:77], v[168:171], v[192:195], v[74:77]
	v_mfma_f32_16x16x32_bf16 v[70:73], v[160:163], v[208:211], v[70:73]
	v_mfma_f32_16x16x32_bf16 v[66:69], v[168:171], v[208:211], v[66:69]
	s_setprio 0
	s_barrier
	s_add_i32 s0, s2, s24
	v_lshl_add_u64 v[200:201], v[200:201], 0, s[80:81]
	s_mov_b32 m0, s0
	ds_read_b128 v[172:175], v139 offset:49152
	ds_read_b128 v[176:179], v139 offset:50176
	ds_read_b128 v[180:183], v139 offset:51200
	ds_read_b128 v[184:187], v139 offset:52224
	ds_read_b128 v[188:191], v139 offset:53248
	ds_read_b128 v[192:195], v139 offset:54272
	ds_read_b128 v[196:199], v139 offset:55296
	ds_read_b128 v[208:211], v139 offset:56320
	global_load_lds_dwordx4 v[200:201], off
	s_add_i32 m0, s0, 0x2000
	s_add_u32 s0, s18, 0x160080
	v_lshl_add_u64 v[200:201], v[204:205], 0, s[80:81]
	s_addc_u32 s1, s19, 0
	s_add_i32 s2, s3, s24
	global_load_lds_dwordx4 v[200:201], off
	v_lshl_add_u64 v[200:201], s[0:1], 0, v[202:203]
	s_mov_b32 m0, s2
	s_nop 0
	global_load_lds_dwordx4 v[200:201], off
	v_lshl_add_u64 v[200:201], s[0:1], 0, v[130:131]
	s_add_i32 m0, s2, 0x2000
	s_nop 0
	global_load_lds_dwordx4 v[200:201], off
	v_lshl_add_u64 v[200:201], v[206:207], 0, s[80:81]
	s_mov_b32 m0, s29
	s_nop 0
	global_load_lds_dwordx4 v[200:201], off
	v_lshl_add_u64 v[200:201], v[212:213], 0, s[80:81]
	s_mov_b32 m0, s30
	s_nop 0
	global_load_lds_dwordx4 v[200:201], off
	s_waitcnt vmcnt(8)
	s_waitcnt lgkmcnt(0)
	s_barrier
	s_setprio 1
	s_waitcnt lgkmcnt(0)
	v_mfma_f32_16x16x32_bf16 v[62:65], v[140:143], v[172:175], v[62:65]
	v_mfma_f32_16x16x32_bf16 v[58:61], v[148:151], v[172:175], v[58:61]
	v_mfma_f32_16x16x32_bf16 v[54:57], v[140:143], v[180:183], v[54:57]
	v_mfma_f32_16x16x32_bf16 v[50:53], v[148:151], v[180:183], v[50:53]
	v_mfma_f32_16x16x32_bf16 v[38:41], v[140:143], v[188:191], v[38:41]
	v_mfma_f32_16x16x32_bf16 v[34:37], v[148:151], v[188:191], v[34:37]
	v_mfma_f32_16x16x32_bf16 v[22:25], v[140:143], v[196:199], v[22:25]
	v_mfma_f32_16x16x32_bf16 v[18:21], v[148:151], v[196:199], v[18:21]
	v_mfma_f32_16x16x32_bf16 v[62:65], v[144:147], v[176:179], v[62:65]
	v_mfma_f32_16x16x32_bf16 v[58:61], v[152:155], v[176:179], v[58:61]
	v_mfma_f32_16x16x32_bf16 v[54:57], v[144:147], v[184:187], v[54:57]
	v_mfma_f32_16x16x32_bf16 v[50:53], v[152:155], v[184:187], v[50:53]
	v_mfma_f32_16x16x32_bf16 v[38:41], v[144:147], v[192:195], v[38:41]
	v_mfma_f32_16x16x32_bf16 v[34:37], v[152:155], v[192:195], v[34:37]
	v_mfma_f32_16x16x32_bf16 v[22:25], v[144:147], v[208:211], v[22:25]
	v_mfma_f32_16x16x32_bf16 v[18:21], v[152:155], v[208:211], v[18:21]
	s_setprio 0
	s_setprio 1
	v_mfma_f32_16x16x32_bf16 v[46:49], v[156:159], v[172:175], v[46:49]
	v_mfma_f32_16x16x32_bf16 v[42:45], v[164:167], v[172:175], v[42:45]
	v_mfma_f32_16x16x32_bf16 v[30:33], v[156:159], v[180:183], v[30:33]
	v_mfma_f32_16x16x32_bf16 v[26:29], v[164:167], v[180:183], v[26:29]
	v_mfma_f32_16x16x32_bf16 v[14:17], v[156:159], v[188:191], v[14:17]
	v_mfma_f32_16x16x32_bf16 v[10:13], v[164:167], v[188:191], v[10:13]
	v_mfma_f32_16x16x32_bf16 v[6:9], v[156:159], v[196:199], v[6:9]
	v_mfma_f32_16x16x32_bf16 v[2:5], v[164:167], v[196:199], v[2:5]
	v_mfma_f32_16x16x32_bf16 v[46:49], v[160:163], v[176:179], v[46:49]
	v_mfma_f32_16x16x32_bf16 v[42:45], v[168:171], v[176:179], v[42:45]
	v_mfma_f32_16x16x32_bf16 v[30:33], v[160:163], v[184:187], v[30:33]
	v_mfma_f32_16x16x32_bf16 v[26:29], v[168:171], v[184:187], v[26:29]
	v_mfma_f32_16x16x32_bf16 v[14:17], v[160:163], v[192:195], v[14:17]
	v_mfma_f32_16x16x32_bf16 v[10:13], v[168:171], v[192:195], v[10:13]
	v_mfma_f32_16x16x32_bf16 v[6:9], v[160:163], v[208:211], v[6:9]
	v_mfma_f32_16x16x32_bf16 v[2:5], v[168:171], v[208:211], v[2:5]
	s_setprio 0
	s_add_i32 s59, s59, 2
	s_add_u32 s49, s49, 0x100
	s_addc_u32 s58, s58, 0
	s_cmp_gt_u32 s59, 5
	s_mov_b64 s[2:3], s[4:5]
	s_cbranch_scc1 .Lrot_exit_5
	s_add_u32 s4, s2, 0x100
	s_addc_u32 s5, s3, 0
	s_add_i32 s0, 0, 0x10000
	s_cmp_eq_u32 s59, 4
	s_cselect_b32 s21, s15, s5
	s_cselect_b32 s20, s14, s4
	s_cselect_b32 s19, s17, s58
	s_cselect_b32 s18, s16, s49
	s_add_i32 s33, 0, 0x14000
	v_add_u32_e32 v152, s0, v136
	v_add_u32_e32 v168, s33, v136
	s_barrier
	s_branch .LBB0_990

.LBB0_1114:
	s_ashr_i32 s17, s16, 31
	s_lshl_b64 s[0:1], s[16:17], 20
	s_add_u32 s18, s42, s0
	s_addc_u32 s19, s43, s1
	s_and_b64 s[0:1], s[6:7], exec
	s_cselect_b32 s17, s19, s5
	s_cselect_b32 s39, s18, s4
	s_ashr_i32 s15, s14, 31
	s_lshl_b64 s[0:1], s[14:15], 20
	s_add_u32 s20, s24, s0
	s_addc_u32 s21, s25, s1
	s_and_b64 s[0:1], s[6:7], exec
	s_cselect_b32 s15, s21, s3
	s_cselect_b32 s40, s20, s2
	s_add_u32 s22, s4, 0x80080
	s_addc_u32 s23, s5, 0
	s_add_u32 s41, s2, 0x100
	v_mov_b32_e32 v2, 0
	s_addc_u32 s49, s3, 0
	s_mov_b32 s58, -2
	v_mov_b32_e32 v3, v2
	v_mov_b32_e32 v4, v2
	v_mov_b32_e32 v5, v2
	v_mov_b32_e32 v6, v2
	v_mov_b32_e32 v7, v2
	v_mov_b32_e32 v8, v2
	v_mov_b32_e32 v9, v2
	v_mov_b32_e32 v18, v2
	v_mov_b32_e32 v19, v2
	v_mov_b32_e32 v20, v2
	v_mov_b32_e32 v21, v2
	v_mov_b32_e32 v22, v2
	v_mov_b32_e32 v23, v2
	v_mov_b32_e32 v24, v2
	v_mov_b32_e32 v25, v2
	v_mov_b32_e32 v34, v2
	v_mov_b32_e32 v35, v2
	v_mov_b32_e32 v36, v2
	v_mov_b32_e32 v37, v2
	v_mov_b32_e32 v38, v2
	v_mov_b32_e32 v39, v2
	v_mov_b32_e32 v40, v2
	v_mov_b32_e32 v41, v2
	v_mov_b32_e32 v50, v2
	v_mov_b32_e32 v51, v2
	v_mov_b32_e32 v52, v2
	v_mov_b32_e32 v53, v2
	v_mov_b32_e32 v54, v2
	v_mov_b32_e32 v55, v2
	v_mov_b32_e32 v56, v2
	v_mov_b32_e32 v57, v2
	v_mov_b32_e32 v10, v2
	v_mov_b32_e32 v11, v2
	v_mov_b32_e32 v12, v2
	v_mov_b32_e32 v13, v2
	v_mov_b32_e32 v14, v2
	v_mov_b32_e32 v15, v2
	v_mov_b32_e32 v16, v2
	v_mov_b32_e32 v17, v2
	v_mov_b32_e32 v26, v2
	v_mov_b32_e32 v27, v2
	v_mov_b32_e32 v28, v2
	v_mov_b32_e32 v29, v2
	v_mov_b32_e32 v30, v2
	v_mov_b32_e32 v31, v2
	v_mov_b32_e32 v32, v2
	v_mov_b32_e32 v33, v2
	v_mov_b32_e32 v42, v2
	v_mov_b32_e32 v43, v2
	v_mov_b32_e32 v44, v2
	v_mov_b32_e32 v45, v2
	v_mov_b32_e32 v46, v2
	v_mov_b32_e32 v47, v2
	v_mov_b32_e32 v48, v2
	v_mov_b32_e32 v49, v2
	v_mov_b32_e32 v58, v2
	v_mov_b32_e32 v59, v2
	v_mov_b32_e32 v60, v2
	v_mov_b32_e32 v61, v2
	v_mov_b32_e32 v62, v2
	v_mov_b32_e32 v63, v2
	v_mov_b32_e32 v64, v2
	v_mov_b32_e32 v65, v2
	v_mov_b32_e32 v66, v2
	v_mov_b32_e32 v67, v2
	v_mov_b32_e32 v68, v2
	v_mov_b32_e32 v69, v2
	v_mov_b32_e32 v70, v2
	v_mov_b32_e32 v71, v2
	v_mov_b32_e32 v72, v2
	v_mov_b32_e32 v73, v2
	v_mov_b32_e32 v82, v2
	v_mov_b32_e32 v83, v2
	v_mov_b32_e32 v84, v2
	v_mov_b32_e32 v85, v2
	v_mov_b32_e32 v86, v2
	v_mov_b32_e32 v87, v2
	v_mov_b32_e32 v88, v2
	v_mov_b32_e32 v89, v2
	v_mov_b32_e32 v98, v2
	v_mov_b32_e32 v99, v2
	v_mov_b32_e32 v100, v2
	v_mov_b32_e32 v101, v2
	v_mov_b32_e32 v102, v2
	v_mov_b32_e32 v103, v2
	v_mov_b32_e32 v104, v2
	v_mov_b32_e32 v105, v2
	v_mov_b32_e32 v114, v2
	v_mov_b32_e32 v115, v2
	v_mov_b32_e32 v116, v2
	v_mov_b32_e32 v117, v2
	v_mov_b32_e32 v118, v2
	v_mov_b32_e32 v119, v2
	v_mov_b32_e32 v120, v2
	v_mov_b32_e32 v121, v2
	v_mov_b32_e32 v74, v2
	v_mov_b32_e32 v75, v2
	v_mov_b32_e32 v76, v2
	v_mov_b32_e32 v77, v2
	v_mov_b32_e32 v78, v2
	v_mov_b32_e32 v79, v2
	v_mov_b32_e32 v80, v2
	v_mov_b32_e32 v81, v2
	v_mov_b32_e32 v90, v2
	v_mov_b32_e32 v91, v2
	v_mov_b32_e32 v92, v2
	v_mov_b32_e32 v93, v2
	v_mov_b32_e32 v94, v2
	v_mov_b32_e32 v95, v2
	v_mov_b32_e32 v96, v2
	v_mov_b32_e32 v97, v2
	v_mov_b32_e32 v106, v2
	v_mov_b32_e32 v107, v2
	v_mov_b32_e32 v108, v2
	v_mov_b32_e32 v109, v2
	v_mov_b32_e32 v110, v2
	v_mov_b32_e32 v111, v2
	v_mov_b32_e32 v112, v2
	v_mov_b32_e32 v113, v2
	v_mov_b32_e32 v122, v2
	v_mov_b32_e32 v123, v2
	v_mov_b32_e32 v124, v2
	v_mov_b32_e32 v125, v2
	v_mov_b32_e32 v126, v2
	v_mov_b32_e32 v127, v2
	v_mov_b32_e32 v128, v2
	v_mov_b32_e32 v129, v2
	s_add_u32 s0, s22, 0xfff80080
	s_addc_u32 s1, s23, -1
	s_add_i32 s33, 0, 0x10000
	s_cmp_eq_u32 s58, 28
	s_cselect_b32 s5, s17, s1
	s_cselect_b32 s4, s39, s0
	v_add_u32_e32 v143, s33, v145
	s_cselect_b32 s3, s15, s49
	s_cselect_b32 s2, s40, s41
	s_add_i32 s55, 0, 0x14000
.LBB0_1115:
	ds_read_b128 v[148:151], v143
	ds_read_b128 v[152:155], v143 offset:1024
	ds_read_b128 v[156:159], v143 offset:2048
	ds_read_b128 v[160:163], v143 offset:3072
	v_add_u32_e32 v143, s55, v145
	ds_read_b128 v[164:167], v143
	ds_read_b128 v[168:171], v143 offset:1024
	ds_read_b128 v[172:175], v143 offset:2048
	ds_read_b128 v[176:179], v143 offset:3072
	v_lshl_add_u64 v[200:201], s[22:23], 0, v[138:139]
	s_add_i32 m0, s27, 0xc000
	ds_read_b128 v[180:183], v147
	ds_read_b128 v[184:187], v147 offset:1024
	ds_read_b128 v[188:191], v147 offset:2048
	ds_read_b128 v[192:195], v147 offset:3072
	ds_read_b128 v[196:199], v147 offset:4096
	ds_read_b128 v[208:211], v147 offset:5120
	ds_read_b128 v[212:215], v147 offset:6144
	ds_read_b128 v[216:219], v147 offset:7168
	global_load_lds_dwordx4 v[200:201], off
	v_lshl_add_u64 v[200:201], s[22:23], 0, v[140:141]
	s_add_i32 m0, s27, 0xe000
	s_nop 0
	global_load_lds_dwordx4 v[200:201], off
	s_waitcnt vmcnt(8)
	s_waitcnt lgkmcnt(0)
	s_barrier
	s_setprio 1
	s_waitcnt lgkmcnt(0)
	v_mfma_f32_16x16x32_bf16 v[126:129], v[148:151], v[180:183], v[126:129]
	v_mfma_f32_16x16x32_bf16 v[122:125], v[156:159], v[180:183], v[122:125]
	v_mfma_f32_16x16x32_bf16 v[110:113], v[148:151], v[188:191], v[110:113]
	v_mfma_f32_16x16x32_bf16 v[106:109], v[156:159], v[188:191], v[106:109]
	v_mfma_f32_16x16x32_bf16 v[94:97], v[148:151], v[196:199], v[94:97]
	v_mfma_f32_16x16x32_bf16 v[90:93], v[156:159], v[196:199], v[90:93]
	v_mfma_f32_16x16x32_bf16 v[78:81], v[148:151], v[212:215], v[78:81]
	v_mfma_f32_16x16x32_bf16 v[74:77], v[156:159], v[212:215], v[74:77]
	v_mfma_f32_16x16x32_bf16 v[126:129], v[152:155], v[184:187], v[126:129]
	v_mfma_f32_16x16x32_bf16 v[122:125], v[160:163], v[184:187], v[122:125]
	v_mfma_f32_16x16x32_bf16 v[110:113], v[152:155], v[192:195], v[110:113]
	v_mfma_f32_16x16x32_bf16 v[106:109], v[160:163], v[192:195], v[106:109]
	v_mfma_f32_16x16x32_bf16 v[94:97], v[152:155], v[208:211], v[94:97]
	v_mfma_f32_16x16x32_bf16 v[90:93], v[160:163], v[208:211], v[90:93]
	v_mfma_f32_16x16x32_bf16 v[78:81], v[152:155], v[216:219], v[78:81]
	v_mfma_f32_16x16x32_bf16 v[74:77], v[160:163], v[216:219], v[74:77]
	s_setprio 0
	s_setprio 1
	v_mfma_f32_16x16x32_bf16 v[118:121], v[164:167], v[180:183], v[118:121]
	v_mfma_f32_16x16x32_bf16 v[114:117], v[172:175], v[180:183], v[114:117]
	v_mfma_f32_16x16x32_bf16 v[102:105], v[164:167], v[188:191], v[102:105]
	v_mfma_f32_16x16x32_bf16 v[98:101], v[172:175], v[188:191], v[98:101]
	v_mfma_f32_16x16x32_bf16 v[86:89], v[164:167], v[196:199], v[86:89]
	v_mfma_f32_16x16x32_bf16 v[82:85], v[172:175], v[196:199], v[82:85]
	v_mfma_f32_16x16x32_bf16 v[70:73], v[164:167], v[212:215], v[70:73]
	v_mfma_f32_16x16x32_bf16 v[66:69], v[172:175], v[212:215], v[66:69]
	v_mfma_f32_16x16x32_bf16 v[118:121], v[168:171], v[184:187], v[118:121]
	v_mfma_f32_16x16x32_bf16 v[114:117], v[176:179], v[184:187], v[114:117]
	v_mfma_f32_16x16x32_bf16 v[102:105], v[168:171], v[192:195], v[102:105]
	v_mfma_f32_16x16x32_bf16 v[98:101], v[176:179], v[192:195], v[98:101]
	v_mfma_f32_16x16x32_bf16 v[86:89], v[168:171], v[208:211], v[86:89]
	v_mfma_f32_16x16x32_bf16 v[82:85], v[176:179], v[208:211], v[82:85]
	v_mfma_f32_16x16x32_bf16 v[70:73], v[168:171], v[216:219], v[70:73]
	v_mfma_f32_16x16x32_bf16 v[66:69], v[176:179], v[216:219], v[66:69]
	s_setprio 0
	s_barrier
	s_add_i32 s0, s33, s26
	v_lshl_add_u64 v[200:201], s[2:3], 0, v[134:135]
	s_mov_b32 m0, s0
	ds_read_b128 v[180:183], v147 offset:16384
	ds_read_b128 v[184:187], v147 offset:17408
	ds_read_b128 v[188:191], v147 offset:18432
	ds_read_b128 v[192:195], v147 offset:19456
	ds_read_b128 v[196:199], v147 offset:20480
	ds_read_b128 v[208:211], v147 offset:21504
	ds_read_b128 v[212:215], v147 offset:22528
	ds_read_b128 v[216:219], v147 offset:23552
	global_load_lds_dwordx4 v[200:201], off
	s_add_i32 m0, s0, 0x2000
	s_add_u32 s0, s2, 0x80000
	v_lshl_add_u64 v[204:205], s[2:3], 0, v[130:131]
	s_addc_u32 s1, s3, 0
	s_add_i32 s33, s55, s26
	global_load_lds_dwordx4 v[204:205], off
	v_lshl_add_u64 v[206:207], s[0:1], 0, v[134:135]
	s_mov_b32 m0, s33
	v_lshl_add_u64 v[220:221], s[4:5], 0, v[132:133]
	global_load_lds_dwordx4 v[206:207], off
	v_lshl_add_u64 v[206:207], s[0:1], 0, v[130:131]
	s_add_i32 m0, s33, 0x2000
	s_nop 0
	global_load_lds_dwordx4 v[206:207], off
	v_lshl_add_u64 v[206:207], s[4:5], 0, v[136:137]
	s_mov_b32 m0, s27
	s_nop 0
	global_load_lds_dwordx4 v[206:207], off
	s_mov_b32 m0, s28
	s_nop 0
	global_load_lds_dwordx4 v[220:221], off
	s_waitcnt vmcnt(8)
	s_waitcnt lgkmcnt(0)
	s_barrier
	s_setprio 1
	s_waitcnt lgkmcnt(0)
	v_mfma_f32_16x16x32_bf16 v[62:65], v[148:151], v[180:183], v[62:65]
	v_mfma_f32_16x16x32_bf16 v[58:61], v[156:159], v[180:183], v[58:61]
	v_mfma_f32_16x16x32_bf16 v[46:49], v[148:151], v[188:191], v[46:49]
	v_mfma_f32_16x16x32_bf16 v[42:45], v[156:159], v[188:191], v[42:45]
	v_mfma_f32_16x16x32_bf16 v[30:33], v[148:151], v[196:199], v[30:33]
	v_mfma_f32_16x16x32_bf16 v[26:29], v[156:159], v[196:199], v[26:29]
	v_mfma_f32_16x16x32_bf16 v[14:17], v[148:151], v[212:215], v[14:17]
	v_mfma_f32_16x16x32_bf16 v[10:13], v[156:159], v[212:215], v[10:13]
	v_mfma_f32_16x16x32_bf16 v[62:65], v[152:155], v[184:187], v[62:65]
	v_mfma_f32_16x16x32_bf16 v[58:61], v[160:163], v[184:187], v[58:61]
	v_mfma_f32_16x16x32_bf16 v[46:49], v[152:155], v[192:195], v[46:49]
	v_mfma_f32_16x16x32_bf16 v[42:45], v[160:163], v[192:195], v[42:45]
	v_mfma_f32_16x16x32_bf16 v[30:33], v[152:155], v[208:211], v[30:33]
	v_mfma_f32_16x16x32_bf16 v[26:29], v[160:163], v[208:211], v[26:29]
	v_mfma_f32_16x16x32_bf16 v[14:17], v[152:155], v[216:219], v[14:17]
	v_mfma_f32_16x16x32_bf16 v[10:13], v[160:163], v[216:219], v[10:13]
	s_setprio 0
	s_setprio 1
	v_mfma_f32_16x16x32_bf16 v[54:57], v[164:167], v[180:183], v[54:57]
	v_mfma_f32_16x16x32_bf16 v[50:53], v[172:175], v[180:183], v[50:53]
	v_mfma_f32_16x16x32_bf16 v[38:41], v[164:167], v[188:191], v[38:41]
	v_mfma_f32_16x16x32_bf16 v[34:37], v[172:175], v[188:191], v[34:37]
	v_mfma_f32_16x16x32_bf16 v[22:25], v[164:167], v[196:199], v[22:25]
	v_mfma_f32_16x16x32_bf16 v[18:21], v[172:175], v[196:199], v[18:21]
	v_mfma_f32_16x16x32_bf16 v[6:9], v[164:167], v[212:215], v[6:9]
	v_mfma_f32_16x16x32_bf16 v[2:5], v[172:175], v[212:215], v[2:5]
	v_mfma_f32_16x16x32_bf16 v[54:57], v[168:171], v[184:187], v[54:57]
	v_mfma_f32_16x16x32_bf16 v[50:53], v[176:179], v[184:187], v[50:53]
	v_mfma_f32_16x16x32_bf16 v[38:41], v[168:171], v[192:195], v[38:41]
	v_mfma_f32_16x16x32_bf16 v[34:37], v[176:179], v[192:195], v[34:37]
	v_mfma_f32_16x16x32_bf16 v[22:25], v[168:171], v[208:211], v[22:25]
	v_mfma_f32_16x16x32_bf16 v[18:21], v[176:179], v[208:211], v[18:21]
	v_mfma_f32_16x16x32_bf16 v[6:9], v[168:171], v[216:219], v[6:9]
	v_mfma_f32_16x16x32_bf16 v[2:5], v[176:179], v[216:219], v[2:5]
	s_setprio 0
	s_barrier
	s_add_i32 s33, 0, 0x18000
	v_add_u32_e32 v143, s33, v145
	s_add_i32 s55, 0, 0x1c000
	ds_read_b128 v[148:151], v143
	ds_read_b128 v[152:155], v143 offset:1024
	ds_read_b128 v[156:159], v143 offset:2048
	ds_read_b128 v[160:163], v143 offset:3072
	v_add_u32_e32 v143, s55, v145
	ds_read_b128 v[164:167], v143
	ds_read_b128 v[168:171], v143 offset:1024
	ds_read_b128 v[172:175], v143 offset:2048
	ds_read_b128 v[176:179], v143 offset:3072
	s_add_u32 s0, s4, 0x80000
	s_addc_u32 s1, s5, 0
	s_mov_b32 m0, s29
	v_lshl_add_u64 v[222:223], s[0:1], 0, v[136:137]
	ds_read_b128 v[180:183], v147 offset:32768
	ds_read_b128 v[184:187], v147 offset:33792
	ds_read_b128 v[188:191], v147 offset:34816
	ds_read_b128 v[192:195], v147 offset:35840
	ds_read_b128 v[196:199], v147 offset:36864
	ds_read_b128 v[208:211], v147 offset:37888
	ds_read_b128 v[212:215], v147 offset:38912
	ds_read_b128 v[216:219], v147 offset:39936
	global_load_lds_dwordx4 v[222:223], off
	v_lshl_add_u64 v[222:223], s[0:1], 0, v[132:133]
	s_mov_b32 m0, s30
	s_nop 0
	global_load_lds_dwordx4 v[222:223], off
	s_waitcnt vmcnt(8)
	s_waitcnt lgkmcnt(0)
	s_barrier
	s_setprio 1
	s_waitcnt lgkmcnt(0)
	v_mfma_f32_16x16x32_bf16 v[126:129], v[148:151], v[180:183], v[126:129]
	v_mfma_f32_16x16x32_bf16 v[122:125], v[156:159], v[180:183], v[122:125]
	v_mfma_f32_16x16x32_bf16 v[110:113], v[148:151], v[188:191], v[110:113]
	v_mfma_f32_16x16x32_bf16 v[106:109], v[156:159], v[188:191], v[106:109]
	v_mfma_f32_16x16x32_bf16 v[94:97], v[148:151], v[196:199], v[94:97]
	v_mfma_f32_16x16x32_bf16 v[90:93], v[156:159], v[196:199], v[90:93]
	v_mfma_f32_16x16x32_bf16 v[78:81], v[148:151], v[212:215], v[78:81]
	v_mfma_f32_16x16x32_bf16 v[74:77], v[156:159], v[212:215], v[74:77]
	v_mfma_f32_16x16x32_bf16 v[126:129], v[152:155], v[184:187], v[126:129]
	v_mfma_f32_16x16x32_bf16 v[122:125], v[160:163], v[184:187], v[122:125]
	v_mfma_f32_16x16x32_bf16 v[110:113], v[152:155], v[192:195], v[110:113]
	v_mfma_f32_16x16x32_bf16 v[106:109], v[160:163], v[192:195], v[106:109]
	v_mfma_f32_16x16x32_bf16 v[94:97], v[152:155], v[208:211], v[94:97]
	v_mfma_f32_16x16x32_bf16 v[90:93], v[160:163], v[208:211], v[90:93]
	v_mfma_f32_16x16x32_bf16 v[78:81], v[152:155], v[216:219], v[78:81]
	v_mfma_f32_16x16x32_bf16 v[74:77], v[160:163], v[216:219], v[74:77]
	s_setprio 0
	s_setprio 1
	v_mfma_f32_16x16x32_bf16 v[118:121], v[164:167], v[180:183], v[118:121]
	v_mfma_f32_16x16x32_bf16 v[114:117], v[172:175], v[180:183], v[114:117]
	v_mfma_f32_16x16x32_bf16 v[102:105], v[164:167], v[188:191], v[102:105]
	v_mfma_f32_16x16x32_bf16 v[98:101], v[172:175], v[188:191], v[98:101]
	v_mfma_f32_16x16x32_bf16 v[86:89], v[164:167], v[196:199], v[86:89]
	v_mfma_f32_16x16x32_bf16 v[82:85], v[172:175], v[196:199], v[82:85]
	v_mfma_f32_16x16x32_bf16 v[70:73], v[164:167], v[212:215], v[70:73]
	v_mfma_f32_16x16x32_bf16 v[66:69], v[172:175], v[212:215], v[66:69]
	v_mfma_f32_16x16x32_bf16 v[118:121], v[168:171], v[184:187], v[118:121]
	v_mfma_f32_16x16x32_bf16 v[114:117], v[176:179], v[184:187], v[114:117]
	v_mfma_f32_16x16x32_bf16 v[102:105], v[168:171], v[192:195], v[102:105]
	v_mfma_f32_16x16x32_bf16 v[98:101], v[176:179], v[192:195], v[98:101]
	v_mfma_f32_16x16x32_bf16 v[86:89], v[168:171], v[208:211], v[86:89]
	v_mfma_f32_16x16x32_bf16 v[82:85], v[176:179], v[208:211], v[82:85]
	v_mfma_f32_16x16x32_bf16 v[70:73], v[168:171], v[216:219], v[70:73]
	v_mfma_f32_16x16x32_bf16 v[66:69], v[176:179], v[216:219], v[66:69]
	s_setprio 0
	s_barrier
	s_add_i32 s0, s33, s26
	v_lshl_add_u64 v[200:201], v[200:201], 0, s[80:81]
	s_mov_b32 m0, s0
	ds_read_b128 v[180:183], v147 offset:49152
	ds_read_b128 v[184:187], v147 offset:50176
	ds_read_b128 v[188:191], v147 offset:51200
	ds_read_b128 v[192:195], v147 offset:52224
	ds_read_b128 v[196:199], v147 offset:53248
	ds_read_b128 v[208:211], v147 offset:54272
	ds_read_b128 v[212:215], v147 offset:55296
	ds_read_b128 v[216:219], v147 offset:56320
	global_load_lds_dwordx4 v[200:201], off
	s_add_i32 m0, s0, 0x2000
	s_add_u32 s0, s2, 0x80080
	v_lshl_add_u64 v[200:201], v[204:205], 0, s[80:81]
	s_addc_u32 s1, s3, 0
	s_add_i32 s2, s55, s26
	global_load_lds_dwordx4 v[200:201], off
	v_lshl_add_u64 v[200:201], s[0:1], 0, v[134:135]
	s_mov_b32 m0, s2
	s_nop 0
	global_load_lds_dwordx4 v[200:201], off
	v_lshl_add_u64 v[200:201], s[0:1], 0, v[130:131]
	s_add_i32 m0, s2, 0x2000
	s_nop 0
	global_load_lds_dwordx4 v[200:201], off
	v_lshl_add_u64 v[200:201], v[206:207], 0, s[80:81]
	s_mov_b32 m0, s34
	s_nop 0
	global_load_lds_dwordx4 v[200:201], off
	v_lshl_add_u64 v[200:201], v[220:221], 0, s[80:81]
	s_mov_b32 m0, s35
	s_nop 0
	global_load_lds_dwordx4 v[200:201], off
	s_waitcnt vmcnt(8)
	s_waitcnt lgkmcnt(0)
	s_barrier
	s_setprio 1
	s_waitcnt lgkmcnt(0)
	v_mfma_f32_16x16x32_bf16 v[62:65], v[148:151], v[180:183], v[62:65]
	v_mfma_f32_16x16x32_bf16 v[58:61], v[156:159], v[180:183], v[58:61]
	v_mfma_f32_16x16x32_bf16 v[46:49], v[148:151], v[188:191], v[46:49]
	v_mfma_f32_16x16x32_bf16 v[42:45], v[156:159], v[188:191], v[42:45]
	v_mfma_f32_16x16x32_bf16 v[30:33], v[148:151], v[196:199], v[30:33]
	v_mfma_f32_16x16x32_bf16 v[26:29], v[156:159], v[196:199], v[26:29]
	v_mfma_f32_16x16x32_bf16 v[14:17], v[148:151], v[212:215], v[14:17]
	v_mfma_f32_16x16x32_bf16 v[10:13], v[156:159], v[212:215], v[10:13]
	v_mfma_f32_16x16x32_bf16 v[62:65], v[152:155], v[184:187], v[62:65]
	v_mfma_f32_16x16x32_bf16 v[58:61], v[160:163], v[184:187], v[58:61]
	v_mfma_f32_16x16x32_bf16 v[46:49], v[152:155], v[192:195], v[46:49]
	v_mfma_f32_16x16x32_bf16 v[42:45], v[160:163], v[192:195], v[42:45]
	v_mfma_f32_16x16x32_bf16 v[30:33], v[152:155], v[208:211], v[30:33]
	v_mfma_f32_16x16x32_bf16 v[26:29], v[160:163], v[208:211], v[26:29]
	v_mfma_f32_16x16x32_bf16 v[14:17], v[152:155], v[216:219], v[14:17]
	v_mfma_f32_16x16x32_bf16 v[10:13], v[160:163], v[216:219], v[10:13]
	s_setprio 0
	s_setprio 1
	v_mfma_f32_16x16x32_bf16 v[54:57], v[164:167], v[180:183], v[54:57]
	v_mfma_f32_16x16x32_bf16 v[50:53], v[172:175], v[180:183], v[50:53]
	v_mfma_f32_16x16x32_bf16 v[38:41], v[164:167], v[188:191], v[38:41]
	v_mfma_f32_16x16x32_bf16 v[34:37], v[172:175], v[188:191], v[34:37]
	v_mfma_f32_16x16x32_bf16 v[22:25], v[164:167], v[196:199], v[22:25]
	v_mfma_f32_16x16x32_bf16 v[18:21], v[172:175], v[196:199], v[18:21]
	v_mfma_f32_16x16x32_bf16 v[6:9], v[164:167], v[212:215], v[6:9]
	v_mfma_f32_16x16x32_bf16 v[2:5], v[172:175], v[212:215], v[2:5]
	v_mfma_f32_16x16x32_bf16 v[54:57], v[168:171], v[184:187], v[54:57]
	v_mfma_f32_16x16x32_bf16 v[50:53], v[176:179], v[184:187], v[50:53]
	v_mfma_f32_16x16x32_bf16 v[38:41], v[168:171], v[192:195], v[38:41]
	v_mfma_f32_16x16x32_bf16 v[34:37], v[176:179], v[192:195], v[34:37]
	v_mfma_f32_16x16x32_bf16 v[22:25], v[168:171], v[208:211], v[22:25]
	v_mfma_f32_16x16x32_bf16 v[18:21], v[176:179], v[208:211], v[18:21]
	v_mfma_f32_16x16x32_bf16 v[6:9], v[168:171], v[216:219], v[6:9]
	v_mfma_f32_16x16x32_bf16 v[2:5], v[176:179], v[216:219], v[2:5]
	s_setprio 0
	s_add_i32 s58, s58, 2
	s_add_u32 s22, s22, 0x100
	s_addc_u32 s23, s23, 0
	s_add_u32 s41, s41, 0x100
	s_addc_u32 s49, s49, 0
	s_cmp_gt_u32 s58, 29
	s_cbranch_scc1 .Lrot_exit_6
	s_add_u32 s0, s22, 0xfff80080
	s_addc_u32 s1, s23, -1
	s_add_i32 s33, 0, 0x10000
	s_cmp_eq_u32 s58, 28
	s_cselect_b32 s5, s17, s1
	s_cselect_b32 s4, s39, s0
	v_add_u32_e32 v143, s33, v145
	s_cselect_b32 s3, s15, s49
	s_cselect_b32 s2, s40, s41
	s_add_i32 s55, 0, 0x14000
	s_barrier
	s_branch .LBB0_1115

.LBB0_1362:
	s_add_i32 s31, s31, 1
	s_mul_i32 s4, s31, s96
	s_mov_b64 s[2:3], s[8:9]
	s_mov_b32 s8, s34
	s_mov_b32 s37, s34
	s_add_i32 s34, s4, s56
	s_cmpk_lt_i32 s34, 0x200
	s_mov_b32 s9, s35
	s_mov_b32 s36, s35
	s_cselect_b64 s[18:19], -1, 0
	s_ashr_i32 s35, s34, 2
	s_and_b64 s[4:5], s[18:19], exec
	s_cselect_b32 s8, s34, s8
	s_cselect_b32 s4, s35, s9
	s_ashr_i32 s9, s8, 31
	s_lshl_b64 s[8:9], s[8:9], 18
	s_mov_b64 s[0:1], s[16:17]
	s_add_u32 s16, s78, s8
	s_addc_u32 s17, s79, s9
	s_and_b64 s[8:9], s[18:19], exec
	s_cselect_b32 s38, s17, s1
	s_cselect_b32 s39, s16, s0
	s_ashr_i32 s5, s4, 31
	s_lshl_b64 s[4:5], s[4:5], 18
	s_add_u32 s8, s22, s4
	s_addc_u32 s9, s23, s5
	s_and_b64 s[4:5], s[18:19], exec
	s_cselect_b32 s40, s9, s3
	s_cselect_b32 s41, s8, s2
	s_add_u32 s20, s0, 0x20080
	s_addc_u32 s21, s1, 0
	s_add_u32 s49, s2, 0x100
	v_mov_b32_e32 v2, 0
	s_addc_u32 s58, s3, 0
	s_mov_b32 s59, -2
	v_mov_b32_e32 v3, v2
	v_mov_b32_e32 v4, v2
	v_mov_b32_e32 v5, v2
	v_mov_b32_e32 v6, v2
	v_mov_b32_e32 v7, v2
	v_mov_b32_e32 v8, v2
	v_mov_b32_e32 v9, v2
	v_mov_b32_e32 v18, v2
	v_mov_b32_e32 v19, v2
	v_mov_b32_e32 v20, v2
	v_mov_b32_e32 v21, v2
	v_mov_b32_e32 v22, v2
	v_mov_b32_e32 v23, v2
	v_mov_b32_e32 v24, v2
	v_mov_b32_e32 v25, v2
	v_mov_b32_e32 v34, v2
	v_mov_b32_e32 v35, v2
	v_mov_b32_e32 v36, v2
	v_mov_b32_e32 v37, v2
	v_mov_b32_e32 v38, v2
	v_mov_b32_e32 v39, v2
	v_mov_b32_e32 v40, v2
	v_mov_b32_e32 v41, v2
	v_mov_b32_e32 v50, v2
	v_mov_b32_e32 v51, v2
	v_mov_b32_e32 v52, v2
	v_mov_b32_e32 v53, v2
	v_mov_b32_e32 v54, v2
	v_mov_b32_e32 v55, v2
	v_mov_b32_e32 v56, v2
	v_mov_b32_e32 v57, v2
	v_mov_b32_e32 v10, v2
	v_mov_b32_e32 v11, v2
	v_mov_b32_e32 v12, v2
	v_mov_b32_e32 v13, v2
	v_mov_b32_e32 v14, v2
	v_mov_b32_e32 v15, v2
	v_mov_b32_e32 v16, v2
	v_mov_b32_e32 v17, v2
	v_mov_b32_e32 v26, v2
	v_mov_b32_e32 v27, v2
	v_mov_b32_e32 v28, v2
	v_mov_b32_e32 v29, v2
	v_mov_b32_e32 v30, v2
	v_mov_b32_e32 v31, v2
	v_mov_b32_e32 v32, v2
	v_mov_b32_e32 v33, v2
	v_mov_b32_e32 v42, v2
	v_mov_b32_e32 v43, v2
	v_mov_b32_e32 v44, v2
	v_mov_b32_e32 v45, v2
	v_mov_b32_e32 v46, v2
	v_mov_b32_e32 v47, v2
	v_mov_b32_e32 v48, v2
	v_mov_b32_e32 v49, v2
	v_mov_b32_e32 v58, v2
	v_mov_b32_e32 v59, v2
	v_mov_b32_e32 v60, v2
	v_mov_b32_e32 v61, v2
	v_mov_b32_e32 v62, v2
	v_mov_b32_e32 v63, v2
	v_mov_b32_e32 v64, v2
	v_mov_b32_e32 v65, v2
	v_mov_b32_e32 v66, v2
	v_mov_b32_e32 v67, v2
	v_mov_b32_e32 v68, v2
	v_mov_b32_e32 v69, v2
	v_mov_b32_e32 v70, v2
	v_mov_b32_e32 v71, v2
	v_mov_b32_e32 v72, v2
	v_mov_b32_e32 v73, v2
	v_mov_b32_e32 v82, v2
	v_mov_b32_e32 v83, v2
	v_mov_b32_e32 v84, v2
	v_mov_b32_e32 v85, v2
	v_mov_b32_e32 v86, v2
	v_mov_b32_e32 v87, v2
	v_mov_b32_e32 v88, v2
	v_mov_b32_e32 v89, v2
	v_mov_b32_e32 v98, v2
	v_mov_b32_e32 v99, v2
	v_mov_b32_e32 v100, v2
	v_mov_b32_e32 v101, v2
	v_mov_b32_e32 v102, v2
	v_mov_b32_e32 v103, v2
	v_mov_b32_e32 v104, v2
	v_mov_b32_e32 v105, v2
	v_mov_b32_e32 v114, v2
	v_mov_b32_e32 v115, v2
	v_mov_b32_e32 v116, v2
	v_mov_b32_e32 v117, v2
	v_mov_b32_e32 v118, v2
	v_mov_b32_e32 v119, v2
	v_mov_b32_e32 v120, v2
	v_mov_b32_e32 v121, v2
	v_mov_b32_e32 v74, v2
	v_mov_b32_e32 v75, v2
	v_mov_b32_e32 v76, v2
	v_mov_b32_e32 v77, v2
	v_mov_b32_e32 v78, v2
	v_mov_b32_e32 v79, v2
	v_mov_b32_e32 v80, v2
	v_mov_b32_e32 v81, v2
	v_mov_b32_e32 v90, v2
	v_mov_b32_e32 v91, v2
	v_mov_b32_e32 v92, v2
	v_mov_b32_e32 v93, v2
	v_mov_b32_e32 v94, v2
	v_mov_b32_e32 v95, v2
	v_mov_b32_e32 v96, v2
	v_mov_b32_e32 v97, v2
	v_mov_b32_e32 v106, v2
	v_mov_b32_e32 v107, v2
	v_mov_b32_e32 v108, v2
	v_mov_b32_e32 v109, v2
	v_mov_b32_e32 v110, v2
	v_mov_b32_e32 v111, v2
	v_mov_b32_e32 v112, v2
	v_mov_b32_e32 v113, v2
	v_mov_b32_e32 v122, v2
	v_mov_b32_e32 v123, v2
	v_mov_b32_e32 v124, v2
	v_mov_b32_e32 v125, v2
	v_mov_b32_e32 v126, v2
	v_mov_b32_e32 v127, v2
	v_mov_b32_e32 v128, v2
	v_mov_b32_e32 v129, v2
	s_add_u32 s0, s20, 0xfffe0080
	s_addc_u32 s1, s21, -1
	s_add_i32 s33, 0, 0x10000
	s_cmp_eq_u32 s59, 4
	s_cselect_b32 s5, s38, s1
	s_cselect_b32 s4, s39, s0
	v_add_u32_e32 v147, s33, v143
	s_cselect_b32 s3, s40, s58
	s_cselect_b32 s2, s41, s49
	s_add_i32 s55, 0, 0x14000
.LBB0_1363:
	ds_read_b128 v[148:151], v147
	ds_read_b128 v[152:155], v147 offset:1024
	ds_read_b128 v[156:159], v147 offset:2048
	ds_read_b128 v[160:163], v147 offset:3072
	v_add_u32_e32 v147, s55, v143
	ds_read_b128 v[164:167], v147
	ds_read_b128 v[168:171], v147 offset:1024
	ds_read_b128 v[172:175], v147 offset:2048
	ds_read_b128 v[176:179], v147 offset:3072
	v_lshl_add_u64 v[200:201], s[20:21], 0, v[138:139]
	s_add_i32 m0, s25, 0xc000
	ds_read_b128 v[180:183], v146
	ds_read_b128 v[184:187], v146 offset:1024
	ds_read_b128 v[188:191], v146 offset:2048
	ds_read_b128 v[192:195], v146 offset:3072
	ds_read_b128 v[196:199], v146 offset:4096
	ds_read_b128 v[208:211], v146 offset:5120
	ds_read_b128 v[212:215], v146 offset:6144
	ds_read_b128 v[216:219], v146 offset:7168
	global_load_lds_dwordx4 v[200:201], off
	v_lshl_add_u64 v[200:201], s[20:21], 0, v[140:141]
	s_add_i32 m0, s25, 0xe000
	s_nop 0
	global_load_lds_dwordx4 v[200:201], off
	s_waitcnt vmcnt(8)
	s_waitcnt lgkmcnt(0)
	s_barrier
	s_setprio 1
	s_waitcnt lgkmcnt(0)
	v_mfma_f32_16x16x32_bf16 v[126:129], v[148:151], v[180:183], v[126:129]
	v_mfma_f32_16x16x32_bf16 v[122:125], v[156:159], v[180:183], v[122:125]
	v_mfma_f32_16x16x32_bf16 v[110:113], v[148:151], v[188:191], v[110:113]
	v_mfma_f32_16x16x32_bf16 v[106:109], v[156:159], v[188:191], v[106:109]
	v_mfma_f32_16x16x32_bf16 v[94:97], v[148:151], v[196:199], v[94:97]
	v_mfma_f32_16x16x32_bf16 v[90:93], v[156:159], v[196:199], v[90:93]
	v_mfma_f32_16x16x32_bf16 v[78:81], v[148:151], v[212:215], v[78:81]
	v_mfma_f32_16x16x32_bf16 v[74:77], v[156:159], v[212:215], v[74:77]
	v_mfma_f32_16x16x32_bf16 v[126:129], v[152:155], v[184:187], v[126:129]
	v_mfma_f32_16x16x32_bf16 v[122:125], v[160:163], v[184:187], v[122:125]
	v_mfma_f32_16x16x32_bf16 v[110:113], v[152:155], v[192:195], v[110:113]
	v_mfma_f32_16x16x32_bf16 v[106:109], v[160:163], v[192:195], v[106:109]
	v_mfma_f32_16x16x32_bf16 v[94:97], v[152:155], v[208:211], v[94:97]
	v_mfma_f32_16x16x32_bf16 v[90:93], v[160:163], v[208:211], v[90:93]
	v_mfma_f32_16x16x32_bf16 v[78:81], v[152:155], v[216:219], v[78:81]
	v_mfma_f32_16x16x32_bf16 v[74:77], v[160:163], v[216:219], v[74:77]
	s_setprio 0
	s_setprio 1
	v_mfma_f32_16x16x32_bf16 v[118:121], v[164:167], v[180:183], v[118:121]
	v_mfma_f32_16x16x32_bf16 v[114:117], v[172:175], v[180:183], v[114:117]
	v_mfma_f32_16x16x32_bf16 v[102:105], v[164:167], v[188:191], v[102:105]
	v_mfma_f32_16x16x32_bf16 v[98:101], v[172:175], v[188:191], v[98:101]
	v_mfma_f32_16x16x32_bf16 v[86:89], v[164:167], v[196:199], v[86:89]
	v_mfma_f32_16x16x32_bf16 v[82:85], v[172:175], v[196:199], v[82:85]
	v_mfma_f32_16x16x32_bf16 v[70:73], v[164:167], v[212:215], v[70:73]
	v_mfma_f32_16x16x32_bf16 v[66:69], v[172:175], v[212:215], v[66:69]
	v_mfma_f32_16x16x32_bf16 v[118:121], v[168:171], v[184:187], v[118:121]
	v_mfma_f32_16x16x32_bf16 v[114:117], v[176:179], v[184:187], v[114:117]
	v_mfma_f32_16x16x32_bf16 v[102:105], v[168:171], v[192:195], v[102:105]
	v_mfma_f32_16x16x32_bf16 v[98:101], v[176:179], v[192:195], v[98:101]
	v_mfma_f32_16x16x32_bf16 v[86:89], v[168:171], v[208:211], v[86:89]
	v_mfma_f32_16x16x32_bf16 v[82:85], v[176:179], v[208:211], v[82:85]
	v_mfma_f32_16x16x32_bf16 v[70:73], v[168:171], v[216:219], v[70:73]
	v_mfma_f32_16x16x32_bf16 v[66:69], v[176:179], v[216:219], v[66:69]
	s_setprio 0
	s_barrier
	s_add_i32 s0, s33, s24
	v_lshl_add_u64 v[200:201], s[2:3], 0, v[134:135]
	s_mov_b32 m0, s0
	ds_read_b128 v[180:183], v146 offset:16384
	ds_read_b128 v[184:187], v146 offset:17408
	ds_read_b128 v[188:191], v146 offset:18432
	ds_read_b128 v[192:195], v146 offset:19456
	ds_read_b128 v[196:199], v146 offset:20480
	ds_read_b128 v[208:211], v146 offset:21504
	ds_read_b128 v[212:215], v146 offset:22528
	ds_read_b128 v[216:219], v146 offset:23552
	global_load_lds_dwordx4 v[200:201], off
	s_add_i32 m0, s0, 0x2000
	s_add_u32 s0, s2, 0x20000
	v_lshl_add_u64 v[204:205], s[2:3], 0, v[130:131]
	s_addc_u32 s1, s3, 0
	s_add_i32 s33, s55, s24
	global_load_lds_dwordx4 v[204:205], off
	v_lshl_add_u64 v[206:207], s[0:1], 0, v[134:135]
	s_mov_b32 m0, s33
	v_lshl_add_u64 v[220:221], s[4:5], 0, v[132:133]
	global_load_lds_dwordx4 v[206:207], off
	v_lshl_add_u64 v[206:207], s[0:1], 0, v[130:131]
	s_add_i32 m0, s33, 0x2000
	s_nop 0
	global_load_lds_dwordx4 v[206:207], off
	v_lshl_add_u64 v[206:207], s[4:5], 0, v[136:137]
	s_mov_b32 m0, s25
	s_nop 0
	global_load_lds_dwordx4 v[206:207], off
	s_mov_b32 m0, s26
	s_nop 0
	global_load_lds_dwordx4 v[220:221], off
	s_waitcnt vmcnt(8)
	s_waitcnt lgkmcnt(0)
	s_barrier
	s_setprio 1
	s_waitcnt lgkmcnt(0)
	v_mfma_f32_16x16x32_bf16 v[62:65], v[148:151], v[180:183], v[62:65]
	v_mfma_f32_16x16x32_bf16 v[58:61], v[156:159], v[180:183], v[58:61]
	v_mfma_f32_16x16x32_bf16 v[46:49], v[148:151], v[188:191], v[46:49]
	v_mfma_f32_16x16x32_bf16 v[42:45], v[156:159], v[188:191], v[42:45]
	v_mfma_f32_16x16x32_bf16 v[30:33], v[148:151], v[196:199], v[30:33]
	v_mfma_f32_16x16x32_bf16 v[26:29], v[156:159], v[196:199], v[26:29]
	v_mfma_f32_16x16x32_bf16 v[14:17], v[148:151], v[212:215], v[14:17]
	v_mfma_f32_16x16x32_bf16 v[10:13], v[156:159], v[212:215], v[10:13]
	v_mfma_f32_16x16x32_bf16 v[62:65], v[152:155], v[184:187], v[62:65]
	v_mfma_f32_16x16x32_bf16 v[58:61], v[160:163], v[184:187], v[58:61]
	v_mfma_f32_16x16x32_bf16 v[46:49], v[152:155], v[192:195], v[46:49]
	v_mfma_f32_16x16x32_bf16 v[42:45], v[160:163], v[192:195], v[42:45]
	v_mfma_f32_16x16x32_bf16 v[30:33], v[152:155], v[208:211], v[30:33]
	v_mfma_f32_16x16x32_bf16 v[26:29], v[160:163], v[208:211], v[26:29]
	v_mfma_f32_16x16x32_bf16 v[14:17], v[152:155], v[216:219], v[14:17]
	v_mfma_f32_16x16x32_bf16 v[10:13], v[160:163], v[216:219], v[10:13]
	s_setprio 0
	s_setprio 1
	v_mfma_f32_16x16x32_bf16 v[54:57], v[164:167], v[180:183], v[54:57]
	v_mfma_f32_16x16x32_bf16 v[50:53], v[172:175], v[180:183], v[50:53]
	v_mfma_f32_16x16x32_bf16 v[38:41], v[164:167], v[188:191], v[38:41]
	v_mfma_f32_16x16x32_bf16 v[34:37], v[172:175], v[188:191], v[34:37]
	v_mfma_f32_16x16x32_bf16 v[22:25], v[164:167], v[196:199], v[22:25]
	v_mfma_f32_16x16x32_bf16 v[18:21], v[172:175], v[196:199], v[18:21]
	v_mfma_f32_16x16x32_bf16 v[6:9], v[164:167], v[212:215], v[6:9]
	v_mfma_f32_16x16x32_bf16 v[2:5], v[172:175], v[212:215], v[2:5]
	v_mfma_f32_16x16x32_bf16 v[54:57], v[168:171], v[184:187], v[54:57]
	v_mfma_f32_16x16x32_bf16 v[50:53], v[176:179], v[184:187], v[50:53]
	v_mfma_f32_16x16x32_bf16 v[38:41], v[168:171], v[192:195], v[38:41]
	v_mfma_f32_16x16x32_bf16 v[34:37], v[176:179], v[192:195], v[34:37]
	v_mfma_f32_16x16x32_bf16 v[22:25], v[168:171], v[208:211], v[22:25]
	v_mfma_f32_16x16x32_bf16 v[18:21], v[176:179], v[208:211], v[18:21]
	v_mfma_f32_16x16x32_bf16 v[6:9], v[168:171], v[216:219], v[6:9]
	v_mfma_f32_16x16x32_bf16 v[2:5], v[176:179], v[216:219], v[2:5]
	s_setprio 0
	s_barrier
	s_add_i32 s33, 0, 0x18000
	v_add_u32_e32 v147, s33, v143
	s_add_i32 s55, 0, 0x1c000
	ds_read_b128 v[148:151], v147
	ds_read_b128 v[152:155], v147 offset:1024
	ds_read_b128 v[156:159], v147 offset:2048
	ds_read_b128 v[160:163], v147 offset:3072
	v_add_u32_e32 v147, s55, v143
	ds_read_b128 v[164:167], v147
	ds_read_b128 v[168:171], v147 offset:1024
	ds_read_b128 v[172:175], v147 offset:2048
	ds_read_b128 v[176:179], v147 offset:3072
	s_add_u32 s0, s4, 0x20000
	s_addc_u32 s1, s5, 0
	s_mov_b32 m0, s27
	v_lshl_add_u64 v[222:223], s[0:1], 0, v[136:137]
	ds_read_b128 v[180:183], v146 offset:32768
	ds_read_b128 v[184:187], v146 offset:33792
	ds_read_b128 v[188:191], v146 offset:34816
	ds_read_b128 v[192:195], v146 offset:35840
	ds_read_b128 v[196:199], v146 offset:36864
	ds_read_b128 v[208:211], v146 offset:37888
	ds_read_b128 v[212:215], v146 offset:38912
	ds_read_b128 v[216:219], v146 offset:39936
	global_load_lds_dwordx4 v[222:223], off
	v_lshl_add_u64 v[222:223], s[0:1], 0, v[132:133]
	s_mov_b32 m0, s28
	s_nop 0
	global_load_lds_dwordx4 v[222:223], off
	s_waitcnt vmcnt(8)
	s_waitcnt lgkmcnt(0)
	s_barrier
	s_setprio 1
	s_waitcnt lgkmcnt(0)
	v_mfma_f32_16x16x32_bf16 v[126:129], v[148:151], v[180:183], v[126:129]
	v_mfma_f32_16x16x32_bf16 v[122:125], v[156:159], v[180:183], v[122:125]
	v_mfma_f32_16x16x32_bf16 v[110:113], v[148:151], v[188:191], v[110:113]
	v_mfma_f32_16x16x32_bf16 v[106:109], v[156:159], v[188:191], v[106:109]
	v_mfma_f32_16x16x32_bf16 v[94:97], v[148:151], v[196:199], v[94:97]
	v_mfma_f32_16x16x32_bf16 v[90:93], v[156:159], v[196:199], v[90:93]
	v_mfma_f32_16x16x32_bf16 v[78:81], v[148:151], v[212:215], v[78:81]
	v_mfma_f32_16x16x32_bf16 v[74:77], v[156:159], v[212:215], v[74:77]
	v_mfma_f32_16x16x32_bf16 v[126:129], v[152:155], v[184:187], v[126:129]
	v_mfma_f32_16x16x32_bf16 v[122:125], v[160:163], v[184:187], v[122:125]
	v_mfma_f32_16x16x32_bf16 v[110:113], v[152:155], v[192:195], v[110:113]
	v_mfma_f32_16x16x32_bf16 v[106:109], v[160:163], v[192:195], v[106:109]
	v_mfma_f32_16x16x32_bf16 v[94:97], v[152:155], v[208:211], v[94:97]
	v_mfma_f32_16x16x32_bf16 v[90:93], v[160:163], v[208:211], v[90:93]
	v_mfma_f32_16x16x32_bf16 v[78:81], v[152:155], v[216:219], v[78:81]
	v_mfma_f32_16x16x32_bf16 v[74:77], v[160:163], v[216:219], v[74:77]
	s_setprio 0
	s_setprio 1
	v_mfma_f32_16x16x32_bf16 v[118:121], v[164:167], v[180:183], v[118:121]
	v_mfma_f32_16x16x32_bf16 v[114:117], v[172:175], v[180:183], v[114:117]
	v_mfma_f32_16x16x32_bf16 v[102:105], v[164:167], v[188:191], v[102:105]
	v_mfma_f32_16x16x32_bf16 v[98:101], v[172:175], v[188:191], v[98:101]
	v_mfma_f32_16x16x32_bf16 v[86:89], v[164:167], v[196:199], v[86:89]
	v_mfma_f32_16x16x32_bf16 v[82:85], v[172:175], v[196:199], v[82:85]
	v_mfma_f32_16x16x32_bf16 v[70:73], v[164:167], v[212:215], v[70:73]
	v_mfma_f32_16x16x32_bf16 v[66:69], v[172:175], v[212:215], v[66:69]
	v_mfma_f32_16x16x32_bf16 v[118:121], v[168:171], v[184:187], v[118:121]
	v_mfma_f32_16x16x32_bf16 v[114:117], v[176:179], v[184:187], v[114:117]
	v_mfma_f32_16x16x32_bf16 v[102:105], v[168:171], v[192:195], v[102:105]
	v_mfma_f32_16x16x32_bf16 v[98:101], v[176:179], v[192:195], v[98:101]
	v_mfma_f32_16x16x32_bf16 v[86:89], v[168:171], v[208:211], v[86:89]
	v_mfma_f32_16x16x32_bf16 v[82:85], v[176:179], v[208:211], v[82:85]
	v_mfma_f32_16x16x32_bf16 v[70:73], v[168:171], v[216:219], v[70:73]
	v_mfma_f32_16x16x32_bf16 v[66:69], v[176:179], v[216:219], v[66:69]
	s_setprio 0
	s_barrier
	s_add_i32 s0, s33, s24
	v_lshl_add_u64 v[200:201], v[200:201], 0, s[80:81]
	s_mov_b32 m0, s0
	ds_read_b128 v[180:183], v146 offset:49152
	ds_read_b128 v[184:187], v146 offset:50176
	ds_read_b128 v[188:191], v146 offset:51200
	ds_read_b128 v[192:195], v146 offset:52224
	ds_read_b128 v[196:199], v146 offset:53248
	ds_read_b128 v[208:211], v146 offset:54272
	ds_read_b128 v[212:215], v146 offset:55296
	ds_read_b128 v[216:219], v146 offset:56320
	global_load_lds_dwordx4 v[200:201], off
	s_add_i32 m0, s0, 0x2000
	s_add_u32 s0, s2, 0x20080
	v_lshl_add_u64 v[200:201], v[204:205], 0, s[80:81]
	s_addc_u32 s1, s3, 0
	s_add_i32 s2, s55, s24
	global_load_lds_dwordx4 v[200:201], off
	v_lshl_add_u64 v[200:201], s[0:1], 0, v[134:135]
	s_mov_b32 m0, s2
	s_nop 0
	global_load_lds_dwordx4 v[200:201], off
	v_lshl_add_u64 v[200:201], s[0:1], 0, v[130:131]
	s_add_i32 m0, s2, 0x2000
	s_nop 0
	global_load_lds_dwordx4 v[200:201], off
	v_lshl_add_u64 v[200:201], v[206:207], 0, s[80:81]
	s_mov_b32 m0, s29
	s_nop 0
	global_load_lds_dwordx4 v[200:201], off
	v_lshl_add_u64 v[200:201], v[220:221], 0, s[80:81]
	s_mov_b32 m0, s30
	s_nop 0
	global_load_lds_dwordx4 v[200:201], off
	s_waitcnt vmcnt(8)
	s_waitcnt lgkmcnt(0)
	s_barrier
	s_setprio 1
	s_waitcnt lgkmcnt(0)
	v_mfma_f32_16x16x32_bf16 v[62:65], v[148:151], v[180:183], v[62:65]
	v_mfma_f32_16x16x32_bf16 v[58:61], v[156:159], v[180:183], v[58:61]
	v_mfma_f32_16x16x32_bf16 v[46:49], v[148:151], v[188:191], v[46:49]
	v_mfma_f32_16x16x32_bf16 v[42:45], v[156:159], v[188:191], v[42:45]
	v_mfma_f32_16x16x32_bf16 v[30:33], v[148:151], v[196:199], v[30:33]
	v_mfma_f32_16x16x32_bf16 v[26:29], v[156:159], v[196:199], v[26:29]
	v_mfma_f32_16x16x32_bf16 v[14:17], v[148:151], v[212:215], v[14:17]
	v_mfma_f32_16x16x32_bf16 v[10:13], v[156:159], v[212:215], v[10:13]
	v_mfma_f32_16x16x32_bf16 v[62:65], v[152:155], v[184:187], v[62:65]
	v_mfma_f32_16x16x32_bf16 v[58:61], v[160:163], v[184:187], v[58:61]
	v_mfma_f32_16x16x32_bf16 v[46:49], v[152:155], v[192:195], v[46:49]
	v_mfma_f32_16x16x32_bf16 v[42:45], v[160:163], v[192:195], v[42:45]
	v_mfma_f32_16x16x32_bf16 v[30:33], v[152:155], v[208:211], v[30:33]
	v_mfma_f32_16x16x32_bf16 v[26:29], v[160:163], v[208:211], v[26:29]
	v_mfma_f32_16x16x32_bf16 v[14:17], v[152:155], v[216:219], v[14:17]
	v_mfma_f32_16x16x32_bf16 v[10:13], v[160:163], v[216:219], v[10:13]
	s_setprio 0
	s_setprio 1
	v_mfma_f32_16x16x32_bf16 v[54:57], v[164:167], v[180:183], v[54:57]
	v_mfma_f32_16x16x32_bf16 v[50:53], v[172:175], v[180:183], v[50:53]
	v_mfma_f32_16x16x32_bf16 v[38:41], v[164:167], v[188:191], v[38:41]
	v_mfma_f32_16x16x32_bf16 v[34:37], v[172:175], v[188:191], v[34:37]
	v_mfma_f32_16x16x32_bf16 v[22:25], v[164:167], v[196:199], v[22:25]
	v_mfma_f32_16x16x32_bf16 v[18:21], v[172:175], v[196:199], v[18:21]
	v_mfma_f32_16x16x32_bf16 v[6:9], v[164:167], v[212:215], v[6:9]
	v_mfma_f32_16x16x32_bf16 v[2:5], v[172:175], v[212:215], v[2:5]
	v_mfma_f32_16x16x32_bf16 v[54:57], v[168:171], v[184:187], v[54:57]
	v_mfma_f32_16x16x32_bf16 v[50:53], v[176:179], v[184:187], v[50:53]
	v_mfma_f32_16x16x32_bf16 v[38:41], v[168:171], v[192:195], v[38:41]
	v_mfma_f32_16x16x32_bf16 v[34:37], v[176:179], v[192:195], v[34:37]
	v_mfma_f32_16x16x32_bf16 v[22:25], v[168:171], v[208:211], v[22:25]
	v_mfma_f32_16x16x32_bf16 v[18:21], v[176:179], v[208:211], v[18:21]
	v_mfma_f32_16x16x32_bf16 v[6:9], v[168:171], v[216:219], v[6:9]
	v_mfma_f32_16x16x32_bf16 v[2:5], v[176:179], v[216:219], v[2:5]
	s_setprio 0
	s_add_i32 s59, s59, 2
	s_add_u32 s20, s20, 0x100
	s_addc_u32 s21, s21, 0
	s_add_u32 s49, s49, 0x100
	s_addc_u32 s58, s58, 0
	s_cmp_gt_u32 s59, 5
	s_cbranch_scc1 .Lrot_exit_7
	s_add_u32 s0, s20, 0xfffe0080
	s_addc_u32 s1, s21, -1
	s_add_i32 s33, 0, 0x10000
	s_cmp_eq_u32 s59, 4
	s_cselect_b32 s5, s38, s1
	s_cselect_b32 s4, s39, s0
	v_add_u32_e32 v147, s33, v143
	s_cselect_b32 s3, s40, s58
	s_cselect_b32 s2, s41, s49
	s_add_i32 s55, 0, 0x14000
	s_barrier
	s_branch .LBB0_1363

.LBB0_1427:
	s_ashr_i32 s17, s16, 31
	s_lshl_b64 s[0:1], s[16:17], 20
	s_add_u32 s18, s64, s0
	s_addc_u32 s19, s65, s1
	s_and_b64 s[0:1], s[6:7], exec
	s_cselect_b32 s17, s19, s5
	s_cselect_b32 s49, s18, s4
	s_ashr_i32 s15, s14, 31
	s_lshl_b64 s[0:1], s[14:15], 20
	s_add_u32 s20, s28, s0
	s_addc_u32 s21, s29, s1
	s_and_b64 s[0:1], s[6:7], exec
	s_cselect_b32 s15, s21, s3
	s_cselect_b32 s58, s20, s2
	s_add_u32 s26, s4, 0x80080
	s_addc_u32 s27, s5, 0
	s_add_u32 s59, s2, 0x100
	v_mov_b32_e32 v2, 0
	s_addc_u32 s60, s3, 0
	s_mov_b32 s61, -2
	v_mov_b32_e32 v3, v2
	v_mov_b32_e32 v4, v2
	v_mov_b32_e32 v5, v2
	v_mov_b32_e32 v10, v2
	v_mov_b32_e32 v11, v2
	v_mov_b32_e32 v12, v2
	v_mov_b32_e32 v13, v2
	v_mov_b32_e32 v18, v2
	v_mov_b32_e32 v19, v2
	v_mov_b32_e32 v20, v2
	v_mov_b32_e32 v21, v2
	v_mov_b32_e32 v26, v2
	v_mov_b32_e32 v27, v2
	v_mov_b32_e32 v28, v2
	v_mov_b32_e32 v29, v2
	v_mov_b32_e32 v34, v2
	v_mov_b32_e32 v35, v2
	v_mov_b32_e32 v36, v2
	v_mov_b32_e32 v37, v2
	v_mov_b32_e32 v42, v2
	v_mov_b32_e32 v43, v2
	v_mov_b32_e32 v44, v2
	v_mov_b32_e32 v45, v2
	v_mov_b32_e32 v50, v2
	v_mov_b32_e32 v51, v2
	v_mov_b32_e32 v52, v2
	v_mov_b32_e32 v53, v2
	v_mov_b32_e32 v58, v2
	v_mov_b32_e32 v59, v2
	v_mov_b32_e32 v60, v2
	v_mov_b32_e32 v61, v2
	v_mov_b32_e32 v6, v2
	v_mov_b32_e32 v7, v2
	v_mov_b32_e32 v8, v2
	v_mov_b32_e32 v9, v2
	v_mov_b32_e32 v14, v2
	v_mov_b32_e32 v15, v2
	v_mov_b32_e32 v16, v2
	v_mov_b32_e32 v17, v2
	v_mov_b32_e32 v22, v2
	v_mov_b32_e32 v23, v2
	v_mov_b32_e32 v24, v2
	v_mov_b32_e32 v25, v2
	v_mov_b32_e32 v30, v2
	v_mov_b32_e32 v31, v2
	v_mov_b32_e32 v32, v2
	v_mov_b32_e32 v33, v2
	v_mov_b32_e32 v38, v2
	v_mov_b32_e32 v39, v2
	v_mov_b32_e32 v40, v2
	v_mov_b32_e32 v41, v2
	v_mov_b32_e32 v46, v2
	v_mov_b32_e32 v47, v2
	v_mov_b32_e32 v48, v2
	v_mov_b32_e32 v49, v2
	v_mov_b32_e32 v54, v2
	v_mov_b32_e32 v55, v2
	v_mov_b32_e32 v56, v2
	v_mov_b32_e32 v57, v2
	v_mov_b32_e32 v62, v2
	v_mov_b32_e32 v63, v2
	v_mov_b32_e32 v64, v2
	v_mov_b32_e32 v65, v2
	v_mov_b32_e32 v66, v2
	v_mov_b32_e32 v67, v2
	v_mov_b32_e32 v68, v2
	v_mov_b32_e32 v69, v2
	v_mov_b32_e32 v74, v2
	v_mov_b32_e32 v75, v2
	v_mov_b32_e32 v76, v2
	v_mov_b32_e32 v77, v2
	v_mov_b32_e32 v82, v2
	v_mov_b32_e32 v83, v2
	v_mov_b32_e32 v84, v2
	v_mov_b32_e32 v85, v2
	v_mov_b32_e32 v90, v2
	v_mov_b32_e32 v91, v2
	v_mov_b32_e32 v92, v2
	v_mov_b32_e32 v93, v2
	v_mov_b32_e32 v98, v2
	v_mov_b32_e32 v99, v2
	v_mov_b32_e32 v100, v2
	v_mov_b32_e32 v101, v2
	v_mov_b32_e32 v106, v2
	v_mov_b32_e32 v107, v2
	v_mov_b32_e32 v108, v2
	v_mov_b32_e32 v109, v2
	v_mov_b32_e32 v114, v2
	v_mov_b32_e32 v115, v2
	v_mov_b32_e32 v116, v2
	v_mov_b32_e32 v117, v2
	v_mov_b32_e32 v122, v2
	v_mov_b32_e32 v123, v2
	v_mov_b32_e32 v124, v2
	v_mov_b32_e32 v125, v2
	v_mov_b32_e32 v70, v2
	v_mov_b32_e32 v71, v2
	v_mov_b32_e32 v72, v2
	v_mov_b32_e32 v73, v2
	v_mov_b32_e32 v78, v2
	v_mov_b32_e32 v79, v2
	v_mov_b32_e32 v80, v2
	v_mov_b32_e32 v81, v2
	v_mov_b32_e32 v86, v2
	v_mov_b32_e32 v87, v2
	v_mov_b32_e32 v88, v2
	v_mov_b32_e32 v89, v2
	v_mov_b32_e32 v94, v2
	v_mov_b32_e32 v95, v2
	v_mov_b32_e32 v96, v2
	v_mov_b32_e32 v97, v2
	v_mov_b32_e32 v102, v2
	v_mov_b32_e32 v103, v2
	v_mov_b32_e32 v104, v2
	v_mov_b32_e32 v105, v2
	v_mov_b32_e32 v110, v2
	v_mov_b32_e32 v111, v2
	v_mov_b32_e32 v112, v2
	v_mov_b32_e32 v113, v2
	v_mov_b32_e32 v118, v2
	v_mov_b32_e32 v119, v2
	v_mov_b32_e32 v120, v2
	v_mov_b32_e32 v121, v2
	v_mov_b32_e32 v130, v2
	v_mov_b32_e32 v131, v2
	v_mov_b32_e32 v132, v2
	v_mov_b32_e32 v133, v2
	s_add_u32 s0, s26, 0xfff80080
	s_addc_u32 s1, s27, -1
	s_add_i32 s33, 0, 0x10000
	s_cmp_eq_u32 s61, 28
	s_cselect_b32 s5, s17, s1
	s_cselect_b32 s4, s49, s0
	s_cselect_b32 s3, s15, s60
	s_cselect_b32 s2, s58, s59
	s_add_i32 s55, 0, 0x14000
	v_add_u32_e32 v142, s33, v187
	v_add_u32_e32 v158, s55, v187
.LBB0_1428:
	ds_read_b128 v[126:129], v142
	ds_read_b128 v[134:137], v142 offset:1024
	ds_read_b128 v[138:141], v142 offset:2048
	ds_read_b128 v[142:145], v142 offset:3072
	ds_read_b128 v[146:149], v158
	ds_read_b128 v[150:153], v158 offset:1024
	ds_read_b128 v[154:157], v158 offset:2048
	ds_read_b128 v[158:161], v158 offset:3072
	v_lshl_add_u64 v[184:185], s[26:27], 0, v[168:169]
	s_add_i32 m0, s23, 0xc000
	ds_read_b128 v[172:175], v189
	ds_read_b128 v[176:179], v189 offset:1024
	ds_read_b128 v[180:183], v189 offset:2048
	ds_read_b128 v[190:193], v189 offset:3072
	ds_read_b128 v[194:197], v189 offset:4096
	ds_read_b128 v[198:201], v189 offset:5120
	ds_read_b128 v[208:211], v189 offset:6144
	ds_read_b128 v[212:215], v189 offset:7168
	global_load_lds_dwordx4 v[184:185], off
	v_lshl_add_u64 v[184:185], s[26:27], 0, v[170:171]
	s_add_i32 m0, s23, 0xe000
	s_nop 0
	global_load_lds_dwordx4 v[184:185], off
	s_waitcnt vmcnt(8)
	s_waitcnt lgkmcnt(0)
	s_barrier
	s_setprio 1
	s_waitcnt lgkmcnt(0)
	v_mfma_f32_16x16x32_bf16 v[130:133], v[126:129], v[172:175], v[130:133]
	v_mfma_f32_16x16x32_bf16 v[118:121], v[138:141], v[172:175], v[118:121]
	v_mfma_f32_16x16x32_bf16 v[110:113], v[126:129], v[180:183], v[110:113]
	v_mfma_f32_16x16x32_bf16 v[102:105], v[138:141], v[180:183], v[102:105]
	v_mfma_f32_16x16x32_bf16 v[94:97], v[126:129], v[194:197], v[94:97]
	v_mfma_f32_16x16x32_bf16 v[86:89], v[138:141], v[194:197], v[86:89]
	v_mfma_f32_16x16x32_bf16 v[78:81], v[126:129], v[208:211], v[78:81]
	v_mfma_f32_16x16x32_bf16 v[70:73], v[138:141], v[208:211], v[70:73]
	v_mfma_f32_16x16x32_bf16 v[130:133], v[134:137], v[176:179], v[130:133]
	v_mfma_f32_16x16x32_bf16 v[118:121], v[142:145], v[176:179], v[118:121]
	v_mfma_f32_16x16x32_bf16 v[110:113], v[134:137], v[190:193], v[110:113]
	v_mfma_f32_16x16x32_bf16 v[102:105], v[142:145], v[190:193], v[102:105]
	v_mfma_f32_16x16x32_bf16 v[94:97], v[134:137], v[198:201], v[94:97]
	v_mfma_f32_16x16x32_bf16 v[86:89], v[142:145], v[198:201], v[86:89]
	v_mfma_f32_16x16x32_bf16 v[78:81], v[134:137], v[212:215], v[78:81]
	v_mfma_f32_16x16x32_bf16 v[70:73], v[142:145], v[212:215], v[70:73]
	s_setprio 0
	s_setprio 1
	v_mfma_f32_16x16x32_bf16 v[122:125], v[146:149], v[172:175], v[122:125]
	v_mfma_f32_16x16x32_bf16 v[114:117], v[154:157], v[172:175], v[114:117]
	v_mfma_f32_16x16x32_bf16 v[106:109], v[146:149], v[180:183], v[106:109]
	v_mfma_f32_16x16x32_bf16 v[98:101], v[154:157], v[180:183], v[98:101]
	v_mfma_f32_16x16x32_bf16 v[90:93], v[146:149], v[194:197], v[90:93]
	v_mfma_f32_16x16x32_bf16 v[82:85], v[154:157], v[194:197], v[82:85]
	v_mfma_f32_16x16x32_bf16 v[74:77], v[146:149], v[208:211], v[74:77]
	v_mfma_f32_16x16x32_bf16 v[66:69], v[154:157], v[208:211], v[66:69]
	v_mfma_f32_16x16x32_bf16 v[122:125], v[150:153], v[176:179], v[122:125]
	v_mfma_f32_16x16x32_bf16 v[114:117], v[158:161], v[176:179], v[114:117]
	v_mfma_f32_16x16x32_bf16 v[106:109], v[150:153], v[190:193], v[106:109]
	v_mfma_f32_16x16x32_bf16 v[98:101], v[158:161], v[190:193], v[98:101]
	v_mfma_f32_16x16x32_bf16 v[90:93], v[150:153], v[198:201], v[90:93]
	v_mfma_f32_16x16x32_bf16 v[82:85], v[158:161], v[198:201], v[82:85]
	v_mfma_f32_16x16x32_bf16 v[74:77], v[150:153], v[212:215], v[74:77]
	v_mfma_f32_16x16x32_bf16 v[66:69], v[158:161], v[212:215], v[66:69]
	s_setprio 0
	s_barrier
	s_add_i32 s0, s33, s34
	v_lshl_add_u64 v[184:185], s[2:3], 0, v[202:203]
	s_mov_b32 m0, s0
	ds_read_b128 v[172:175], v189 offset:16384
	ds_read_b128 v[176:179], v189 offset:17408
	ds_read_b128 v[180:183], v189 offset:18432
	ds_read_b128 v[190:193], v189 offset:19456
	ds_read_b128 v[194:197], v189 offset:20480
	ds_read_b128 v[198:201], v189 offset:21504
	ds_read_b128 v[208:211], v189 offset:22528
	ds_read_b128 v[212:215], v189 offset:23552
	global_load_lds_dwordx4 v[184:185], off
	s_add_i32 m0, s0, 0x2000
	s_add_u32 s0, s2, 0x80000
	v_lshl_add_u64 v[204:205], s[2:3], 0, v[162:163]
	s_addc_u32 s1, s3, 0
	s_add_i32 s33, s55, s34
	global_load_lds_dwordx4 v[204:205], off
	v_lshl_add_u64 v[206:207], s[0:1], 0, v[202:203]
	s_mov_b32 m0, s33
	v_lshl_add_u64 v[216:217], s[4:5], 0, v[164:165]
	global_load_lds_dwordx4 v[206:207], off
	v_lshl_add_u64 v[206:207], s[0:1], 0, v[162:163]
	s_add_i32 m0, s33, 0x2000
	s_nop 0
	global_load_lds_dwordx4 v[206:207], off
	v_lshl_add_u64 v[206:207], s[4:5], 0, v[166:167]
	s_mov_b32 m0, s23
	s_nop 0
	global_load_lds_dwordx4 v[206:207], off
	s_mov_b32 m0, s25
	s_nop 0
	global_load_lds_dwordx4 v[216:217], off
	s_waitcnt vmcnt(8)
	s_waitcnt lgkmcnt(0)
	s_barrier
	s_setprio 1
	s_waitcnt lgkmcnt(0)
	v_mfma_f32_16x16x32_bf16 v[62:65], v[126:129], v[172:175], v[62:65]
	v_mfma_f32_16x16x32_bf16 v[54:57], v[138:141], v[172:175], v[54:57]
	v_mfma_f32_16x16x32_bf16 v[46:49], v[126:129], v[180:183], v[46:49]
	v_mfma_f32_16x16x32_bf16 v[38:41], v[138:141], v[180:183], v[38:41]
	v_mfma_f32_16x16x32_bf16 v[30:33], v[126:129], v[194:197], v[30:33]
	v_mfma_f32_16x16x32_bf16 v[22:25], v[138:141], v[194:197], v[22:25]
	v_mfma_f32_16x16x32_bf16 v[14:17], v[126:129], v[208:211], v[14:17]
	v_mfma_f32_16x16x32_bf16 v[6:9], v[138:141], v[208:211], v[6:9]
	v_mfma_f32_16x16x32_bf16 v[62:65], v[134:137], v[176:179], v[62:65]
	v_mfma_f32_16x16x32_bf16 v[54:57], v[142:145], v[176:179], v[54:57]
	v_mfma_f32_16x16x32_bf16 v[46:49], v[134:137], v[190:193], v[46:49]
	v_mfma_f32_16x16x32_bf16 v[38:41], v[142:145], v[190:193], v[38:41]
	v_mfma_f32_16x16x32_bf16 v[30:33], v[134:137], v[198:201], v[30:33]
	v_mfma_f32_16x16x32_bf16 v[22:25], v[142:145], v[198:201], v[22:25]
	v_mfma_f32_16x16x32_bf16 v[14:17], v[134:137], v[212:215], v[14:17]
	v_mfma_f32_16x16x32_bf16 v[6:9], v[142:145], v[212:215], v[6:9]
	s_setprio 0
	s_setprio 1
	v_mfma_f32_16x16x32_bf16 v[58:61], v[146:149], v[172:175], v[58:61]
	v_mfma_f32_16x16x32_bf16 v[50:53], v[154:157], v[172:175], v[50:53]
	v_mfma_f32_16x16x32_bf16 v[42:45], v[146:149], v[180:183], v[42:45]
	v_mfma_f32_16x16x32_bf16 v[34:37], v[154:157], v[180:183], v[34:37]
	v_mfma_f32_16x16x32_bf16 v[26:29], v[146:149], v[194:197], v[26:29]
	v_mfma_f32_16x16x32_bf16 v[18:21], v[154:157], v[194:197], v[18:21]
	v_mfma_f32_16x16x32_bf16 v[10:13], v[146:149], v[208:211], v[10:13]
	v_mfma_f32_16x16x32_bf16 v[2:5], v[154:157], v[208:211], v[2:5]
	v_mfma_f32_16x16x32_bf16 v[58:61], v[150:153], v[176:179], v[58:61]
	v_mfma_f32_16x16x32_bf16 v[50:53], v[158:161], v[176:179], v[50:53]
	v_mfma_f32_16x16x32_bf16 v[42:45], v[150:153], v[190:193], v[42:45]
	v_mfma_f32_16x16x32_bf16 v[34:37], v[158:161], v[190:193], v[34:37]
	v_mfma_f32_16x16x32_bf16 v[26:29], v[150:153], v[198:201], v[26:29]
	v_mfma_f32_16x16x32_bf16 v[18:21], v[158:161], v[198:201], v[18:21]
	v_mfma_f32_16x16x32_bf16 v[10:13], v[150:153], v[212:215], v[10:13]
	v_mfma_f32_16x16x32_bf16 v[2:5], v[158:161], v[212:215], v[2:5]
	s_setprio 0
	s_barrier
	s_add_i32 s33, 0, 0x18000
	s_add_i32 s55, 0, 0x1c000
	v_add_u32_e32 v142, s33, v187
	v_add_u32_e32 v158, s55, v187
	ds_read_b128 v[126:129], v142
	ds_read_b128 v[134:137], v142 offset:1024
	ds_read_b128 v[138:141], v142 offset:2048
	ds_read_b128 v[142:145], v142 offset:3072
	ds_read_b128 v[146:149], v158
	ds_read_b128 v[150:153], v158 offset:1024
	ds_read_b128 v[154:157], v158 offset:2048
	ds_read_b128 v[158:161], v158 offset:3072
	s_add_u32 s0, s4, 0x80000
	s_addc_u32 s1, s5, 0
	s_mov_b32 m0, s35
	v_lshl_add_u64 v[218:219], s[0:1], 0, v[166:167]
	ds_read_b128 v[172:175], v189 offset:32768
	ds_read_b128 v[176:179], v189 offset:33792
	ds_read_b128 v[180:183], v189 offset:34816
	ds_read_b128 v[190:193], v189 offset:35840
	ds_read_b128 v[194:197], v189 offset:36864
	ds_read_b128 v[198:201], v189 offset:37888
	ds_read_b128 v[208:211], v189 offset:38912
	ds_read_b128 v[212:215], v189 offset:39936
	global_load_lds_dwordx4 v[218:219], off
	v_lshl_add_u64 v[218:219], s[0:1], 0, v[164:165]
	s_mov_b32 m0, s36
	s_nop 0
	global_load_lds_dwordx4 v[218:219], off
	s_waitcnt vmcnt(8)
	s_waitcnt lgkmcnt(0)
	s_barrier
	s_setprio 1
	s_waitcnt lgkmcnt(0)
	v_mfma_f32_16x16x32_bf16 v[130:133], v[126:129], v[172:175], v[130:133]
	v_mfma_f32_16x16x32_bf16 v[118:121], v[138:141], v[172:175], v[118:121]
	v_mfma_f32_16x16x32_bf16 v[110:113], v[126:129], v[180:183], v[110:113]
	v_mfma_f32_16x16x32_bf16 v[102:105], v[138:141], v[180:183], v[102:105]
	v_mfma_f32_16x16x32_bf16 v[94:97], v[126:129], v[194:197], v[94:97]
	v_mfma_f32_16x16x32_bf16 v[86:89], v[138:141], v[194:197], v[86:89]
	v_mfma_f32_16x16x32_bf16 v[78:81], v[126:129], v[208:211], v[78:81]
	v_mfma_f32_16x16x32_bf16 v[70:73], v[138:141], v[208:211], v[70:73]
	v_mfma_f32_16x16x32_bf16 v[130:133], v[134:137], v[176:179], v[130:133]
	v_mfma_f32_16x16x32_bf16 v[118:121], v[142:145], v[176:179], v[118:121]
	v_mfma_f32_16x16x32_bf16 v[110:113], v[134:137], v[190:193], v[110:113]
	v_mfma_f32_16x16x32_bf16 v[102:105], v[142:145], v[190:193], v[102:105]
	v_mfma_f32_16x16x32_bf16 v[94:97], v[134:137], v[198:201], v[94:97]
	v_mfma_f32_16x16x32_bf16 v[86:89], v[142:145], v[198:201], v[86:89]
	v_mfma_f32_16x16x32_bf16 v[78:81], v[134:137], v[212:215], v[78:81]
	v_mfma_f32_16x16x32_bf16 v[70:73], v[142:145], v[212:215], v[70:73]
	s_setprio 0
	s_setprio 1
	v_mfma_f32_16x16x32_bf16 v[122:125], v[146:149], v[172:175], v[122:125]
	v_mfma_f32_16x16x32_bf16 v[114:117], v[154:157], v[172:175], v[114:117]
	v_mfma_f32_16x16x32_bf16 v[106:109], v[146:149], v[180:183], v[106:109]
	v_mfma_f32_16x16x32_bf16 v[98:101], v[154:157], v[180:183], v[98:101]
	v_mfma_f32_16x16x32_bf16 v[90:93], v[146:149], v[194:197], v[90:93]
	v_mfma_f32_16x16x32_bf16 v[82:85], v[154:157], v[194:197], v[82:85]
	v_mfma_f32_16x16x32_bf16 v[74:77], v[146:149], v[208:211], v[74:77]
	v_mfma_f32_16x16x32_bf16 v[66:69], v[154:157], v[208:211], v[66:69]
	v_mfma_f32_16x16x32_bf16 v[122:125], v[150:153], v[176:179], v[122:125]
	v_mfma_f32_16x16x32_bf16 v[114:117], v[158:161], v[176:179], v[114:117]
	v_mfma_f32_16x16x32_bf16 v[106:109], v[150:153], v[190:193], v[106:109]
	v_mfma_f32_16x16x32_bf16 v[98:101], v[158:161], v[190:193], v[98:101]
	v_mfma_f32_16x16x32_bf16 v[90:93], v[150:153], v[198:201], v[90:93]
	v_mfma_f32_16x16x32_bf16 v[82:85], v[158:161], v[198:201], v[82:85]
	v_mfma_f32_16x16x32_bf16 v[74:77], v[150:153], v[212:215], v[74:77]
	v_mfma_f32_16x16x32_bf16 v[66:69], v[158:161], v[212:215], v[66:69]
	s_setprio 0
	s_barrier
	s_add_i32 s0, s33, s34
	v_lshl_add_u64 v[184:185], v[184:185], 0, s[80:81]
	s_mov_b32 m0, s0
	ds_read_b128 v[172:175], v189 offset:49152
	ds_read_b128 v[176:179], v189 offset:50176
	ds_read_b128 v[180:183], v189 offset:51200
	ds_read_b128 v[190:193], v189 offset:52224
	ds_read_b128 v[194:197], v189 offset:53248
	ds_read_b128 v[198:201], v189 offset:54272
	ds_read_b128 v[208:211], v189 offset:55296
	ds_read_b128 v[212:215], v189 offset:56320
	global_load_lds_dwordx4 v[184:185], off
	s_add_i32 m0, s0, 0x2000
	s_add_u32 s0, s2, 0x80080
	v_lshl_add_u64 v[184:185], v[204:205], 0, s[80:81]
	s_addc_u32 s1, s3, 0
	s_add_i32 s2, s55, s34
	global_load_lds_dwordx4 v[184:185], off
	v_lshl_add_u64 v[184:185], s[0:1], 0, v[202:203]
	s_mov_b32 m0, s2
	s_nop 0
	global_load_lds_dwordx4 v[184:185], off
	v_lshl_add_u64 v[184:185], s[0:1], 0, v[162:163]
	s_add_i32 m0, s2, 0x2000
	s_nop 0
	global_load_lds_dwordx4 v[184:185], off
	v_lshl_add_u64 v[184:185], v[206:207], 0, s[80:81]
	s_mov_b32 m0, s39
	s_nop 0
	global_load_lds_dwordx4 v[184:185], off
	v_lshl_add_u64 v[184:185], v[216:217], 0, s[80:81]
	s_mov_b32 m0, s40
	s_nop 0
	global_load_lds_dwordx4 v[184:185], off
	s_waitcnt vmcnt(8)
	s_waitcnt lgkmcnt(0)
	s_barrier
	s_setprio 1
	s_waitcnt lgkmcnt(0)
	v_mfma_f32_16x16x32_bf16 v[62:65], v[126:129], v[172:175], v[62:65]
	v_mfma_f32_16x16x32_bf16 v[54:57], v[138:141], v[172:175], v[54:57]
	v_mfma_f32_16x16x32_bf16 v[46:49], v[126:129], v[180:183], v[46:49]
	v_mfma_f32_16x16x32_bf16 v[38:41], v[138:141], v[180:183], v[38:41]
	v_mfma_f32_16x16x32_bf16 v[30:33], v[126:129], v[194:197], v[30:33]
	v_mfma_f32_16x16x32_bf16 v[22:25], v[138:141], v[194:197], v[22:25]
	v_mfma_f32_16x16x32_bf16 v[14:17], v[126:129], v[208:211], v[14:17]
	v_mfma_f32_16x16x32_bf16 v[6:9], v[138:141], v[208:211], v[6:9]
	v_mfma_f32_16x16x32_bf16 v[62:65], v[134:137], v[176:179], v[62:65]
	v_mfma_f32_16x16x32_bf16 v[54:57], v[142:145], v[176:179], v[54:57]
	v_mfma_f32_16x16x32_bf16 v[46:49], v[134:137], v[190:193], v[46:49]
	v_mfma_f32_16x16x32_bf16 v[38:41], v[142:145], v[190:193], v[38:41]
	v_mfma_f32_16x16x32_bf16 v[30:33], v[134:137], v[198:201], v[30:33]
	v_mfma_f32_16x16x32_bf16 v[22:25], v[142:145], v[198:201], v[22:25]
	v_mfma_f32_16x16x32_bf16 v[14:17], v[134:137], v[212:215], v[14:17]
	v_mfma_f32_16x16x32_bf16 v[6:9], v[142:145], v[212:215], v[6:9]
	s_setprio 0
	s_setprio 1
	v_mfma_f32_16x16x32_bf16 v[58:61], v[146:149], v[172:175], v[58:61]
	v_mfma_f32_16x16x32_bf16 v[50:53], v[154:157], v[172:175], v[50:53]
	v_mfma_f32_16x16x32_bf16 v[42:45], v[146:149], v[180:183], v[42:45]
	v_mfma_f32_16x16x32_bf16 v[34:37], v[154:157], v[180:183], v[34:37]
	v_mfma_f32_16x16x32_bf16 v[26:29], v[146:149], v[194:197], v[26:29]
	v_mfma_f32_16x16x32_bf16 v[18:21], v[154:157], v[194:197], v[18:21]
	v_mfma_f32_16x16x32_bf16 v[10:13], v[146:149], v[208:211], v[10:13]
	v_mfma_f32_16x16x32_bf16 v[2:5], v[154:157], v[208:211], v[2:5]
	v_mfma_f32_16x16x32_bf16 v[58:61], v[150:153], v[176:179], v[58:61]
	v_mfma_f32_16x16x32_bf16 v[50:53], v[158:161], v[176:179], v[50:53]
	v_mfma_f32_16x16x32_bf16 v[42:45], v[150:153], v[190:193], v[42:45]
	v_mfma_f32_16x16x32_bf16 v[34:37], v[158:161], v[190:193], v[34:37]
	v_mfma_f32_16x16x32_bf16 v[26:29], v[150:153], v[198:201], v[26:29]
	v_mfma_f32_16x16x32_bf16 v[18:21], v[158:161], v[198:201], v[18:21]
	v_mfma_f32_16x16x32_bf16 v[10:13], v[150:153], v[212:215], v[10:13]
	v_mfma_f32_16x16x32_bf16 v[2:5], v[158:161], v[212:215], v[2:5]
	s_setprio 0
	s_add_i32 s61, s61, 2
	s_add_u32 s26, s26, 0x100
	s_addc_u32 s27, s27, 0
	s_add_u32 s59, s59, 0x100
	s_addc_u32 s60, s60, 0
	s_cmp_gt_u32 s61, 29
	s_cbranch_scc1 .Lrot_exit_8
	s_add_u32 s0, s26, 0xfff80080
	s_addc_u32 s1, s27, -1
	s_add_i32 s33, 0, 0x10000
	s_cmp_eq_u32 s61, 28
	s_cselect_b32 s5, s17, s1
	s_cselect_b32 s4, s49, s0
	s_cselect_b32 s3, s15, s60
	s_cselect_b32 s2, s58, s59
	s_add_i32 s55, 0, 0x14000
	v_add_u32_e32 v142, s33, v187
	v_add_u32_e32 v158, s55, v187
	s_barrier
	s_branch .LBB0_1428

.LBB0_1593:
	s_ashr_i32 s19, s18, 31
	s_lshl_b64 s[0:1], s[18:19], 20
	s_add_u32 s20, s42, s0
	s_addc_u32 s21, s43, s1
	s_and_b64 s[0:1], s[8:9], exec
	s_cselect_b32 s19, s21, s5
	s_cselect_b32 s49, s20, s4
	s_ashr_i32 s17, s16, 31
	s_lshl_b64 s[0:1], s[16:17], 20
	s_add_u32 s22, s30, s0
	s_addc_u32 s23, s31, s1
	s_and_b64 s[0:1], s[8:9], exec
	s_cselect_b32 s17, s23, s3
	s_cselect_b32 s58, s22, s2
	s_add_u32 s28, s4, 0x80080
	s_addc_u32 s29, s5, 0
	s_add_u32 s59, s2, 0x100
	v_mov_b32_e32 v2, 0
	s_addc_u32 s60, s3, 0
	s_mov_b32 s61, -2
	v_mov_b32_e32 v3, v2
	v_mov_b32_e32 v4, v2
	v_mov_b32_e32 v5, v2
	v_mov_b32_e32 v10, v2
	v_mov_b32_e32 v11, v2
	v_mov_b32_e32 v12, v2
	v_mov_b32_e32 v13, v2
	v_mov_b32_e32 v18, v2
	v_mov_b32_e32 v19, v2
	v_mov_b32_e32 v20, v2
	v_mov_b32_e32 v21, v2
	v_mov_b32_e32 v26, v2
	v_mov_b32_e32 v27, v2
	v_mov_b32_e32 v28, v2
	v_mov_b32_e32 v29, v2
	v_mov_b32_e32 v34, v2
	v_mov_b32_e32 v35, v2
	v_mov_b32_e32 v36, v2
	v_mov_b32_e32 v37, v2
	v_mov_b32_e32 v42, v2
	v_mov_b32_e32 v43, v2
	v_mov_b32_e32 v44, v2
	v_mov_b32_e32 v45, v2
	v_mov_b32_e32 v50, v2
	v_mov_b32_e32 v51, v2
	v_mov_b32_e32 v52, v2
	v_mov_b32_e32 v53, v2
	v_mov_b32_e32 v58, v2
	v_mov_b32_e32 v59, v2
	v_mov_b32_e32 v60, v2
	v_mov_b32_e32 v61, v2
	v_mov_b32_e32 v6, v2
	v_mov_b32_e32 v7, v2
	v_mov_b32_e32 v8, v2
	v_mov_b32_e32 v9, v2
	v_mov_b32_e32 v14, v2
	v_mov_b32_e32 v15, v2
	v_mov_b32_e32 v16, v2
	v_mov_b32_e32 v17, v2
	v_mov_b32_e32 v22, v2
	v_mov_b32_e32 v23, v2
	v_mov_b32_e32 v24, v2
	v_mov_b32_e32 v25, v2
	v_mov_b32_e32 v30, v2
	v_mov_b32_e32 v31, v2
	v_mov_b32_e32 v32, v2
	v_mov_b32_e32 v33, v2
	v_mov_b32_e32 v38, v2
	v_mov_b32_e32 v39, v2
	v_mov_b32_e32 v40, v2
	v_mov_b32_e32 v41, v2
	v_mov_b32_e32 v46, v2
	v_mov_b32_e32 v47, v2
	v_mov_b32_e32 v48, v2
	v_mov_b32_e32 v49, v2
	v_mov_b32_e32 v54, v2
	v_mov_b32_e32 v55, v2
	v_mov_b32_e32 v56, v2
	v_mov_b32_e32 v57, v2
	v_mov_b32_e32 v62, v2
	v_mov_b32_e32 v63, v2
	v_mov_b32_e32 v64, v2
	v_mov_b32_e32 v65, v2
	v_mov_b32_e32 v66, v2
	v_mov_b32_e32 v67, v2
	v_mov_b32_e32 v68, v2
	v_mov_b32_e32 v69, v2
	v_mov_b32_e32 v74, v2
	v_mov_b32_e32 v75, v2
	v_mov_b32_e32 v76, v2
	v_mov_b32_e32 v77, v2
	v_mov_b32_e32 v82, v2
	v_mov_b32_e32 v83, v2
	v_mov_b32_e32 v84, v2
	v_mov_b32_e32 v85, v2
	v_mov_b32_e32 v90, v2
	v_mov_b32_e32 v91, v2
	v_mov_b32_e32 v92, v2
	v_mov_b32_e32 v93, v2
	v_mov_b32_e32 v98, v2
	v_mov_b32_e32 v99, v2
	v_mov_b32_e32 v100, v2
	v_mov_b32_e32 v101, v2
	v_mov_b32_e32 v106, v2
	v_mov_b32_e32 v107, v2
	v_mov_b32_e32 v108, v2
	v_mov_b32_e32 v109, v2
	v_mov_b32_e32 v114, v2
	v_mov_b32_e32 v115, v2
	v_mov_b32_e32 v116, v2
	v_mov_b32_e32 v117, v2
	v_mov_b32_e32 v122, v2
	v_mov_b32_e32 v123, v2
	v_mov_b32_e32 v124, v2
	v_mov_b32_e32 v125, v2
	v_mov_b32_e32 v70, v2
	v_mov_b32_e32 v71, v2
	v_mov_b32_e32 v72, v2
	v_mov_b32_e32 v73, v2
	v_mov_b32_e32 v78, v2
	v_mov_b32_e32 v79, v2
	v_mov_b32_e32 v80, v2
	v_mov_b32_e32 v81, v2
	v_mov_b32_e32 v86, v2
	v_mov_b32_e32 v87, v2
	v_mov_b32_e32 v88, v2
	v_mov_b32_e32 v89, v2
	v_mov_b32_e32 v94, v2
	v_mov_b32_e32 v95, v2
	v_mov_b32_e32 v96, v2
	v_mov_b32_e32 v97, v2
	v_mov_b32_e32 v102, v2
	v_mov_b32_e32 v103, v2
	v_mov_b32_e32 v104, v2
	v_mov_b32_e32 v105, v2
	v_mov_b32_e32 v110, v2
	v_mov_b32_e32 v111, v2
	v_mov_b32_e32 v112, v2
	v_mov_b32_e32 v113, v2
	v_mov_b32_e32 v118, v2
	v_mov_b32_e32 v119, v2
	v_mov_b32_e32 v120, v2
	v_mov_b32_e32 v121, v2
	v_mov_b32_e32 v126, v2
	v_mov_b32_e32 v127, v2
	v_mov_b32_e32 v128, v2
	v_mov_b32_e32 v129, v2
	s_add_u32 s0, s28, 0xfff80080
	s_addc_u32 s1, s29, -1
	s_add_i32 s33, 0, 0x10000
	s_cmp_eq_u32 s61, 28
	s_cselect_b32 s5, s19, s1
	s_cselect_b32 s4, s49, s0
	v_add_u32_e32 v140, s33, v143
	s_cselect_b32 s3, s17, s60
	s_cselect_b32 s2, s58, s59
	s_add_i32 s55, 0, 0x14000
.LBB0_1594:
	ds_read_b128 v[146:149], v140
	ds_read_b128 v[150:153], v140 offset:1024
	ds_read_b128 v[154:157], v140 offset:2048
	ds_read_b128 v[158:161], v140 offset:3072
	v_add_u32_e32 v140, s55, v143
	ds_read_b128 v[162:165], v140
	ds_read_b128 v[166:169], v140 offset:1024
	ds_read_b128 v[170:173], v140 offset:2048
	ds_read_b128 v[174:177], v140 offset:3072
	v_lshl_add_u64 v[140:141], s[28:29], 0, v[136:137]
	s_add_i32 m0, s25, 0xc000
	ds_read_b128 v[178:181], v145
	ds_read_b128 v[182:185], v145 offset:1024
	ds_read_b128 v[186:189], v145 offset:2048
	ds_read_b128 v[190:193], v145 offset:3072
	ds_read_b128 v[194:197], v145 offset:4096
	ds_read_b128 v[198:201], v145 offset:5120
	ds_read_b128 v[208:211], v145 offset:6144
	ds_read_b128 v[212:215], v145 offset:7168
	global_load_lds_dwordx4 v[140:141], off
	v_lshl_add_u64 v[140:141], s[28:29], 0, v[138:139]
	s_add_i32 m0, s25, 0xe000
	s_nop 0
	global_load_lds_dwordx4 v[140:141], off
	s_waitcnt vmcnt(8)
	s_waitcnt lgkmcnt(0)
	s_barrier
	s_setprio 1
	s_waitcnt lgkmcnt(0)
	v_mfma_f32_16x16x32_bf16 v[126:129], v[146:149], v[178:181], v[126:129]
	v_mfma_f32_16x16x32_bf16 v[118:121], v[154:157], v[178:181], v[118:121]
	v_mfma_f32_16x16x32_bf16 v[110:113], v[146:149], v[186:189], v[110:113]
	v_mfma_f32_16x16x32_bf16 v[102:105], v[154:157], v[186:189], v[102:105]
	v_mfma_f32_16x16x32_bf16 v[94:97], v[146:149], v[194:197], v[94:97]
	v_mfma_f32_16x16x32_bf16 v[86:89], v[154:157], v[194:197], v[86:89]
	v_mfma_f32_16x16x32_bf16 v[78:81], v[146:149], v[208:211], v[78:81]
	v_mfma_f32_16x16x32_bf16 v[70:73], v[154:157], v[208:211], v[70:73]
	v_mfma_f32_16x16x32_bf16 v[126:129], v[150:153], v[182:185], v[126:129]
	v_mfma_f32_16x16x32_bf16 v[118:121], v[158:161], v[182:185], v[118:121]
	v_mfma_f32_16x16x32_bf16 v[110:113], v[150:153], v[190:193], v[110:113]
	v_mfma_f32_16x16x32_bf16 v[102:105], v[158:161], v[190:193], v[102:105]
	v_mfma_f32_16x16x32_bf16 v[94:97], v[150:153], v[198:201], v[94:97]
	v_mfma_f32_16x16x32_bf16 v[86:89], v[158:161], v[198:201], v[86:89]
	v_mfma_f32_16x16x32_bf16 v[78:81], v[150:153], v[212:215], v[78:81]
	v_mfma_f32_16x16x32_bf16 v[70:73], v[158:161], v[212:215], v[70:73]
	s_setprio 0
	s_setprio 1
	v_mfma_f32_16x16x32_bf16 v[122:125], v[162:165], v[178:181], v[122:125]
	v_mfma_f32_16x16x32_bf16 v[114:117], v[170:173], v[178:181], v[114:117]
	v_mfma_f32_16x16x32_bf16 v[106:109], v[162:165], v[186:189], v[106:109]
	v_mfma_f32_16x16x32_bf16 v[98:101], v[170:173], v[186:189], v[98:101]
	v_mfma_f32_16x16x32_bf16 v[90:93], v[162:165], v[194:197], v[90:93]
	v_mfma_f32_16x16x32_bf16 v[82:85], v[170:173], v[194:197], v[82:85]
	v_mfma_f32_16x16x32_bf16 v[74:77], v[162:165], v[208:211], v[74:77]
	v_mfma_f32_16x16x32_bf16 v[66:69], v[170:173], v[208:211], v[66:69]
	v_mfma_f32_16x16x32_bf16 v[122:125], v[166:169], v[182:185], v[122:125]
	v_mfma_f32_16x16x32_bf16 v[114:117], v[174:177], v[182:185], v[114:117]
	v_mfma_f32_16x16x32_bf16 v[106:109], v[166:169], v[190:193], v[106:109]
	v_mfma_f32_16x16x32_bf16 v[98:101], v[174:177], v[190:193], v[98:101]
	v_mfma_f32_16x16x32_bf16 v[90:93], v[166:169], v[198:201], v[90:93]
	v_mfma_f32_16x16x32_bf16 v[82:85], v[174:177], v[198:201], v[82:85]
	v_mfma_f32_16x16x32_bf16 v[74:77], v[166:169], v[212:215], v[74:77]
	v_mfma_f32_16x16x32_bf16 v[66:69], v[174:177], v[212:215], v[66:69]
	s_setprio 0
	s_barrier
	s_add_i32 s0, s33, s36
	v_lshl_add_u64 v[140:141], s[2:3], 0, v[202:203]
	s_mov_b32 m0, s0
	ds_read_b128 v[178:181], v145 offset:16384
	ds_read_b128 v[182:185], v145 offset:17408
	ds_read_b128 v[186:189], v145 offset:18432
	ds_read_b128 v[190:193], v145 offset:19456
	ds_read_b128 v[194:197], v145 offset:20480
	ds_read_b128 v[198:201], v145 offset:21504
	ds_read_b128 v[208:211], v145 offset:22528
	ds_read_b128 v[212:215], v145 offset:23552
	global_load_lds_dwordx4 v[140:141], off
	s_add_i32 m0, s0, 0x2000
	s_add_u32 s0, s2, 0x80000
	v_lshl_add_u64 v[204:205], s[2:3], 0, v[130:131]
	s_addc_u32 s1, s3, 0
	s_add_i32 s33, s55, s36
	global_load_lds_dwordx4 v[204:205], off
	v_lshl_add_u64 v[206:207], s[0:1], 0, v[202:203]
	s_mov_b32 m0, s33
	v_lshl_add_u64 v[216:217], s[4:5], 0, v[132:133]
	global_load_lds_dwordx4 v[206:207], off
	v_lshl_add_u64 v[206:207], s[0:1], 0, v[130:131]
	s_add_i32 m0, s33, 0x2000
	s_nop 0
	global_load_lds_dwordx4 v[206:207], off
	v_lshl_add_u64 v[206:207], s[4:5], 0, v[134:135]
	s_mov_b32 m0, s25
	s_nop 0
	global_load_lds_dwordx4 v[206:207], off
	s_mov_b32 m0, s27
	s_nop 0
	global_load_lds_dwordx4 v[216:217], off
	s_waitcnt vmcnt(8)
	s_waitcnt lgkmcnt(0)
	s_barrier
	s_setprio 1
	s_waitcnt lgkmcnt(0)
	v_mfma_f32_16x16x32_bf16 v[62:65], v[146:149], v[178:181], v[62:65]
	v_mfma_f32_16x16x32_bf16 v[54:57], v[154:157], v[178:181], v[54:57]
	v_mfma_f32_16x16x32_bf16 v[46:49], v[146:149], v[186:189], v[46:49]
	v_mfma_f32_16x16x32_bf16 v[38:41], v[154:157], v[186:189], v[38:41]
	v_mfma_f32_16x16x32_bf16 v[30:33], v[146:149], v[194:197], v[30:33]
	v_mfma_f32_16x16x32_bf16 v[22:25], v[154:157], v[194:197], v[22:25]
	v_mfma_f32_16x16x32_bf16 v[14:17], v[146:149], v[208:211], v[14:17]
	v_mfma_f32_16x16x32_bf16 v[6:9], v[154:157], v[208:211], v[6:9]
	v_mfma_f32_16x16x32_bf16 v[62:65], v[150:153], v[182:185], v[62:65]
	v_mfma_f32_16x16x32_bf16 v[54:57], v[158:161], v[182:185], v[54:57]
	v_mfma_f32_16x16x32_bf16 v[46:49], v[150:153], v[190:193], v[46:49]
	v_mfma_f32_16x16x32_bf16 v[38:41], v[158:161], v[190:193], v[38:41]
	v_mfma_f32_16x16x32_bf16 v[30:33], v[150:153], v[198:201], v[30:33]
	v_mfma_f32_16x16x32_bf16 v[22:25], v[158:161], v[198:201], v[22:25]
	v_mfma_f32_16x16x32_bf16 v[14:17], v[150:153], v[212:215], v[14:17]
	v_mfma_f32_16x16x32_bf16 v[6:9], v[158:161], v[212:215], v[6:9]
	s_setprio 0
	s_setprio 1
	v_mfma_f32_16x16x32_bf16 v[58:61], v[162:165], v[178:181], v[58:61]
	v_mfma_f32_16x16x32_bf16 v[50:53], v[170:173], v[178:181], v[50:53]
	v_mfma_f32_16x16x32_bf16 v[42:45], v[162:165], v[186:189], v[42:45]
	v_mfma_f32_16x16x32_bf16 v[34:37], v[170:173], v[186:189], v[34:37]
	v_mfma_f32_16x16x32_bf16 v[26:29], v[162:165], v[194:197], v[26:29]
	v_mfma_f32_16x16x32_bf16 v[18:21], v[170:173], v[194:197], v[18:21]
	v_mfma_f32_16x16x32_bf16 v[10:13], v[162:165], v[208:211], v[10:13]
	v_mfma_f32_16x16x32_bf16 v[2:5], v[170:173], v[208:211], v[2:5]
	v_mfma_f32_16x16x32_bf16 v[58:61], v[166:169], v[182:185], v[58:61]
	v_mfma_f32_16x16x32_bf16 v[50:53], v[174:177], v[182:185], v[50:53]
	v_mfma_f32_16x16x32_bf16 v[42:45], v[166:169], v[190:193], v[42:45]
	v_mfma_f32_16x16x32_bf16 v[34:37], v[174:177], v[190:193], v[34:37]
	v_mfma_f32_16x16x32_bf16 v[26:29], v[166:169], v[198:201], v[26:29]
	v_mfma_f32_16x16x32_bf16 v[18:21], v[174:177], v[198:201], v[18:21]
	v_mfma_f32_16x16x32_bf16 v[10:13], v[166:169], v[212:215], v[10:13]
	v_mfma_f32_16x16x32_bf16 v[2:5], v[174:177], v[212:215], v[2:5]
	s_setprio 0
	s_barrier
	s_add_i32 s33, 0, 0x18000
	s_add_i32 s55, 0, 0x1c000
	v_add_u32_e32 v158, s33, v143
	v_add_u32_e32 v174, s55, v143
	ds_read_b128 v[146:149], v158
	ds_read_b128 v[150:153], v158 offset:1024
	ds_read_b128 v[154:157], v158 offset:2048
	ds_read_b128 v[158:161], v158 offset:3072
	ds_read_b128 v[162:165], v174
	ds_read_b128 v[166:169], v174 offset:1024
	ds_read_b128 v[170:173], v174 offset:2048
	ds_read_b128 v[174:177], v174 offset:3072
	s_add_u32 s0, s4, 0x80000
	s_addc_u32 s1, s5, 0
	s_mov_b32 m0, s37
	v_lshl_add_u64 v[218:219], s[0:1], 0, v[134:135]
	ds_read_b128 v[178:181], v145 offset:32768
	ds_read_b128 v[182:185], v145 offset:33792
	ds_read_b128 v[186:189], v145 offset:34816
	ds_read_b128 v[190:193], v145 offset:35840
	ds_read_b128 v[194:197], v145 offset:36864
	ds_read_b128 v[198:201], v145 offset:37888
	ds_read_b128 v[208:211], v145 offset:38912
	ds_read_b128 v[212:215], v145 offset:39936
	global_load_lds_dwordx4 v[218:219], off
	v_lshl_add_u64 v[218:219], s[0:1], 0, v[132:133]
	s_mov_b32 m0, s38
	s_nop 0
	global_load_lds_dwordx4 v[218:219], off
	s_waitcnt vmcnt(8)
	s_waitcnt lgkmcnt(0)
	s_barrier
	s_setprio 1
	s_waitcnt lgkmcnt(0)
	v_mfma_f32_16x16x32_bf16 v[126:129], v[146:149], v[178:181], v[126:129]
	v_mfma_f32_16x16x32_bf16 v[118:121], v[154:157], v[178:181], v[118:121]
	v_mfma_f32_16x16x32_bf16 v[110:113], v[146:149], v[186:189], v[110:113]
	v_mfma_f32_16x16x32_bf16 v[102:105], v[154:157], v[186:189], v[102:105]
	v_mfma_f32_16x16x32_bf16 v[94:97], v[146:149], v[194:197], v[94:97]
	v_mfma_f32_16x16x32_bf16 v[86:89], v[154:157], v[194:197], v[86:89]
	v_mfma_f32_16x16x32_bf16 v[78:81], v[146:149], v[208:211], v[78:81]
	v_mfma_f32_16x16x32_bf16 v[70:73], v[154:157], v[208:211], v[70:73]
	v_mfma_f32_16x16x32_bf16 v[126:129], v[150:153], v[182:185], v[126:129]
	v_mfma_f32_16x16x32_bf16 v[118:121], v[158:161], v[182:185], v[118:121]
	v_mfma_f32_16x16x32_bf16 v[110:113], v[150:153], v[190:193], v[110:113]
	v_mfma_f32_16x16x32_bf16 v[102:105], v[158:161], v[190:193], v[102:105]
	v_mfma_f32_16x16x32_bf16 v[94:97], v[150:153], v[198:201], v[94:97]
	v_mfma_f32_16x16x32_bf16 v[86:89], v[158:161], v[198:201], v[86:89]
	v_mfma_f32_16x16x32_bf16 v[78:81], v[150:153], v[212:215], v[78:81]
	v_mfma_f32_16x16x32_bf16 v[70:73], v[158:161], v[212:215], v[70:73]
	s_setprio 0
	s_setprio 1
	v_mfma_f32_16x16x32_bf16 v[122:125], v[162:165], v[178:181], v[122:125]
	v_mfma_f32_16x16x32_bf16 v[114:117], v[170:173], v[178:181], v[114:117]
	v_mfma_f32_16x16x32_bf16 v[106:109], v[162:165], v[186:189], v[106:109]
	v_mfma_f32_16x16x32_bf16 v[98:101], v[170:173], v[186:189], v[98:101]
	v_mfma_f32_16x16x32_bf16 v[90:93], v[162:165], v[194:197], v[90:93]
	v_mfma_f32_16x16x32_bf16 v[82:85], v[170:173], v[194:197], v[82:85]
	v_mfma_f32_16x16x32_bf16 v[74:77], v[162:165], v[208:211], v[74:77]
	v_mfma_f32_16x16x32_bf16 v[66:69], v[170:173], v[208:211], v[66:69]
	v_mfma_f32_16x16x32_bf16 v[122:125], v[166:169], v[182:185], v[122:125]
	v_mfma_f32_16x16x32_bf16 v[114:117], v[174:177], v[182:185], v[114:117]
	v_mfma_f32_16x16x32_bf16 v[106:109], v[166:169], v[190:193], v[106:109]
	v_mfma_f32_16x16x32_bf16 v[98:101], v[174:177], v[190:193], v[98:101]
	v_mfma_f32_16x16x32_bf16 v[90:93], v[166:169], v[198:201], v[90:93]
	v_mfma_f32_16x16x32_bf16 v[82:85], v[174:177], v[198:201], v[82:85]
	v_mfma_f32_16x16x32_bf16 v[74:77], v[166:169], v[212:215], v[74:77]
	v_mfma_f32_16x16x32_bf16 v[66:69], v[174:177], v[212:215], v[66:69]
	s_setprio 0
	s_barrier
	s_add_i32 s0, s33, s36
	v_lshl_add_u64 v[140:141], v[140:141], 0, s[80:81]
	s_mov_b32 m0, s0
	ds_read_b128 v[178:181], v145 offset:49152
	ds_read_b128 v[182:185], v145 offset:50176
	ds_read_b128 v[186:189], v145 offset:51200
	ds_read_b128 v[190:193], v145 offset:52224
	ds_read_b128 v[194:197], v145 offset:53248
	ds_read_b128 v[198:201], v145 offset:54272
	ds_read_b128 v[208:211], v145 offset:55296
	ds_read_b128 v[212:215], v145 offset:56320
	global_load_lds_dwordx4 v[140:141], off
	s_add_i32 m0, s0, 0x2000
	s_add_u32 s0, s2, 0x80080
	v_lshl_add_u64 v[140:141], v[204:205], 0, s[80:81]
	s_addc_u32 s1, s3, 0
	s_add_i32 s2, s55, s36
	global_load_lds_dwordx4 v[140:141], off
	v_lshl_add_u64 v[140:141], s[0:1], 0, v[202:203]
	s_mov_b32 m0, s2
	s_nop 0
	global_load_lds_dwordx4 v[140:141], off
	v_lshl_add_u64 v[140:141], s[0:1], 0, v[130:131]
	s_add_i32 m0, s2, 0x2000
	s_nop 0
	global_load_lds_dwordx4 v[140:141], off
	v_lshl_add_u64 v[140:141], v[206:207], 0, s[80:81]
	s_mov_b32 m0, s39
	s_nop 0
	global_load_lds_dwordx4 v[140:141], off
	v_lshl_add_u64 v[140:141], v[216:217], 0, s[80:81]
	s_mov_b32 m0, s40
	s_nop 0
	global_load_lds_dwordx4 v[140:141], off
	s_waitcnt vmcnt(8)
	s_waitcnt lgkmcnt(0)
	s_barrier
	s_setprio 1
	s_waitcnt lgkmcnt(0)
	v_mfma_f32_16x16x32_bf16 v[62:65], v[146:149], v[178:181], v[62:65]
	v_mfma_f32_16x16x32_bf16 v[54:57], v[154:157], v[178:181], v[54:57]
	v_mfma_f32_16x16x32_bf16 v[46:49], v[146:149], v[186:189], v[46:49]
	v_mfma_f32_16x16x32_bf16 v[38:41], v[154:157], v[186:189], v[38:41]
	v_mfma_f32_16x16x32_bf16 v[30:33], v[146:149], v[194:197], v[30:33]
	v_mfma_f32_16x16x32_bf16 v[22:25], v[154:157], v[194:197], v[22:25]
	v_mfma_f32_16x16x32_bf16 v[14:17], v[146:149], v[208:211], v[14:17]
	v_mfma_f32_16x16x32_bf16 v[6:9], v[154:157], v[208:211], v[6:9]
	v_mfma_f32_16x16x32_bf16 v[62:65], v[150:153], v[182:185], v[62:65]
	v_mfma_f32_16x16x32_bf16 v[54:57], v[158:161], v[182:185], v[54:57]
	v_mfma_f32_16x16x32_bf16 v[46:49], v[150:153], v[190:193], v[46:49]
	v_mfma_f32_16x16x32_bf16 v[38:41], v[158:161], v[190:193], v[38:41]
	v_mfma_f32_16x16x32_bf16 v[30:33], v[150:153], v[198:201], v[30:33]
	v_mfma_f32_16x16x32_bf16 v[22:25], v[158:161], v[198:201], v[22:25]
	v_mfma_f32_16x16x32_bf16 v[14:17], v[150:153], v[212:215], v[14:17]
	v_mfma_f32_16x16x32_bf16 v[6:9], v[158:161], v[212:215], v[6:9]
	s_setprio 0
	s_setprio 1
	v_mfma_f32_16x16x32_bf16 v[58:61], v[162:165], v[178:181], v[58:61]
	v_mfma_f32_16x16x32_bf16 v[50:53], v[170:173], v[178:181], v[50:53]
	v_mfma_f32_16x16x32_bf16 v[42:45], v[162:165], v[186:189], v[42:45]
	v_mfma_f32_16x16x32_bf16 v[34:37], v[170:173], v[186:189], v[34:37]
	v_mfma_f32_16x16x32_bf16 v[26:29], v[162:165], v[194:197], v[26:29]
	v_mfma_f32_16x16x32_bf16 v[18:21], v[170:173], v[194:197], v[18:21]
	v_mfma_f32_16x16x32_bf16 v[10:13], v[162:165], v[208:211], v[10:13]
	v_mfma_f32_16x16x32_bf16 v[2:5], v[170:173], v[208:211], v[2:5]
	v_mfma_f32_16x16x32_bf16 v[58:61], v[166:169], v[182:185], v[58:61]
	v_mfma_f32_16x16x32_bf16 v[50:53], v[174:177], v[182:185], v[50:53]
	v_mfma_f32_16x16x32_bf16 v[42:45], v[166:169], v[190:193], v[42:45]
	v_mfma_f32_16x16x32_bf16 v[34:37], v[174:177], v[190:193], v[34:37]
	v_mfma_f32_16x16x32_bf16 v[26:29], v[166:169], v[198:201], v[26:29]
	v_mfma_f32_16x16x32_bf16 v[18:21], v[174:177], v[198:201], v[18:21]
	v_mfma_f32_16x16x32_bf16 v[10:13], v[166:169], v[212:215], v[10:13]
	v_mfma_f32_16x16x32_bf16 v[2:5], v[174:177], v[212:215], v[2:5]
	s_setprio 0
	s_add_i32 s61, s61, 2
	s_add_u32 s28, s28, 0x100
	s_addc_u32 s29, s29, 0
	s_add_u32 s59, s59, 0x100
	s_addc_u32 s60, s60, 0
	s_cmp_gt_u32 s61, 29
	s_cbranch_scc1 .Lrot_exit_9
	s_add_u32 s0, s28, 0xfff80080
	s_addc_u32 s1, s29, -1
	s_add_i32 s33, 0, 0x10000
	s_cmp_eq_u32 s61, 28
	s_cselect_b32 s5, s19, s1
	s_cselect_b32 s4, s49, s0
	v_add_u32_e32 v140, s33, v143
	s_cselect_b32 s3, s17, s60
	s_cselect_b32 s2, s58, s59
	s_add_i32 s55, 0, 0x14000
	s_barrier
	s_branch .LBB0_1594

.LBB0_1717:
	s_add_u32 s49, s18, 0x100
	v_mov_b32_e32 v2, 0
	s_addc_u32 s58, s19, 0
	s_mov_b32 s59, -2
	v_mov_b32_e32 v3, v2
	v_mov_b32_e32 v4, v2
	v_mov_b32_e32 v5, v2
	v_mov_b32_e32 v6, v2
	v_mov_b32_e32 v7, v2
	v_mov_b32_e32 v8, v2
	v_mov_b32_e32 v9, v2
	v_mov_b32_e32 v18, v2
	v_mov_b32_e32 v19, v2
	v_mov_b32_e32 v20, v2
	v_mov_b32_e32 v21, v2
	v_mov_b32_e32 v22, v2
	v_mov_b32_e32 v23, v2
	v_mov_b32_e32 v24, v2
	v_mov_b32_e32 v25, v2
	v_mov_b32_e32 v34, v2
	v_mov_b32_e32 v35, v2
	v_mov_b32_e32 v36, v2
	v_mov_b32_e32 v37, v2
	v_mov_b32_e32 v38, v2
	v_mov_b32_e32 v39, v2
	v_mov_b32_e32 v40, v2
	v_mov_b32_e32 v41, v2
	v_mov_b32_e32 v50, v2
	v_mov_b32_e32 v51, v2
	v_mov_b32_e32 v52, v2
	v_mov_b32_e32 v53, v2
	v_mov_b32_e32 v54, v2
	v_mov_b32_e32 v55, v2
	v_mov_b32_e32 v56, v2
	v_mov_b32_e32 v57, v2
	v_mov_b32_e32 v10, v2
	v_mov_b32_e32 v11, v2
	v_mov_b32_e32 v12, v2
	v_mov_b32_e32 v13, v2
	v_mov_b32_e32 v14, v2
	v_mov_b32_e32 v15, v2
	v_mov_b32_e32 v16, v2
	v_mov_b32_e32 v17, v2
	v_mov_b32_e32 v26, v2
	v_mov_b32_e32 v27, v2
	v_mov_b32_e32 v28, v2
	v_mov_b32_e32 v29, v2
	v_mov_b32_e32 v30, v2
	v_mov_b32_e32 v31, v2
	v_mov_b32_e32 v32, v2
	v_mov_b32_e32 v33, v2
	v_mov_b32_e32 v42, v2
	v_mov_b32_e32 v43, v2
	v_mov_b32_e32 v44, v2
	v_mov_b32_e32 v45, v2
	v_mov_b32_e32 v46, v2
	v_mov_b32_e32 v47, v2
	v_mov_b32_e32 v48, v2
	v_mov_b32_e32 v49, v2
	v_mov_b32_e32 v58, v2
	v_mov_b32_e32 v59, v2
	v_mov_b32_e32 v60, v2
	v_mov_b32_e32 v61, v2
	v_mov_b32_e32 v62, v2
	v_mov_b32_e32 v63, v2
	v_mov_b32_e32 v64, v2
	v_mov_b32_e32 v65, v2
	v_mov_b32_e32 v66, v2
	v_mov_b32_e32 v67, v2
	v_mov_b32_e32 v68, v2
	v_mov_b32_e32 v69, v2
	v_mov_b32_e32 v70, v2
	v_mov_b32_e32 v71, v2
	v_mov_b32_e32 v72, v2
	v_mov_b32_e32 v73, v2
	v_mov_b32_e32 v90, v2
	v_mov_b32_e32 v91, v2
	v_mov_b32_e32 v92, v2
	v_mov_b32_e32 v93, v2
	v_mov_b32_e32 v102, v2
	v_mov_b32_e32 v103, v2
	v_mov_b32_e32 v104, v2
	v_mov_b32_e32 v105, v2
	v_mov_b32_e32 v122, v2
	v_mov_b32_e32 v123, v2
	v_mov_b32_e32 v124, v2
	v_mov_b32_e32 v125, v2
	v_mov_b32_e32 v130, v2
	v_mov_b32_e32 v131, v2
	v_mov_b32_e32 v132, v2
	v_mov_b32_e32 v133, v2
	v_mov_b32_e32 v150, v2
	v_mov_b32_e32 v151, v2
	v_mov_b32_e32 v152, v2
	v_mov_b32_e32 v153, v2
	v_mov_b32_e32 v154, v2
	v_mov_b32_e32 v155, v2
	v_mov_b32_e32 v156, v2
	v_mov_b32_e32 v157, v2
	v_mov_b32_e32 v74, v2
	v_mov_b32_e32 v75, v2
	v_mov_b32_e32 v76, v2
	v_mov_b32_e32 v77, v2
	v_mov_b32_e32 v86, v2
	v_mov_b32_e32 v87, v2
	v_mov_b32_e32 v88, v2
	v_mov_b32_e32 v89, v2
	v_mov_b32_e32 v114, v2
	v_mov_b32_e32 v115, v2
	v_mov_b32_e32 v116, v2
	v_mov_b32_e32 v117, v2
	v_mov_b32_e32 v118, v2
	v_mov_b32_e32 v119, v2
	v_mov_b32_e32 v120, v2
	v_mov_b32_e32 v121, v2
	v_mov_b32_e32 v138, v2
	v_mov_b32_e32 v139, v2
	v_mov_b32_e32 v140, v2
	v_mov_b32_e32 v141, v2
	v_mov_b32_e32 v142, v2
	v_mov_b32_e32 v143, v2
	v_mov_b32_e32 v144, v2
	v_mov_b32_e32 v145, v2
	v_mov_b32_e32 v162, v2
	v_mov_b32_e32 v163, v2
	v_mov_b32_e32 v164, v2
	v_mov_b32_e32 v165, v2
	v_mov_b32_e32 v170, v2
	v_mov_b32_e32 v171, v2
	v_mov_b32_e32 v172, v2
	v_mov_b32_e32 v173, v2
	s_add_u32 s18, s4, 0x100
	s_addc_u32 s19, s5, 0
	s_add_i32 s0, 0, 0x10000
	s_cmpk_eq_i32 s59, 0x54
	s_cselect_b32 s23, s9, s19
	s_cselect_b32 s22, s8, s18
	s_cselect_b32 s21, s17, s58
	s_cselect_b32 s20, s16, s49
	s_add_i32 s33, 0, 0x14000
	v_add_u32_e32 v98, s0, v205
	v_add_u32_e32 v134, s33, v205
.LBB0_1718:
	ds_read_b128 v[78:81], v98
	ds_read_b128 v[82:85], v98 offset:1024
	ds_read_b128 v[94:97], v98 offset:2048
	ds_read_b128 v[98:101], v98 offset:3072
	ds_read_b128 v[106:109], v134
	ds_read_b128 v[110:113], v134 offset:1024
	ds_read_b128 v[126:129], v134 offset:2048
	ds_read_b128 v[134:137], v134 offset:3072
	v_lshl_add_u64 v[194:195], s[4:5], 0, v[214:215]
	s_add_i32 m0, s27, 0xc000
	ds_read_b128 v[146:149], v239
	ds_read_b128 v[158:161], v239 offset:1024
	ds_read_b128 v[166:169], v239 offset:2048
	ds_read_b128 v[174:177], v239 offset:3072
	ds_read_b128 v[178:181], v239 offset:4096
	ds_read_b128 v[182:185], v239 offset:5120
	ds_read_b128 v[186:189], v239 offset:6144
	ds_read_b128 v[190:193], v239 offset:7168
	global_load_lds_dwordx4 v[194:195], off
	v_lshl_add_u64 v[194:195], s[4:5], 0, v[216:217]
	s_add_i32 m0, s27, 0xe000
	s_nop 0
	global_load_lds_dwordx4 v[194:195], off
	s_waitcnt vmcnt(8)
	s_waitcnt lgkmcnt(0)
	s_barrier
	s_setprio 1
	s_waitcnt lgkmcnt(0)
	v_mfma_f32_16x16x32_bf16 v[170:173], v[78:81], v[146:149], v[170:173]
	v_mfma_f32_16x16x32_bf16 v[162:165], v[94:97], v[146:149], v[162:165]
	v_mfma_f32_16x16x32_bf16 v[142:145], v[78:81], v[166:169], v[142:145]
	v_mfma_f32_16x16x32_bf16 v[138:141], v[94:97], v[166:169], v[138:141]
	v_mfma_f32_16x16x32_bf16 v[118:121], v[78:81], v[178:181], v[118:121]
	v_mfma_f32_16x16x32_bf16 v[114:117], v[94:97], v[178:181], v[114:117]
	v_mfma_f32_16x16x32_bf16 v[86:89], v[78:81], v[186:189], v[86:89]
	v_mfma_f32_16x16x32_bf16 v[74:77], v[94:97], v[186:189], v[74:77]
	v_mfma_f32_16x16x32_bf16 v[170:173], v[82:85], v[158:161], v[170:173]
	v_mfma_f32_16x16x32_bf16 v[162:165], v[98:101], v[158:161], v[162:165]
	v_mfma_f32_16x16x32_bf16 v[142:145], v[82:85], v[174:177], v[142:145]
	v_mfma_f32_16x16x32_bf16 v[138:141], v[98:101], v[174:177], v[138:141]
	v_mfma_f32_16x16x32_bf16 v[118:121], v[82:85], v[182:185], v[118:121]
	v_mfma_f32_16x16x32_bf16 v[114:117], v[98:101], v[182:185], v[114:117]
	v_mfma_f32_16x16x32_bf16 v[86:89], v[82:85], v[190:193], v[86:89]
	v_mfma_f32_16x16x32_bf16 v[74:77], v[98:101], v[190:193], v[74:77]
	s_setprio 0
	s_setprio 1
	v_mfma_f32_16x16x32_bf16 v[154:157], v[106:109], v[146:149], v[154:157]
	v_mfma_f32_16x16x32_bf16 v[130:133], v[106:109], v[166:169], v[130:133]
	v_mfma_f32_16x16x32_bf16 v[122:125], v[126:129], v[166:169], v[122:125]
	v_mfma_f32_16x16x32_bf16 v[102:105], v[106:109], v[178:181], v[102:105]
	v_mfma_f32_16x16x32_bf16 v[90:93], v[126:129], v[178:181], v[90:93]
	v_mfma_f32_16x16x32_bf16 v[70:73], v[106:109], v[186:189], v[70:73]
	v_mfma_f32_16x16x32_bf16 v[66:69], v[126:129], v[186:189], v[66:69]
	v_mfma_f32_16x16x32_bf16 v[154:157], v[110:113], v[158:161], v[154:157]
	v_mfma_f32_16x16x32_bf16 v[146:149], v[126:129], v[146:149], v[150:153]
	v_mfma_f32_16x16x32_bf16 v[130:133], v[110:113], v[174:177], v[130:133]
	v_mfma_f32_16x16x32_bf16 v[122:125], v[134:137], v[174:177], v[122:125]
	v_mfma_f32_16x16x32_bf16 v[102:105], v[110:113], v[182:185], v[102:105]
	v_mfma_f32_16x16x32_bf16 v[90:93], v[134:137], v[182:185], v[90:93]
	v_mfma_f32_16x16x32_bf16 v[70:73], v[110:113], v[190:193], v[70:73]
	v_mfma_f32_16x16x32_bf16 v[66:69], v[134:137], v[190:193], v[66:69]
	v_mfma_f32_16x16x32_bf16 v[146:149], v[134:137], v[158:161], v[146:149]
	s_setprio 0
	s_barrier
	s_add_i32 s0, s0, s26
	v_lshl_add_u64 v[194:195], s[20:21], 0, v[202:203]
	s_mov_b32 m0, s0
	ds_read_b128 v[150:153], v239 offset:16384
	ds_read_b128 v[158:161], v239 offset:17408
	ds_read_b128 v[166:169], v239 offset:18432
	ds_read_b128 v[174:177], v239 offset:19456
	ds_read_b128 v[178:181], v239 offset:20480
	ds_read_b128 v[182:185], v239 offset:21504
	ds_read_b128 v[186:189], v239 offset:22528
	ds_read_b128 v[190:193], v239 offset:23552
	global_load_lds_dwordx4 v[194:195], off
	s_add_i32 m0, s0, 0x2000
	s_add_u32 s0, s20, 0x160000
	v_lshl_add_u64 v[196:197], s[20:21], 0, v[208:209]
	s_addc_u32 s1, s21, 0
	s_add_i32 s4, s33, s26
	global_load_lds_dwordx4 v[196:197], off
	v_lshl_add_u64 v[198:199], s[0:1], 0, v[202:203]
	s_mov_b32 m0, s4
	v_lshl_add_u64 v[200:201], s[22:23], 0, v[210:211]
	global_load_lds_dwordx4 v[198:199], off
	v_lshl_add_u64 v[198:199], s[0:1], 0, v[208:209]
	s_add_i32 m0, s4, 0x2000
	s_nop 0
	global_load_lds_dwordx4 v[198:199], off
	v_lshl_add_u64 v[198:199], s[22:23], 0, v[212:213]
	s_mov_b32 m0, s27
	s_nop 0
	global_load_lds_dwordx4 v[198:199], off
	s_mov_b32 m0, s28
	s_nop 0
	global_load_lds_dwordx4 v[200:201], off
	s_waitcnt vmcnt(8)
	s_waitcnt lgkmcnt(0)
	s_barrier
	s_setprio 1
	s_waitcnt lgkmcnt(0)
	v_mfma_f32_16x16x32_bf16 v[62:65], v[78:81], v[150:153], v[62:65]
	v_mfma_f32_16x16x32_bf16 v[58:61], v[94:97], v[150:153], v[58:61]
	v_mfma_f32_16x16x32_bf16 v[46:49], v[78:81], v[166:169], v[46:49]
	v_mfma_f32_16x16x32_bf16 v[42:45], v[94:97], v[166:169], v[42:45]
	v_mfma_f32_16x16x32_bf16 v[30:33], v[78:81], v[178:181], v[30:33]
	v_mfma_f32_16x16x32_bf16 v[26:29], v[94:97], v[178:181], v[26:29]
	v_mfma_f32_16x16x32_bf16 v[14:17], v[78:81], v[186:189], v[14:17]
	v_mfma_f32_16x16x32_bf16 v[10:13], v[94:97], v[186:189], v[10:13]
	v_mfma_f32_16x16x32_bf16 v[62:65], v[82:85], v[158:161], v[62:65]
	v_mfma_f32_16x16x32_bf16 v[58:61], v[98:101], v[158:161], v[58:61]
	v_mfma_f32_16x16x32_bf16 v[46:49], v[82:85], v[174:177], v[46:49]
	v_mfma_f32_16x16x32_bf16 v[42:45], v[98:101], v[174:177], v[42:45]
	v_mfma_f32_16x16x32_bf16 v[30:33], v[82:85], v[182:185], v[30:33]
	v_mfma_f32_16x16x32_bf16 v[26:29], v[98:101], v[182:185], v[26:29]
	v_mfma_f32_16x16x32_bf16 v[14:17], v[82:85], v[190:193], v[14:17]
	v_mfma_f32_16x16x32_bf16 v[10:13], v[98:101], v[190:193], v[10:13]
	s_setprio 0
	s_setprio 1
	v_mfma_f32_16x16x32_bf16 v[54:57], v[106:109], v[150:153], v[54:57]
	v_mfma_f32_16x16x32_bf16 v[50:53], v[126:129], v[150:153], v[50:53]
	v_mfma_f32_16x16x32_bf16 v[38:41], v[106:109], v[166:169], v[38:41]
	v_mfma_f32_16x16x32_bf16 v[34:37], v[126:129], v[166:169], v[34:37]
	v_mfma_f32_16x16x32_bf16 v[22:25], v[106:109], v[178:181], v[22:25]
	v_mfma_f32_16x16x32_bf16 v[18:21], v[126:129], v[178:181], v[18:21]
	v_mfma_f32_16x16x32_bf16 v[6:9], v[106:109], v[186:189], v[6:9]
	v_mfma_f32_16x16x32_bf16 v[2:5], v[126:129], v[186:189], v[2:5]
	v_mfma_f32_16x16x32_bf16 v[54:57], v[110:113], v[158:161], v[54:57]
	v_mfma_f32_16x16x32_bf16 v[50:53], v[134:137], v[158:161], v[50:53]
	v_mfma_f32_16x16x32_bf16 v[38:41], v[110:113], v[174:177], v[38:41]
	v_mfma_f32_16x16x32_bf16 v[34:37], v[134:137], v[174:177], v[34:37]
	v_mfma_f32_16x16x32_bf16 v[22:25], v[110:113], v[182:185], v[22:25]
	v_mfma_f32_16x16x32_bf16 v[18:21], v[134:137], v[182:185], v[18:21]
	v_mfma_f32_16x16x32_bf16 v[6:9], v[110:113], v[190:193], v[6:9]
	v_mfma_f32_16x16x32_bf16 v[2:5], v[134:137], v[190:193], v[2:5]
	s_setprio 0
	s_barrier
	s_add_i32 s4, 0, 0x18000
	s_add_i32 s5, 0, 0x1c000
	v_add_u32_e32 v98, s4, v205
	v_add_u32_e32 v134, s5, v205
	ds_read_b128 v[78:81], v98
	ds_read_b128 v[82:85], v98 offset:1024
	ds_read_b128 v[94:97], v98 offset:2048
	ds_read_b128 v[98:101], v98 offset:3072
	ds_read_b128 v[106:109], v134
	ds_read_b128 v[110:113], v134 offset:1024
	ds_read_b128 v[126:129], v134 offset:2048
	ds_read_b128 v[134:137], v134 offset:3072
	s_add_u32 s0, s22, 0x160000
	s_addc_u32 s1, s23, 0
	s_mov_b32 m0, s29
	v_lshl_add_u64 v[206:207], s[0:1], 0, v[212:213]
	ds_read_b128 v[150:153], v239 offset:32768
	ds_read_b128 v[158:161], v239 offset:33792
	ds_read_b128 v[166:169], v239 offset:34816
	ds_read_b128 v[174:177], v239 offset:35840
	ds_read_b128 v[178:181], v239 offset:36864
	ds_read_b128 v[182:185], v239 offset:37888
	ds_read_b128 v[186:189], v239 offset:38912
	ds_read_b128 v[190:193], v239 offset:39936
	global_load_lds_dwordx4 v[206:207], off
	v_lshl_add_u64 v[206:207], s[0:1], 0, v[210:211]
	s_mov_b32 m0, s30
	s_nop 0
	global_load_lds_dwordx4 v[206:207], off
	s_waitcnt vmcnt(8)
	s_waitcnt lgkmcnt(0)
	s_barrier
	s_setprio 1
	s_waitcnt lgkmcnt(0)
	v_mfma_f32_16x16x32_bf16 v[170:173], v[78:81], v[150:153], v[170:173]
	v_mfma_f32_16x16x32_bf16 v[162:165], v[94:97], v[150:153], v[162:165]
	v_mfma_f32_16x16x32_bf16 v[142:145], v[78:81], v[166:169], v[142:145]
	v_mfma_f32_16x16x32_bf16 v[138:141], v[94:97], v[166:169], v[138:141]
	v_mfma_f32_16x16x32_bf16 v[118:121], v[78:81], v[178:181], v[118:121]
	v_mfma_f32_16x16x32_bf16 v[114:117], v[94:97], v[178:181], v[114:117]
	v_mfma_f32_16x16x32_bf16 v[86:89], v[78:81], v[186:189], v[86:89]
	v_mfma_f32_16x16x32_bf16 v[74:77], v[94:97], v[186:189], v[74:77]
	v_mfma_f32_16x16x32_bf16 v[170:173], v[82:85], v[158:161], v[170:173]
	v_mfma_f32_16x16x32_bf16 v[162:165], v[98:101], v[158:161], v[162:165]
	v_mfma_f32_16x16x32_bf16 v[142:145], v[82:85], v[174:177], v[142:145]
	v_mfma_f32_16x16x32_bf16 v[138:141], v[98:101], v[174:177], v[138:141]
	v_mfma_f32_16x16x32_bf16 v[118:121], v[82:85], v[182:185], v[118:121]
	v_mfma_f32_16x16x32_bf16 v[114:117], v[98:101], v[182:185], v[114:117]
	v_mfma_f32_16x16x32_bf16 v[86:89], v[82:85], v[190:193], v[86:89]
	v_mfma_f32_16x16x32_bf16 v[74:77], v[98:101], v[190:193], v[74:77]
	s_setprio 0
	s_setprio 1
	v_mfma_f32_16x16x32_bf16 v[154:157], v[106:109], v[150:153], v[154:157]
	v_mfma_f32_16x16x32_bf16 v[146:149], v[126:129], v[150:153], v[146:149]
	v_mfma_f32_16x16x32_bf16 v[130:133], v[106:109], v[166:169], v[130:133]
	v_mfma_f32_16x16x32_bf16 v[122:125], v[126:129], v[166:169], v[122:125]
	v_mfma_f32_16x16x32_bf16 v[102:105], v[106:109], v[178:181], v[102:105]
	v_mfma_f32_16x16x32_bf16 v[90:93], v[126:129], v[178:181], v[90:93]
	v_mfma_f32_16x16x32_bf16 v[70:73], v[106:109], v[186:189], v[70:73]
	v_mfma_f32_16x16x32_bf16 v[66:69], v[126:129], v[186:189], v[66:69]
	v_mfma_f32_16x16x32_bf16 v[154:157], v[110:113], v[158:161], v[154:157]
	v_mfma_f32_16x16x32_bf16 v[150:153], v[134:137], v[158:161], v[146:149]
	v_mfma_f32_16x16x32_bf16 v[130:133], v[110:113], v[174:177], v[130:133]
	v_mfma_f32_16x16x32_bf16 v[122:125], v[134:137], v[174:177], v[122:125]
	v_mfma_f32_16x16x32_bf16 v[102:105], v[110:113], v[182:185], v[102:105]
	v_mfma_f32_16x16x32_bf16 v[90:93], v[134:137], v[182:185], v[90:93]
	v_mfma_f32_16x16x32_bf16 v[70:73], v[110:113], v[190:193], v[70:73]
	v_mfma_f32_16x16x32_bf16 v[66:69], v[134:137], v[190:193], v[66:69]
	s_setprio 0
	s_barrier
	s_add_i32 s0, s4, s26
	v_lshl_add_u64 v[194:195], v[194:195], 0, s[80:81]
	s_mov_b32 m0, s0
	ds_read_b128 v[146:149], v239 offset:49152
	ds_read_b128 v[158:161], v239 offset:50176
	ds_read_b128 v[166:169], v239 offset:51200
	ds_read_b128 v[174:177], v239 offset:52224
	ds_read_b128 v[178:181], v239 offset:53248
	ds_read_b128 v[182:185], v239 offset:54272
	ds_read_b128 v[186:189], v239 offset:55296
	ds_read_b128 v[190:193], v239 offset:56320
	global_load_lds_dwordx4 v[194:195], off
	s_add_i32 m0, s0, 0x2000
	s_add_u32 s0, s20, 0x160080
	v_lshl_add_u64 v[194:195], v[196:197], 0, s[80:81]
	s_addc_u32 s1, s21, 0
	s_add_i32 s4, s5, s26
	global_load_lds_dwordx4 v[194:195], off
	v_lshl_add_u64 v[194:195], s[0:1], 0, v[202:203]
	s_mov_b32 m0, s4
	s_nop 0
	global_load_lds_dwordx4 v[194:195], off
	v_lshl_add_u64 v[194:195], s[0:1], 0, v[208:209]
	s_add_i32 m0, s4, 0x2000
	s_nop 0
	global_load_lds_dwordx4 v[194:195], off
	v_lshl_add_u64 v[194:195], v[198:199], 0, s[80:81]
	s_mov_b32 m0, s35
	s_nop 0
	global_load_lds_dwordx4 v[194:195], off
	v_lshl_add_u64 v[194:195], v[200:201], 0, s[80:81]
	s_mov_b32 m0, s36
	s_nop 0
	global_load_lds_dwordx4 v[194:195], off
	s_waitcnt vmcnt(8)
	s_waitcnt lgkmcnt(0)
	s_barrier
	s_setprio 1
	s_waitcnt lgkmcnt(0)
	v_mfma_f32_16x16x32_bf16 v[62:65], v[78:81], v[146:149], v[62:65]
	v_mfma_f32_16x16x32_bf16 v[58:61], v[94:97], v[146:149], v[58:61]
	v_mfma_f32_16x16x32_bf16 v[46:49], v[78:81], v[166:169], v[46:49]
	v_mfma_f32_16x16x32_bf16 v[42:45], v[94:97], v[166:169], v[42:45]
	v_mfma_f32_16x16x32_bf16 v[30:33], v[78:81], v[178:181], v[30:33]
	v_mfma_f32_16x16x32_bf16 v[26:29], v[94:97], v[178:181], v[26:29]
	v_mfma_f32_16x16x32_bf16 v[14:17], v[78:81], v[186:189], v[14:17]
	v_mfma_f32_16x16x32_bf16 v[10:13], v[94:97], v[186:189], v[10:13]
	v_mfma_f32_16x16x32_bf16 v[62:65], v[82:85], v[158:161], v[62:65]
	v_mfma_f32_16x16x32_bf16 v[58:61], v[98:101], v[158:161], v[58:61]
	v_mfma_f32_16x16x32_bf16 v[46:49], v[82:85], v[174:177], v[46:49]
	v_mfma_f32_16x16x32_bf16 v[42:45], v[98:101], v[174:177], v[42:45]
	v_mfma_f32_16x16x32_bf16 v[30:33], v[82:85], v[182:185], v[30:33]
	v_mfma_f32_16x16x32_bf16 v[26:29], v[98:101], v[182:185], v[26:29]
	v_mfma_f32_16x16x32_bf16 v[14:17], v[82:85], v[190:193], v[14:17]
	v_mfma_f32_16x16x32_bf16 v[10:13], v[98:101], v[190:193], v[10:13]
	s_setprio 0
	s_setprio 1
	v_mfma_f32_16x16x32_bf16 v[54:57], v[106:109], v[146:149], v[54:57]
	v_mfma_f32_16x16x32_bf16 v[50:53], v[126:129], v[146:149], v[50:53]
	v_mfma_f32_16x16x32_bf16 v[38:41], v[106:109], v[166:169], v[38:41]
	v_mfma_f32_16x16x32_bf16 v[34:37], v[126:129], v[166:169], v[34:37]
	v_mfma_f32_16x16x32_bf16 v[22:25], v[106:109], v[178:181], v[22:25]
	v_mfma_f32_16x16x32_bf16 v[18:21], v[126:129], v[178:181], v[18:21]
	v_mfma_f32_16x16x32_bf16 v[6:9], v[106:109], v[186:189], v[6:9]
	v_mfma_f32_16x16x32_bf16 v[2:5], v[126:129], v[186:189], v[2:5]
	v_mfma_f32_16x16x32_bf16 v[54:57], v[110:113], v[158:161], v[54:57]
	v_mfma_f32_16x16x32_bf16 v[50:53], v[134:137], v[158:161], v[50:53]
	v_mfma_f32_16x16x32_bf16 v[38:41], v[110:113], v[174:177], v[38:41]
	v_mfma_f32_16x16x32_bf16 v[34:37], v[134:137], v[174:177], v[34:37]
	v_mfma_f32_16x16x32_bf16 v[22:25], v[110:113], v[182:185], v[22:25]
	v_mfma_f32_16x16x32_bf16 v[18:21], v[134:137], v[182:185], v[18:21]
	v_mfma_f32_16x16x32_bf16 v[6:9], v[110:113], v[190:193], v[6:9]
	v_mfma_f32_16x16x32_bf16 v[2:5], v[134:137], v[190:193], v[2:5]
	s_setprio 0
	s_add_i32 s59, s59, 2
	s_add_u32 s49, s49, 0x100
	s_addc_u32 s58, s58, 0
	s_cmpk_gt_u32 s59, 0x55
	s_mov_b64 s[4:5], s[18:19]
	s_cbranch_scc1 .Lrot_exit_10
	s_add_u32 s18, s4, 0x100
	s_addc_u32 s19, s5, 0
	s_add_i32 s0, 0, 0x10000
	s_cmpk_eq_i32 s59, 0x54
	s_cselect_b32 s23, s9, s19
	s_cselect_b32 s22, s8, s18
	s_cselect_b32 s21, s17, s58
	s_cselect_b32 s20, s16, s49
	s_add_i32 s33, 0, 0x14000
	v_add_u32_e32 v98, s0, v205
	v_add_u32_e32 v134, s33, v205
	s_barrier
	s_branch .LBB0_1718

.LBB0_1738:
	s_add_u32 s40, s16, 0x100
	v_mov_b32_e32 v2, 0
	s_addc_u32 s41, s17, 0
	s_mov_b32 s49, -2
	v_mov_b32_e32 v3, v2
	v_mov_b32_e32 v4, v2
	v_mov_b32_e32 v5, v2
	v_mov_b32_e32 v6, v2
	v_mov_b32_e32 v7, v2
	v_mov_b32_e32 v8, v2
	v_mov_b32_e32 v9, v2
	v_mov_b32_e32 v10, v2
	v_mov_b32_e32 v11, v2
	v_mov_b32_e32 v12, v2
	v_mov_b32_e32 v13, v2
	v_mov_b32_e32 v14, v2
	v_mov_b32_e32 v15, v2
	v_mov_b32_e32 v16, v2
	v_mov_b32_e32 v17, v2
	v_mov_b32_e32 v26, v2
	v_mov_b32_e32 v27, v2
	v_mov_b32_e32 v28, v2
	v_mov_b32_e32 v29, v2
	v_mov_b32_e32 v30, v2
	v_mov_b32_e32 v31, v2
	v_mov_b32_e32 v32, v2
	v_mov_b32_e32 v33, v2
	v_mov_b32_e32 v42, v2
	v_mov_b32_e32 v43, v2
	v_mov_b32_e32 v44, v2
	v_mov_b32_e32 v45, v2
	v_mov_b32_e32 v46, v2
	v_mov_b32_e32 v47, v2
	v_mov_b32_e32 v48, v2
	v_mov_b32_e32 v49, v2
	v_mov_b32_e32 v18, v2
	v_mov_b32_e32 v19, v2
	v_mov_b32_e32 v20, v2
	v_mov_b32_e32 v21, v2
	v_mov_b32_e32 v22, v2
	v_mov_b32_e32 v23, v2
	v_mov_b32_e32 v24, v2
	v_mov_b32_e32 v25, v2
	v_mov_b32_e32 v34, v2
	v_mov_b32_e32 v35, v2
	v_mov_b32_e32 v36, v2
	v_mov_b32_e32 v37, v2
	v_mov_b32_e32 v38, v2
	v_mov_b32_e32 v39, v2
	v_mov_b32_e32 v40, v2
	v_mov_b32_e32 v41, v2
	v_mov_b32_e32 v50, v2
	v_mov_b32_e32 v51, v2
	v_mov_b32_e32 v52, v2
	v_mov_b32_e32 v53, v2
	v_mov_b32_e32 v54, v2
	v_mov_b32_e32 v55, v2
	v_mov_b32_e32 v56, v2
	v_mov_b32_e32 v57, v2
	v_mov_b32_e32 v58, v2
	v_mov_b32_e32 v59, v2
	v_mov_b32_e32 v60, v2
	v_mov_b32_e32 v61, v2
	v_mov_b32_e32 v62, v2
	v_mov_b32_e32 v63, v2
	v_mov_b32_e32 v64, v2
	v_mov_b32_e32 v65, v2
	v_mov_b32_e32 v66, v2
	v_mov_b32_e32 v67, v2
	v_mov_b32_e32 v68, v2
	v_mov_b32_e32 v69, v2
	v_mov_b32_e32 v70, v2
	v_mov_b32_e32 v71, v2
	v_mov_b32_e32 v72, v2
	v_mov_b32_e32 v73, v2
	v_mov_b32_e32 v74, v2
	v_mov_b32_e32 v75, v2
	v_mov_b32_e32 v76, v2
	v_mov_b32_e32 v77, v2
	v_mov_b32_e32 v78, v2
	v_mov_b32_e32 v79, v2
	v_mov_b32_e32 v80, v2
	v_mov_b32_e32 v81, v2
	v_mov_b32_e32 v86, v2
	v_mov_b32_e32 v87, v2
	v_mov_b32_e32 v88, v2
	v_mov_b32_e32 v89, v2
	v_mov_b32_e32 v94, v2
	v_mov_b32_e32 v95, v2
	v_mov_b32_e32 v96, v2
	v_mov_b32_e32 v97, v2
	v_mov_b32_e32 v102, v2
	v_mov_b32_e32 v103, v2
	v_mov_b32_e32 v104, v2
	v_mov_b32_e32 v105, v2
	v_mov_b32_e32 v110, v2
	v_mov_b32_e32 v111, v2
	v_mov_b32_e32 v112, v2
	v_mov_b32_e32 v113, v2
	v_mov_b32_e32 v82, v2
	v_mov_b32_e32 v83, v2
	v_mov_b32_e32 v84, v2
	v_mov_b32_e32 v85, v2
	v_mov_b32_e32 v90, v2
	v_mov_b32_e32 v91, v2
	v_mov_b32_e32 v92, v2
	v_mov_b32_e32 v93, v2
	v_mov_b32_e32 v98, v2
	v_mov_b32_e32 v99, v2
	v_mov_b32_e32 v100, v2
	v_mov_b32_e32 v101, v2
	v_mov_b32_e32 v106, v2
	v_mov_b32_e32 v107, v2
	v_mov_b32_e32 v108, v2
	v_mov_b32_e32 v109, v2
	v_mov_b32_e32 v114, v2
	v_mov_b32_e32 v115, v2
	v_mov_b32_e32 v116, v2
	v_mov_b32_e32 v117, v2
	v_mov_b32_e32 v118, v2
	v_mov_b32_e32 v119, v2
	v_mov_b32_e32 v120, v2
	v_mov_b32_e32 v121, v2
	v_mov_b32_e32 v122, v2
	v_mov_b32_e32 v123, v2
	v_mov_b32_e32 v124, v2
	v_mov_b32_e32 v125, v2
	v_mov_b32_e32 v126, v2
	v_mov_b32_e32 v127, v2
	v_mov_b32_e32 v128, v2
	v_mov_b32_e32 v129, v2
	s_add_u32 s16, s14, 0x100
	s_addc_u32 s17, s15, 0
	s_add_i32 s0, 0, 0x10000
	s_cmp_eq_u32 s49, 4
	s_cselect_b32 s21, s9, s17
	s_cselect_b32 s20, s8, s16
	s_cselect_b32 s19, s11, s41
	s_cselect_b32 s18, s10, s40
	s_add_i32 s33, 0, 0x14000
	v_add_u32_e32 v152, s0, v136
	v_add_u32_e32 v168, s33, v136
.LBB0_1739:
	ds_read_b128 v[140:143], v152
	ds_read_b128 v[144:147], v152 offset:1024
	ds_read_b128 v[148:151], v152 offset:2048
	ds_read_b128 v[152:155], v152 offset:3072
	ds_read_b128 v[156:159], v168
	ds_read_b128 v[160:163], v168 offset:1024
	ds_read_b128 v[164:167], v168 offset:2048
	ds_read_b128 v[168:171], v168 offset:3072
	v_lshl_add_u64 v[200:201], s[14:15], 0, v[132:133]
	s_add_i32 m0, s23, 0xc000
	ds_read_b128 v[172:175], v139
	ds_read_b128 v[176:179], v139 offset:1024
	ds_read_b128 v[180:183], v139 offset:2048
	ds_read_b128 v[184:187], v139 offset:3072
	ds_read_b128 v[188:191], v139 offset:4096
	ds_read_b128 v[192:195], v139 offset:5120
	ds_read_b128 v[196:199], v139 offset:6144
	ds_read_b128 v[208:211], v139 offset:7168
	global_load_lds_dwordx4 v[200:201], off
	v_lshl_add_u64 v[200:201], s[14:15], 0, v[134:135]
	s_add_i32 m0, s23, 0xe000
	s_nop 0
	global_load_lds_dwordx4 v[200:201], off
	s_waitcnt vmcnt(8)
	s_waitcnt lgkmcnt(0)
	s_barrier
	s_setprio 1
	s_waitcnt lgkmcnt(0)
	v_mfma_f32_16x16x32_bf16 v[126:129], v[140:143], v[172:175], v[126:129]
	v_mfma_f32_16x16x32_bf16 v[122:125], v[148:151], v[172:175], v[122:125]
	v_mfma_f32_16x16x32_bf16 v[118:121], v[140:143], v[180:183], v[118:121]
	v_mfma_f32_16x16x32_bf16 v[114:117], v[148:151], v[180:183], v[114:117]
	v_mfma_f32_16x16x32_bf16 v[106:109], v[140:143], v[188:191], v[106:109]
	v_mfma_f32_16x16x32_bf16 v[98:101], v[148:151], v[188:191], v[98:101]
	v_mfma_f32_16x16x32_bf16 v[90:93], v[140:143], v[196:199], v[90:93]
	v_mfma_f32_16x16x32_bf16 v[82:85], v[148:151], v[196:199], v[82:85]
	v_mfma_f32_16x16x32_bf16 v[126:129], v[144:147], v[176:179], v[126:129]
	v_mfma_f32_16x16x32_bf16 v[122:125], v[152:155], v[176:179], v[122:125]
	v_mfma_f32_16x16x32_bf16 v[118:121], v[144:147], v[184:187], v[118:121]
	v_mfma_f32_16x16x32_bf16 v[114:117], v[152:155], v[184:187], v[114:117]
	v_mfma_f32_16x16x32_bf16 v[106:109], v[144:147], v[192:195], v[106:109]
	v_mfma_f32_16x16x32_bf16 v[98:101], v[152:155], v[192:195], v[98:101]
	v_mfma_f32_16x16x32_bf16 v[90:93], v[144:147], v[208:211], v[90:93]
	v_mfma_f32_16x16x32_bf16 v[82:85], v[152:155], v[208:211], v[82:85]
	s_setprio 0
	s_setprio 1
	v_mfma_f32_16x16x32_bf16 v[110:113], v[156:159], v[172:175], v[110:113]
	v_mfma_f32_16x16x32_bf16 v[102:105], v[164:167], v[172:175], v[102:105]
	v_mfma_f32_16x16x32_bf16 v[94:97], v[156:159], v[180:183], v[94:97]
	v_mfma_f32_16x16x32_bf16 v[86:89], v[164:167], v[180:183], v[86:89]
	v_mfma_f32_16x16x32_bf16 v[78:81], v[156:159], v[188:191], v[78:81]
	v_mfma_f32_16x16x32_bf16 v[74:77], v[164:167], v[188:191], v[74:77]
	v_mfma_f32_16x16x32_bf16 v[70:73], v[156:159], v[196:199], v[70:73]
	v_mfma_f32_16x16x32_bf16 v[66:69], v[164:167], v[196:199], v[66:69]
	v_mfma_f32_16x16x32_bf16 v[110:113], v[160:163], v[176:179], v[110:113]
	v_mfma_f32_16x16x32_bf16 v[102:105], v[168:171], v[176:179], v[102:105]
	v_mfma_f32_16x16x32_bf16 v[94:97], v[160:163], v[184:187], v[94:97]
	v_mfma_f32_16x16x32_bf16 v[86:89], v[168:171], v[184:187], v[86:89]
	v_mfma_f32_16x16x32_bf16 v[78:81], v[160:163], v[192:195], v[78:81]
	v_mfma_f32_16x16x32_bf16 v[74:77], v[168:171], v[192:195], v[74:77]
	v_mfma_f32_16x16x32_bf16 v[70:73], v[160:163], v[208:211], v[70:73]
	v_mfma_f32_16x16x32_bf16 v[66:69], v[168:171], v[208:211], v[66:69]
	s_setprio 0
	s_barrier
	s_add_i32 s0, s0, s22
	v_lshl_add_u64 v[200:201], s[18:19], 0, v[202:203]
	s_mov_b32 m0, s0
	ds_read_b128 v[172:175], v139 offset:16384
	ds_read_b128 v[176:179], v139 offset:17408
	ds_read_b128 v[180:183], v139 offset:18432
	ds_read_b128 v[184:187], v139 offset:19456
	ds_read_b128 v[188:191], v139 offset:20480
	ds_read_b128 v[192:195], v139 offset:21504
	ds_read_b128 v[196:199], v139 offset:22528
	ds_read_b128 v[208:211], v139 offset:23552
	global_load_lds_dwordx4 v[200:201], off
	s_add_i32 m0, s0, 0x2000
	s_add_u32 s0, s18, 0x160000
	v_lshl_add_u64 v[204:205], s[18:19], 0, v[130:131]
	s_addc_u32 s1, s19, 0
	s_add_i32 s14, s33, s22
	global_load_lds_dwordx4 v[204:205], off
	v_lshl_add_u64 v[206:207], s[0:1], 0, v[202:203]
	s_mov_b32 m0, s14
	v_lshl_add_u64 v[212:213], s[20:21], 0, v[130:131]
	global_load_lds_dwordx4 v[206:207], off
	v_lshl_add_u64 v[206:207], s[0:1], 0, v[130:131]
	s_add_i32 m0, s14, 0x2000
	s_nop 0
	global_load_lds_dwordx4 v[206:207], off
	v_lshl_add_u64 v[206:207], s[20:21], 0, v[202:203]
	s_mov_b32 m0, s23
	s_nop 0
	global_load_lds_dwordx4 v[206:207], off
	s_mov_b32 m0, s26
	s_nop 0
	global_load_lds_dwordx4 v[212:213], off
	s_waitcnt vmcnt(8)
	s_waitcnt lgkmcnt(0)
	s_barrier
	s_setprio 1
	s_waitcnt lgkmcnt(0)
	v_mfma_f32_16x16x32_bf16 v[62:65], v[140:143], v[172:175], v[62:65]
	v_mfma_f32_16x16x32_bf16 v[58:61], v[148:151], v[172:175], v[58:61]
	v_mfma_f32_16x16x32_bf16 v[54:57], v[140:143], v[180:183], v[54:57]
	v_mfma_f32_16x16x32_bf16 v[50:53], v[148:151], v[180:183], v[50:53]
	v_mfma_f32_16x16x32_bf16 v[38:41], v[140:143], v[188:191], v[38:41]
	v_mfma_f32_16x16x32_bf16 v[34:37], v[148:151], v[188:191], v[34:37]
	v_mfma_f32_16x16x32_bf16 v[22:25], v[140:143], v[196:199], v[22:25]
	v_mfma_f32_16x16x32_bf16 v[18:21], v[148:151], v[196:199], v[18:21]
	v_mfma_f32_16x16x32_bf16 v[62:65], v[144:147], v[176:179], v[62:65]
	v_mfma_f32_16x16x32_bf16 v[58:61], v[152:155], v[176:179], v[58:61]
	v_mfma_f32_16x16x32_bf16 v[54:57], v[144:147], v[184:187], v[54:57]
	v_mfma_f32_16x16x32_bf16 v[50:53], v[152:155], v[184:187], v[50:53]
	v_mfma_f32_16x16x32_bf16 v[38:41], v[144:147], v[192:195], v[38:41]
	v_mfma_f32_16x16x32_bf16 v[34:37], v[152:155], v[192:195], v[34:37]
	v_mfma_f32_16x16x32_bf16 v[22:25], v[144:147], v[208:211], v[22:25]
	v_mfma_f32_16x16x32_bf16 v[18:21], v[152:155], v[208:211], v[18:21]
	s_setprio 0
	s_setprio 1
	v_mfma_f32_16x16x32_bf16 v[46:49], v[156:159], v[172:175], v[46:49]
	v_mfma_f32_16x16x32_bf16 v[42:45], v[164:167], v[172:175], v[42:45]
	v_mfma_f32_16x16x32_bf16 v[30:33], v[156:159], v[180:183], v[30:33]
	v_mfma_f32_16x16x32_bf16 v[26:29], v[164:167], v[180:183], v[26:29]
	v_mfma_f32_16x16x32_bf16 v[14:17], v[156:159], v[188:191], v[14:17]
	v_mfma_f32_16x16x32_bf16 v[10:13], v[164:167], v[188:191], v[10:13]
	v_mfma_f32_16x16x32_bf16 v[6:9], v[156:159], v[196:199], v[6:9]
	v_mfma_f32_16x16x32_bf16 v[2:5], v[164:167], v[196:199], v[2:5]
	v_mfma_f32_16x16x32_bf16 v[46:49], v[160:163], v[176:179], v[46:49]
	v_mfma_f32_16x16x32_bf16 v[42:45], v[168:171], v[176:179], v[42:45]
	v_mfma_f32_16x16x32_bf16 v[30:33], v[160:163], v[184:187], v[30:33]
	v_mfma_f32_16x16x32_bf16 v[26:29], v[168:171], v[184:187], v[26:29]
	v_mfma_f32_16x16x32_bf16 v[14:17], v[160:163], v[192:195], v[14:17]
	v_mfma_f32_16x16x32_bf16 v[10:13], v[168:171], v[192:195], v[10:13]
	v_mfma_f32_16x16x32_bf16 v[6:9], v[160:163], v[208:211], v[6:9]
	v_mfma_f32_16x16x32_bf16 v[2:5], v[168:171], v[208:211], v[2:5]
	s_setprio 0
	s_barrier
	s_add_i32 s14, 0, 0x18000
	s_add_i32 s15, 0, 0x1c000
	v_add_u32_e32 v152, s14, v136
	v_add_u32_e32 v168, s15, v136
	ds_read_b128 v[140:143], v152
	ds_read_b128 v[144:147], v152 offset:1024
	ds_read_b128 v[148:151], v152 offset:2048
	ds_read_b128 v[152:155], v152 offset:3072
	ds_read_b128 v[156:159], v168
	ds_read_b128 v[160:163], v168 offset:1024
	ds_read_b128 v[164:167], v168 offset:2048
	ds_read_b128 v[168:171], v168 offset:3072
	s_add_u32 s0, s20, 0x160000
	s_addc_u32 s1, s21, 0
	s_mov_b32 m0, s27
	v_lshl_add_u64 v[214:215], s[0:1], 0, v[202:203]
	ds_read_b128 v[172:175], v139 offset:32768
	ds_read_b128 v[176:179], v139 offset:33792
	ds_read_b128 v[180:183], v139 offset:34816
	ds_read_b128 v[184:187], v139 offset:35840
	ds_read_b128 v[188:191], v139 offset:36864
	ds_read_b128 v[192:195], v139 offset:37888
	ds_read_b128 v[196:199], v139 offset:38912
	ds_read_b128 v[208:211], v139 offset:39936
	global_load_lds_dwordx4 v[214:215], off
	v_lshl_add_u64 v[214:215], s[0:1], 0, v[130:131]
	s_mov_b32 m0, s28
	s_nop 0
	global_load_lds_dwordx4 v[214:215], off
	s_waitcnt vmcnt(8)
	s_waitcnt lgkmcnt(0)
	s_barrier
	s_setprio 1
	s_waitcnt lgkmcnt(0)
	v_mfma_f32_16x16x32_bf16 v[126:129], v[140:143], v[172:175], v[126:129]
	v_mfma_f32_16x16x32_bf16 v[122:125], v[148:151], v[172:175], v[122:125]
	v_mfma_f32_16x16x32_bf16 v[118:121], v[140:143], v[180:183], v[118:121]
	v_mfma_f32_16x16x32_bf16 v[114:117], v[148:151], v[180:183], v[114:117]
	v_mfma_f32_16x16x32_bf16 v[106:109], v[140:143], v[188:191], v[106:109]
	v_mfma_f32_16x16x32_bf16 v[98:101], v[148:151], v[188:191], v[98:101]
	v_mfma_f32_16x16x32_bf16 v[90:93], v[140:143], v[196:199], v[90:93]
	v_mfma_f32_16x16x32_bf16 v[82:85], v[148:151], v[196:199], v[82:85]
	v_mfma_f32_16x16x32_bf16 v[126:129], v[144:147], v[176:179], v[126:129]
	v_mfma_f32_16x16x32_bf16 v[122:125], v[152:155], v[176:179], v[122:125]
	v_mfma_f32_16x16x32_bf16 v[118:121], v[144:147], v[184:187], v[118:121]
	v_mfma_f32_16x16x32_bf16 v[114:117], v[152:155], v[184:187], v[114:117]
	v_mfma_f32_16x16x32_bf16 v[106:109], v[144:147], v[192:195], v[106:109]
	v_mfma_f32_16x16x32_bf16 v[98:101], v[152:155], v[192:195], v[98:101]
	v_mfma_f32_16x16x32_bf16 v[90:93], v[144:147], v[208:211], v[90:93]
	v_mfma_f32_16x16x32_bf16 v[82:85], v[152:155], v[208:211], v[82:85]
	s_setprio 0
	s_setprio 1
	v_mfma_f32_16x16x32_bf16 v[110:113], v[156:159], v[172:175], v[110:113]
	v_mfma_f32_16x16x32_bf16 v[102:105], v[164:167], v[172:175], v[102:105]
	v_mfma_f32_16x16x32_bf16 v[94:97], v[156:159], v[180:183], v[94:97]
	v_mfma_f32_16x16x32_bf16 v[86:89], v[164:167], v[180:183], v[86:89]
	v_mfma_f32_16x16x32_bf16 v[78:81], v[156:159], v[188:191], v[78:81]
	v_mfma_f32_16x16x32_bf16 v[74:77], v[164:167], v[188:191], v[74:77]
	v_mfma_f32_16x16x32_bf16 v[70:73], v[156:159], v[196:199], v[70:73]
	v_mfma_f32_16x16x32_bf16 v[66:69], v[164:167], v[196:199], v[66:69]
	v_mfma_f32_16x16x32_bf16 v[110:113], v[160:163], v[176:179], v[110:113]
	v_mfma_f32_16x16x32_bf16 v[102:105], v[168:171], v[176:179], v[102:105]
	v_mfma_f32_16x16x32_bf16 v[94:97], v[160:163], v[184:187], v[94:97]
	v_mfma_f32_16x16x32_bf16 v[86:89], v[168:171], v[184:187], v[86:89]
	v_mfma_f32_16x16x32_bf16 v[78:81], v[160:163], v[192:195], v[78:81]
	v_mfma_f32_16x16x32_bf16 v[74:77], v[168:171], v[192:195], v[74:77]
	v_mfma_f32_16x16x32_bf16 v[70:73], v[160:163], v[208:211], v[70:73]
	v_mfma_f32_16x16x32_bf16 v[66:69], v[168:171], v[208:211], v[66:69]
	s_setprio 0
	s_barrier
	s_add_i32 s0, s14, s22
	v_lshl_add_u64 v[200:201], v[200:201], 0, s[80:81]
	s_mov_b32 m0, s0
	ds_read_b128 v[172:175], v139 offset:49152
	ds_read_b128 v[176:179], v139 offset:50176
	ds_read_b128 v[180:183], v139 offset:51200
	ds_read_b128 v[184:187], v139 offset:52224
	ds_read_b128 v[188:191], v139 offset:53248
	ds_read_b128 v[192:195], v139 offset:54272
	ds_read_b128 v[196:199], v139 offset:55296
	ds_read_b128 v[208:211], v139 offset:56320
	global_load_lds_dwordx4 v[200:201], off
	s_add_i32 m0, s0, 0x2000
	s_add_u32 s0, s18, 0x160080
	v_lshl_add_u64 v[200:201], v[204:205], 0, s[80:81]
	s_addc_u32 s1, s19, 0
	s_add_i32 s14, s15, s22
	global_load_lds_dwordx4 v[200:201], off
	v_lshl_add_u64 v[200:201], s[0:1], 0, v[202:203]
	s_mov_b32 m0, s14
	s_nop 0
	global_load_lds_dwordx4 v[200:201], off
	v_lshl_add_u64 v[200:201], s[0:1], 0, v[130:131]
	s_add_i32 m0, s14, 0x2000
	s_nop 0
	global_load_lds_dwordx4 v[200:201], off
	v_lshl_add_u64 v[200:201], v[206:207], 0, s[80:81]
	s_mov_b32 m0, s29
	s_nop 0
	global_load_lds_dwordx4 v[200:201], off
	v_lshl_add_u64 v[200:201], v[212:213], 0, s[80:81]
	s_mov_b32 m0, s30
	s_nop 0
	global_load_lds_dwordx4 v[200:201], off
	s_waitcnt vmcnt(8)
	s_waitcnt lgkmcnt(0)
	s_barrier
	s_setprio 1
	s_waitcnt lgkmcnt(0)
	v_mfma_f32_16x16x32_bf16 v[62:65], v[140:143], v[172:175], v[62:65]
	v_mfma_f32_16x16x32_bf16 v[58:61], v[148:151], v[172:175], v[58:61]
	v_mfma_f32_16x16x32_bf16 v[54:57], v[140:143], v[180:183], v[54:57]
	v_mfma_f32_16x16x32_bf16 v[50:53], v[148:151], v[180:183], v[50:53]
	v_mfma_f32_16x16x32_bf16 v[38:41], v[140:143], v[188:191], v[38:41]
	v_mfma_f32_16x16x32_bf16 v[34:37], v[148:151], v[188:191], v[34:37]
	v_mfma_f32_16x16x32_bf16 v[22:25], v[140:143], v[196:199], v[22:25]
	v_mfma_f32_16x16x32_bf16 v[18:21], v[148:151], v[196:199], v[18:21]
	v_mfma_f32_16x16x32_bf16 v[62:65], v[144:147], v[176:179], v[62:65]
	v_mfma_f32_16x16x32_bf16 v[58:61], v[152:155], v[176:179], v[58:61]
	v_mfma_f32_16x16x32_bf16 v[54:57], v[144:147], v[184:187], v[54:57]
	v_mfma_f32_16x16x32_bf16 v[50:53], v[152:155], v[184:187], v[50:53]
	v_mfma_f32_16x16x32_bf16 v[38:41], v[144:147], v[192:195], v[38:41]
	v_mfma_f32_16x16x32_bf16 v[34:37], v[152:155], v[192:195], v[34:37]
	v_mfma_f32_16x16x32_bf16 v[22:25], v[144:147], v[208:211], v[22:25]
	v_mfma_f32_16x16x32_bf16 v[18:21], v[152:155], v[208:211], v[18:21]
	s_setprio 0
	s_setprio 1
	v_mfma_f32_16x16x32_bf16 v[46:49], v[156:159], v[172:175], v[46:49]
	v_mfma_f32_16x16x32_bf16 v[42:45], v[164:167], v[172:175], v[42:45]
	v_mfma_f32_16x16x32_bf16 v[30:33], v[156:159], v[180:183], v[30:33]
	v_mfma_f32_16x16x32_bf16 v[26:29], v[164:167], v[180:183], v[26:29]
	v_mfma_f32_16x16x32_bf16 v[14:17], v[156:159], v[188:191], v[14:17]
	v_mfma_f32_16x16x32_bf16 v[10:13], v[164:167], v[188:191], v[10:13]
	v_mfma_f32_16x16x32_bf16 v[6:9], v[156:159], v[196:199], v[6:9]
	v_mfma_f32_16x16x32_bf16 v[2:5], v[164:167], v[196:199], v[2:5]
	v_mfma_f32_16x16x32_bf16 v[46:49], v[160:163], v[176:179], v[46:49]
	v_mfma_f32_16x16x32_bf16 v[42:45], v[168:171], v[176:179], v[42:45]
	v_mfma_f32_16x16x32_bf16 v[30:33], v[160:163], v[184:187], v[30:33]
	v_mfma_f32_16x16x32_bf16 v[26:29], v[168:171], v[184:187], v[26:29]
	v_mfma_f32_16x16x32_bf16 v[14:17], v[160:163], v[192:195], v[14:17]
	v_mfma_f32_16x16x32_bf16 v[10:13], v[168:171], v[192:195], v[10:13]
	v_mfma_f32_16x16x32_bf16 v[6:9], v[160:163], v[208:211], v[6:9]
	v_mfma_f32_16x16x32_bf16 v[2:5], v[168:171], v[208:211], v[2:5]
	s_setprio 0
	s_add_i32 s49, s49, 2
	s_add_u32 s40, s40, 0x100
	s_addc_u32 s41, s41, 0
	s_cmp_gt_u32 s49, 5
	s_mov_b64 s[14:15], s[16:17]
	s_cbranch_scc1 .Lrot_exit_11
	s_add_u32 s16, s14, 0x100
	s_addc_u32 s17, s15, 0
	s_add_i32 s0, 0, 0x10000
	s_cmp_eq_u32 s49, 4
	s_cselect_b32 s21, s9, s17
	s_cselect_b32 s20, s8, s16
	s_cselect_b32 s19, s11, s41
	s_cselect_b32 s18, s10, s40
	s_add_i32 s33, 0, 0x14000
	v_add_u32_e32 v152, s0, v136
	v_add_u32_e32 v168, s33, v136
	s_barrier
	s_branch .LBB0_1739
